# merged MMA phase pairs in all 7 big GEMM K-loops (adds even in-proj, FFN-down, compress GEMM1)
# speedup vs baseline: 1.0093x; 1.0072x over previous
; #define PG8_STAGE(bufoff, gbase, voff) do { _Pragma("unroll") for (int _i = 0; _i < 2; ++_i) \
;         __builtin_amdgcn_global_load_lds((const unsigned*)((const char*)(gbase) + (voff)[_i]), (LAS unsigned*)(lds + (bufoff) + ldsw + _i * 8192), 16, 0, 0); } while (0)
; #define PG8_LDA(dst, b, h) do { _Pragma("unroll") for (int m = 0; m < 4; ++m) _Pragma("unroll") for (int k = 0; k < 2; ++k) dst[m][k] = *(const LAS bf16x8*)(lds + PG8_SA(b, h) + aoff + m * 2048 + k * 1024); } while (0)
; #define PG8_LDB(dst, b, h) do { _Pragma("unroll") for (int n = 0; n < 2; ++n) _Pragma("unroll") for (int k = 0; k < 2; ++k) dst[n][k] = *(const LAS bf16x8*)(lds + PG8_SB(b, h) + boff + n * 2048 + k * 1024); } while (0)
; #define PG8_MMA(ai, bj, At, Bt) do { __builtin_amdgcn_s_setprio(1); _Pragma("unroll") for (int m = 0; m < 4; ++m) _Pragma("unroll") for (int n = 0; n < 2; ++n) _Pragma("unroll") for (int k = 0; k < 2; ++k) \
;         acc[ai][bj][m][n] = __builtin_amdgcn_mfma_f32_16x16x32_bf16(Bt[n][k], At[m][k], acc[ai][bj][m][n], 0, 0, 0); __builtin_amdgcn_s_setprio(0); } while (0)
; #define PG8_WAIT_V(n) asm volatile("s_waitcnt vmcnt(" #n ")" ::: "memory")
; #define PG8_WAIT_L(n) asm volatile("s_waitcnt lgkmcnt(" #n ")" ::: "memory")
; template <class Epi, class Sched>
; __device__ __forceinline__ void gemm_phase(LAS unsigned char* lds, const Gemm g, const Sched& S, const Epi& E) {
;     ...
;             const bool last = (t == nt - 2);
;             const char* a1 = cA + (size_t)(t + 1) * kstep;
;             const char* a2 = last ? nA : cA + (size_t)(t + 2) * kstep; const char* b2 = last ? nB : cB + (size_t)(t + 2) * kstep;
;             const char* a3 = a2 + kstep; const char* b3 = b2 + kstep;
;             if (last && has_next) S.a_ready(nxt);
;             PG8_LDB(B0, 0, 0); PG8_SCHED; PG8_LDA(At, 0, 0); PG8_STAGE(PG8_SA(1, 1), a1 + hstepA, voffA);
;             PG8_WAIT_L(8); PG8_BAR; PG8_WAIT_L(0); PG8_MMA(0, 0, At, B0); PG8_BAR; PG8_SCHED;
;             PG8_LDB(B1, 0, 1); PG8_STAGE(PG8_SB(0, 0), b2, voffB);
;             PG8_BAR; PG8_WAIT_L(0); PG8_MMA(0, 1, At, B1); PG8_BAR;
;             PG8_LDA(At, 0, 1); PG8_STAGE(PG8_SA(0, 0), a2, voffA);
;             PG8_BAR; PG8_WAIT_L(0); PG8_MMA(1, 0, At, B0); PG8_BAR; PG8_SCHED;
;             PG8_STAGE(PG8_SB(0, 1), b2 + hstepB, voffB);
;             PG8_WAIT_V(6); PG8_BAR; PG8_MMA(1, 1, At, B1); PG8_BAR;
.LBB0_352:
	s_add_u32 s20, s6, 0xfff80080
	s_addc_u32 s21, s7, -1
	s_add_i32 s56, 0, 0x10000
	v_add_u32_e32 v2, s56, v1
	ds_read_b128 v[144:147], v2
	ds_read_b128 v[150:153], v2 offset:1024
	ds_read_b128 v[154:157], v2 offset:2048
	ds_read_b128 v[158:161], v2 offset:3072
	s_cmp_eq_u32 s55, 28
	s_cselect_b32 s25, s15, s21
	s_cselect_b32 s24, s51, s20
	s_cselect_b32 s21, s1, s54
	s_cselect_b32 s20, s52, s53
	ds_read_b128 v[162:165], v149
	ds_read_b128 v[166:169], v149 offset:1024
	ds_read_b128 v[170:173], v149 offset:2048
	ds_read_b128 v[174:177], v149 offset:3072
	ds_read_b128 v[178:181], v149 offset:4096
	ds_read_b128 v[182:185], v149 offset:5120
	ds_read_b128 v[186:189], v149 offset:6144
	ds_read_b128 v[190:193], v149 offset:7168
	s_add_i32 s58, 0, 0x14000
	v_add_u32_e32 v2, s58, v1
	ds_read_b128 v[194:197], v2
	ds_read_b128 v[198:201], v2 offset:1024
	ds_read_b128 v[202:205], v2 offset:2048
	ds_read_b128 v[206:209], v2 offset:3072
	s_add_i32 m0, s31, 0xc000
	s_nop 0
	global_load_lds_dwordx4 v140, s[6:7]
	s_add_i32 m0, s31, 0xe000
	s_nop 0
	global_load_lds_dwordx4 v142, s[6:7]
	s_waitcnt lgkmcnt(0)
	s_barrier
	s_setprio 1
	v_mfma_f32_16x16x32_bf16 v[128:131], v[144:147], v[162:165], v[128:131]
	v_mfma_f32_16x16x32_bf16 v[124:127], v[154:157], v[162:165], v[124:127]
	v_mfma_f32_16x16x32_bf16 v[112:115], v[144:147], v[170:173], v[112:115]
	v_mfma_f32_16x16x32_bf16 v[108:111], v[154:157], v[170:173], v[108:111]
	v_mfma_f32_16x16x32_bf16 v[96:99], v[144:147], v[178:181], v[96:99]
	v_mfma_f32_16x16x32_bf16 v[92:95], v[154:157], v[178:181], v[92:95]
	v_mfma_f32_16x16x32_bf16 v[80:83], v[144:147], v[186:189], v[80:83]
	v_mfma_f32_16x16x32_bf16 v[76:79], v[154:157], v[186:189], v[76:79]
	v_mfma_f32_16x16x32_bf16 v[128:131], v[150:153], v[166:169], v[128:131]
	v_mfma_f32_16x16x32_bf16 v[124:127], v[158:161], v[166:169], v[124:127]
	v_mfma_f32_16x16x32_bf16 v[112:115], v[150:153], v[174:177], v[112:115]
	v_mfma_f32_16x16x32_bf16 v[108:111], v[158:161], v[174:177], v[108:111]
	v_mfma_f32_16x16x32_bf16 v[96:99], v[150:153], v[182:185], v[96:99]
	v_mfma_f32_16x16x32_bf16 v[92:95], v[158:161], v[182:185], v[92:95]
	v_mfma_f32_16x16x32_bf16 v[80:83], v[150:153], v[190:193], v[80:83]
	v_mfma_f32_16x16x32_bf16 v[76:79], v[158:161], v[190:193], v[76:79]
	v_mfma_f32_16x16x32_bf16 v[120:123], v[194:197], v[162:165], v[120:123]
	v_mfma_f32_16x16x32_bf16 v[116:119], v[202:205], v[162:165], v[116:119]
	v_mfma_f32_16x16x32_bf16 v[104:107], v[194:197], v[170:173], v[104:107]
	v_mfma_f32_16x16x32_bf16 v[100:103], v[202:205], v[170:173], v[100:103]
	v_mfma_f32_16x16x32_bf16 v[88:91], v[194:197], v[178:181], v[88:91]
	v_mfma_f32_16x16x32_bf16 v[84:87], v[202:205], v[178:181], v[84:87]
	v_mfma_f32_16x16x32_bf16 v[72:75], v[194:197], v[186:189], v[72:75]
	v_mfma_f32_16x16x32_bf16 v[68:71], v[202:205], v[186:189], v[68:71]
	v_mfma_f32_16x16x32_bf16 v[120:123], v[198:201], v[166:169], v[120:123]
	v_mfma_f32_16x16x32_bf16 v[116:119], v[206:209], v[166:169], v[116:119]
	v_mfma_f32_16x16x32_bf16 v[104:107], v[198:201], v[174:177], v[104:107]
	v_mfma_f32_16x16x32_bf16 v[100:103], v[206:209], v[174:177], v[100:103]
	v_mfma_f32_16x16x32_bf16 v[88:91], v[198:201], v[182:185], v[88:91]
	v_mfma_f32_16x16x32_bf16 v[84:87], v[206:209], v[182:185], v[84:87]
	v_mfma_f32_16x16x32_bf16 v[72:75], v[198:201], v[190:193], v[72:75]
	v_mfma_f32_16x16x32_bf16 v[68:71], v[206:209], v[190:193], v[68:71]
	s_setprio 0
	s_barrier
	ds_read_b128 v[162:165], v149 offset:16384
	ds_read_b128 v[166:169], v149 offset:17408
	ds_read_b128 v[170:173], v149 offset:18432
	ds_read_b128 v[174:177], v149 offset:19456
	ds_read_b128 v[178:181], v149 offset:20480
	ds_read_b128 v[182:185], v149 offset:21504
	ds_read_b128 v[186:189], v149 offset:22528
	ds_read_b128 v[190:193], v149 offset:23552
	s_add_i32 s56, s56, s30
	v_lshl_add_u64 v[210:211], s[20:21], 0, v[136:137]
	s_mov_b32 m0, s56
	s_nop 0
	global_load_lds_dwordx4 v[210:211], off
	v_lshl_add_u64 v[212:213], s[20:21], 0, v[132:133]
	s_add_i32 m0, s56, 0x2000
	s_nop 0
	global_load_lds_dwordx4 v[212:213], off
	s_mov_b32 m0, s31
	v_lshl_add_u64 v[216:217], s[24:25], 0, v[138:139]
	global_load_lds_dwordx4 v[216:217], off
	v_lshl_add_u64 v[218:219], s[24:25], 0, v[134:135]
	s_mov_b32 m0, s35
	s_nop 0
	global_load_lds_dwordx4 v[218:219], off
	s_add_u32 s56, s20, 0x80000
	s_addc_u32 s57, s21, 0
	s_add_i32 s58, s58, s30
	s_mov_b32 m0, s58
	s_nop 0
	global_load_lds_dwordx4 v136, s[56:57]
	s_add_i32 m0, s58, 0x2000
	s_nop 0
	global_load_lds_dwordx4 v132, s[56:57]
	s_waitcnt lgkmcnt(0)
	s_waitcnt vmcnt(6)
	s_barrier
; #define PG8_STAGE(bufoff, gbase, voff) do { _Pragma("unroll") for (int _i = 0; _i < 2; ++_i) \
;         __builtin_amdgcn_global_load_lds((const unsigned*)((const char*)(gbase) + (voff)[_i]), (LAS unsigned*)(lds + (bufoff) + ldsw + _i * 8192), 16, 0, 0); } while (0)
; #define PG8_LDA(dst, b, h) do { _Pragma("unroll") for (int m = 0; m < 4; ++m) _Pragma("unroll") for (int k = 0; k < 2; ++k) dst[m][k] = *(const LAS bf16x8*)(lds + PG8_SA(b, h) + aoff + m * 2048 + k * 1024); } while (0)
; #define PG8_LDB(dst, b, h) do { _Pragma("unroll") for (int n = 0; n < 2; ++n) _Pragma("unroll") for (int k = 0; k < 2; ++k) dst[n][k] = *(const LAS bf16x8*)(lds + PG8_SB(b, h) + boff + n * 2048 + k * 1024); } while (0)
; #define PG8_MMA(ai, bj, At, Bt) do { __builtin_amdgcn_s_setprio(1); _Pragma("unroll") for (int m = 0; m < 4; ++m) _Pragma("unroll") for (int n = 0; n < 2; ++n) _Pragma("unroll") for (int k = 0; k < 2; ++k) \
;         acc[ai][bj][m][n] = __builtin_amdgcn_mfma_f32_16x16x32_bf16(Bt[n][k], At[m][k], acc[ai][bj][m][n], 0, 0, 0); __builtin_amdgcn_s_setprio(0); } while (0)
; #define PG8_WAIT_V(n) asm volatile("s_waitcnt vmcnt(" #n ")" ::: "memory")
; #define PG8_WAIT_L(n) asm volatile("s_waitcnt lgkmcnt(" #n ")" ::: "memory")
; #define PG8_BAR __builtin_amdgcn_s_barrier()
; #define PG8_SCHED __builtin_amdgcn_sched_barrier(0)
; template <class Epi, class Sched>
; __device__ __forceinline__ void gemm_phase(LAS unsigned char* lds, const Gemm g, const Sched& S, const Epi& E) {
;     ...
;             PG8_BAR; PG8_WAIT_L(0); PG8_MMA(1, 0, At, B0); PG8_BAR; PG8_SCHED;
;             PG8_STAGE(PG8_SB(0, 1), b2 + hstepB, voffB);
;             PG8_WAIT_V(6); PG8_BAR; PG8_MMA(1, 1, At, B1); PG8_BAR;
;             PG8_LDB(B0, 1, 0); PG8_SCHED; PG8_LDA(At, 1, 0); PG8_STAGE(PG8_SA(0, 1), a2 + hstepA, voffA);
;             PG8_WAIT_L(8); PG8_BAR; PG8_WAIT_L(0); PG8_MMA(0, 0, At, B0); PG8_BAR; PG8_SCHED;
;             PG8_LDB(B1, 1, 1); PG8_STAGE(PG8_SB(1, 0), b3, voffB);
;             PG8_BAR; PG8_WAIT_L(0); PG8_MMA(0, 1, At, B1); PG8_BAR;
;             PG8_LDA(At, 1, 1); PG8_STAGE(PG8_SA(1, 0), a3, voffA);
;             PG8_BAR; PG8_WAIT_L(0); PG8_MMA(1, 0, At, B0); PG8_BAR; PG8_SCHED;
	s_setprio 1
	v_mfma_f32_16x16x32_bf16 v[64:67], v[144:147], v[162:165], v[64:67]
	v_mfma_f32_16x16x32_bf16 v[60:63], v[154:157], v[162:165], v[60:63]
	v_mfma_f32_16x16x32_bf16 v[48:51], v[144:147], v[170:173], v[48:51]
	v_mfma_f32_16x16x32_bf16 v[44:47], v[154:157], v[170:173], v[44:47]
	v_mfma_f32_16x16x32_bf16 v[32:35], v[144:147], v[178:181], v[32:35]
	v_mfma_f32_16x16x32_bf16 v[28:31], v[154:157], v[178:181], v[28:31]
	v_mfma_f32_16x16x32_bf16 v[16:19], v[144:147], v[186:189], v[16:19]
	v_mfma_f32_16x16x32_bf16 v[12:15], v[154:157], v[186:189], v[12:15]
	v_mfma_f32_16x16x32_bf16 v[64:67], v[150:153], v[166:169], v[64:67]
	v_mfma_f32_16x16x32_bf16 v[60:63], v[158:161], v[166:169], v[60:63]
	v_mfma_f32_16x16x32_bf16 v[48:51], v[150:153], v[174:177], v[48:51]
	v_mfma_f32_16x16x32_bf16 v[44:47], v[158:161], v[174:177], v[44:47]
	v_mfma_f32_16x16x32_bf16 v[32:35], v[150:153], v[182:185], v[32:35]
	v_mfma_f32_16x16x32_bf16 v[28:31], v[158:161], v[182:185], v[28:31]
	v_mfma_f32_16x16x32_bf16 v[16:19], v[150:153], v[190:193], v[16:19]
	v_mfma_f32_16x16x32_bf16 v[12:15], v[158:161], v[190:193], v[12:15]
	v_mfma_f32_16x16x32_bf16 v[56:59], v[194:197], v[162:165], v[56:59]
	v_mfma_f32_16x16x32_bf16 v[52:55], v[202:205], v[162:165], v[52:55]
	v_mfma_f32_16x16x32_bf16 v[40:43], v[194:197], v[170:173], v[40:43]
	v_mfma_f32_16x16x32_bf16 v[36:39], v[202:205], v[170:173], v[36:39]
	v_mfma_f32_16x16x32_bf16 v[24:27], v[194:197], v[178:181], v[24:27]
	v_mfma_f32_16x16x32_bf16 v[20:23], v[202:205], v[178:181], v[20:23]
	v_mfma_f32_16x16x32_bf16 v[8:11], v[194:197], v[186:189], v[8:11]
	v_mfma_f32_16x16x32_bf16 v[4:7], v[202:205], v[186:189], v[4:7]
	v_mfma_f32_16x16x32_bf16 v[56:59], v[198:201], v[166:169], v[56:59]
	v_mfma_f32_16x16x32_bf16 v[52:55], v[206:209], v[166:169], v[52:55]
	v_mfma_f32_16x16x32_bf16 v[40:43], v[198:201], v[174:177], v[40:43]
	v_mfma_f32_16x16x32_bf16 v[36:39], v[206:209], v[174:177], v[36:39]
	v_mfma_f32_16x16x32_bf16 v[24:27], v[198:201], v[182:185], v[24:27]
	v_mfma_f32_16x16x32_bf16 v[20:23], v[206:209], v[182:185], v[20:23]
	v_mfma_f32_16x16x32_bf16 v[8:11], v[198:201], v[190:193], v[8:11]
	v_mfma_f32_16x16x32_bf16 v[4:7], v[206:209], v[190:193], v[4:7]
	s_setprio 0
	s_add_i32 s56, 0, 0x18000
	v_add_u32_e32 v2, s56, v1
	s_barrier
	ds_read_b128 v[144:147], v2
	ds_read_b128 v[150:153], v2 offset:1024
	ds_read_b128 v[154:157], v2 offset:2048
	ds_read_b128 v[158:161], v2 offset:3072
	s_add_u32 s24, s24, 0x80000
	s_addc_u32 s25, s25, 0
	ds_read_b128 v[162:165], v149 offset:32768
	ds_read_b128 v[166:169], v149 offset:33792
	ds_read_b128 v[170:173], v149 offset:34816
	ds_read_b128 v[174:177], v149 offset:35840
	ds_read_b128 v[178:181], v149 offset:36864
	ds_read_b128 v[182:185], v149 offset:37888
	ds_read_b128 v[186:189], v149 offset:38912
	ds_read_b128 v[190:193], v149 offset:39936
	s_mov_b32 m0, s36
	s_nop 0
	global_load_lds_dwordx4 v138, s[24:25]
	s_mov_b32 m0, s37
	s_nop 0
	global_load_lds_dwordx4 v134, s[24:25]
	s_add_i32 s24, 0, 0x1c000
	v_add_u32_e32 v2, s24, v1
	ds_read_b128 v[194:197], v2
	ds_read_b128 v[198:201], v2 offset:1024
	ds_read_b128 v[202:205], v2 offset:2048
	ds_read_b128 v[206:209], v2 offset:3072
	s_waitcnt lgkmcnt(0)
	s_barrier
	s_setprio 1
	v_mfma_f32_16x16x32_bf16 v[128:131], v[144:147], v[162:165], v[128:131]
	v_mfma_f32_16x16x32_bf16 v[124:127], v[154:157], v[162:165], v[124:127]
	v_mfma_f32_16x16x32_bf16 v[112:115], v[144:147], v[170:173], v[112:115]
	v_mfma_f32_16x16x32_bf16 v[108:111], v[154:157], v[170:173], v[108:111]
	v_mfma_f32_16x16x32_bf16 v[96:99], v[144:147], v[178:181], v[96:99]
	v_mfma_f32_16x16x32_bf16 v[92:95], v[154:157], v[178:181], v[92:95]
	v_mfma_f32_16x16x32_bf16 v[80:83], v[144:147], v[186:189], v[80:83]
	v_mfma_f32_16x16x32_bf16 v[76:79], v[154:157], v[186:189], v[76:79]
	v_mfma_f32_16x16x32_bf16 v[128:131], v[150:153], v[166:169], v[128:131]
	v_mfma_f32_16x16x32_bf16 v[124:127], v[158:161], v[166:169], v[124:127]
	v_mfma_f32_16x16x32_bf16 v[112:115], v[150:153], v[174:177], v[112:115]
	v_mfma_f32_16x16x32_bf16 v[108:111], v[158:161], v[174:177], v[108:111]
	v_mfma_f32_16x16x32_bf16 v[96:99], v[150:153], v[182:185], v[96:99]
	v_mfma_f32_16x16x32_bf16 v[92:95], v[158:161], v[182:185], v[92:95]
	v_mfma_f32_16x16x32_bf16 v[80:83], v[150:153], v[190:193], v[80:83]
	v_mfma_f32_16x16x32_bf16 v[76:79], v[158:161], v[190:193], v[76:79]
	v_mfma_f32_16x16x32_bf16 v[120:123], v[194:197], v[162:165], v[120:123]
	v_mfma_f32_16x16x32_bf16 v[116:119], v[202:205], v[162:165], v[116:119]
	v_mfma_f32_16x16x32_bf16 v[104:107], v[194:197], v[170:173], v[104:107]
	v_mfma_f32_16x16x32_bf16 v[100:103], v[202:205], v[170:173], v[100:103]
	v_mfma_f32_16x16x32_bf16 v[88:91], v[194:197], v[178:181], v[88:91]
	v_mfma_f32_16x16x32_bf16 v[84:87], v[202:205], v[178:181], v[84:87]
	v_mfma_f32_16x16x32_bf16 v[72:75], v[194:197], v[186:189], v[72:75]
	v_mfma_f32_16x16x32_bf16 v[68:71], v[202:205], v[186:189], v[68:71]
	v_mfma_f32_16x16x32_bf16 v[120:123], v[198:201], v[166:169], v[120:123]
	v_mfma_f32_16x16x32_bf16 v[116:119], v[206:209], v[166:169], v[116:119]
	v_mfma_f32_16x16x32_bf16 v[104:107], v[198:201], v[174:177], v[104:107]
	v_mfma_f32_16x16x32_bf16 v[100:103], v[206:209], v[174:177], v[100:103]
	v_mfma_f32_16x16x32_bf16 v[88:91], v[198:201], v[182:185], v[88:91]
	v_mfma_f32_16x16x32_bf16 v[84:87], v[206:209], v[182:185], v[84:87]
	v_mfma_f32_16x16x32_bf16 v[72:75], v[198:201], v[190:193], v[72:75]
	v_mfma_f32_16x16x32_bf16 v[68:71], v[206:209], v[190:193], v[68:71]
	s_setprio 0
	s_barrier
; __device__ __forceinline__ unsigned cvt_pk_bf16(float lo, float hi) { const f32x2 v = {lo, hi}; const bf16v2_ r = __builtin_convertvector(v, bf16v2_); return __builtin_bit_cast(unsigned, r); }
; __device__ __forceinline__ int opaque_tid() { int t = threadIdx.x; asm volatile("" : "+v"(t)); return t; }
; #define PG8_STAGE(bufoff, gbase, voff) do { _Pragma("unroll") for (int _i = 0; _i < 2; ++_i) \
;         __builtin_amdgcn_global_load_lds((const unsigned*)((const char*)(gbase) + (voff)[_i]), (LAS unsigned*)(lds + (bufoff) + ldsw + _i * 8192), 16, 0, 0); } while (0)
; #define PG8_WAIT_V(n) asm volatile("s_waitcnt vmcnt(" #n ")" ::: "memory")
; #define PG8_WAIT_L(n) asm volatile("s_waitcnt lgkmcnt(" #n ")" ::: "memory")
; #define PG8_BAR __builtin_amdgcn_s_barrier()
; template <class Epi, class Sched>
; __device__ __forceinline__ void gemm_phase(LAS unsigned char* lds, const Gemm g, const Sched& S, const Epi& E) {
;     ...
;             PG8_LDA(At, 1, 1); PG8_STAGE(PG8_SA(1, 0), a3, voffA);
;             PG8_BAR; PG8_WAIT_L(0); PG8_MMA(1, 0, At, B0); PG8_BAR; PG8_SCHED;
;             PG8_STAGE(PG8_SB(1, 1), b3 + hstepB, voffB);
;             PG8_WAIT_V(6); PG8_BAR; PG8_MMA(1, 1, At, B1); PG8_BAR;
;     __device__ __forceinline__ void operator()(const f32x4 (&acc)[2][2][4][2], const Unit& u, int wr, int wc, int ui, int) const {
;         const int ol_ = opaque_tid() & 63, fr = ol_ & 15, fq = ol_ >> 4;
;         const int row0 = u.pm * BM + wr * 64 + fr, col0 = u.pn * BM + wc * 32 + 8 * fq;
;         const bool cmp = (u.pn == 8 || u.pn == 9);
;         bf16_t* cb = (u.pn == 8) ? kcmp : vcmp;
;         float r_[2][4];
;         rs_read(r_, ui, wr, fr);
; #pragma unroll
;         for (int ai = 0; ai < 2; ++ai)
; #pragma unroll
;             for (int m = 0; m < 4; ++m) { const int row = row0 + ai * HALF + m * 16; const float r = r_[ai][m];
; #pragma unroll
;                 for (int bj = 0; bj < 2; ++bj) { const f32x4 v0 = acc[ai][bj][m][0] * r, v1 = acc[ai][bj][m][1] * r;
;                     u32x4 w; w.x = cvt_pk_bf16(v0[0], v0[1]); w.y = cvt_pk_bf16(v0[2], v0[3]); w.z = cvt_pk_bf16(v1[0], v1[1]); w.w = cvt_pk_bf16(v1[2], v1[3]);
;                     bf16_t* p = cmp ? cb + ((size_t)((row / T) * 2 + bj) * T + (row % T)) * 128 + wc * 32 + 8 * fq
;                                     : O + (size_t)row * ldc + col0 + bj * HALF;
;                     *(u32x4*)p = w; } }
	ds_read_b128 v[162:165], v149 offset:49152
	ds_read_b128 v[166:169], v149 offset:50176
	ds_read_b128 v[170:173], v149 offset:51200
	ds_read_b128 v[174:177], v149 offset:52224
	ds_read_b128 v[178:181], v149 offset:53248
	ds_read_b128 v[182:185], v149 offset:54272
	ds_read_b128 v[186:189], v149 offset:55296
	ds_read_b128 v[190:193], v149 offset:56320
	s_add_i32 s25, s56, s30
	v_lshl_add_u64 v[210:211], v[210:211], 0, s[8:9]
	s_mov_b32 m0, s25
	s_nop 0
	global_load_lds_dwordx4 v[210:211], off
	v_lshl_add_u64 v[210:211], v[212:213], 0, s[8:9]
	s_add_i32 m0, s25, 0x2000
	s_nop 0
	global_load_lds_dwordx4 v[210:211], off
	s_mov_b32 m0, s40
	v_lshl_add_u64 v[210:211], v[216:217], 0, s[8:9]
	global_load_lds_dwordx4 v[210:211], off
	v_lshl_add_u64 v[210:211], v[218:219], 0, s[8:9]
	s_mov_b32 m0, s41
	s_nop 0
	global_load_lds_dwordx4 v[210:211], off
	s_add_u32 s20, s20, 0x80080
	s_addc_u32 s21, s21, 0
	s_add_i32 s24, s24, s30
	s_mov_b32 m0, s24
	s_nop 0
	global_load_lds_dwordx4 v136, s[20:21]
	s_add_i32 m0, s24, 0x2000
	s_nop 0
	global_load_lds_dwordx4 v132, s[20:21]
	s_waitcnt lgkmcnt(0)
	s_waitcnt vmcnt(6)
	s_barrier
	s_setprio 1
	v_mfma_f32_16x16x32_bf16 v[64:67], v[144:147], v[162:165], v[64:67]
	v_mfma_f32_16x16x32_bf16 v[60:63], v[154:157], v[162:165], v[60:63]
	v_mfma_f32_16x16x32_bf16 v[48:51], v[144:147], v[170:173], v[48:51]
	v_mfma_f32_16x16x32_bf16 v[44:47], v[154:157], v[170:173], v[44:47]
	v_mfma_f32_16x16x32_bf16 v[32:35], v[144:147], v[178:181], v[32:35]
	v_mfma_f32_16x16x32_bf16 v[28:31], v[154:157], v[178:181], v[28:31]
	v_mfma_f32_16x16x32_bf16 v[16:19], v[144:147], v[186:189], v[16:19]
	v_mfma_f32_16x16x32_bf16 v[12:15], v[154:157], v[186:189], v[12:15]
	v_mfma_f32_16x16x32_bf16 v[64:67], v[150:153], v[166:169], v[64:67]
	v_mfma_f32_16x16x32_bf16 v[60:63], v[158:161], v[166:169], v[60:63]
	v_mfma_f32_16x16x32_bf16 v[48:51], v[150:153], v[174:177], v[48:51]
	v_mfma_f32_16x16x32_bf16 v[44:47], v[158:161], v[174:177], v[44:47]
	v_mfma_f32_16x16x32_bf16 v[32:35], v[150:153], v[182:185], v[32:35]
	v_mfma_f32_16x16x32_bf16 v[28:31], v[158:161], v[182:185], v[28:31]
	v_mfma_f32_16x16x32_bf16 v[16:19], v[150:153], v[190:193], v[16:19]
	v_mfma_f32_16x16x32_bf16 v[12:15], v[158:161], v[190:193], v[12:15]
	v_mfma_f32_16x16x32_bf16 v[56:59], v[194:197], v[162:165], v[56:59]
	v_mfma_f32_16x16x32_bf16 v[52:55], v[202:205], v[162:165], v[52:55]
	v_mfma_f32_16x16x32_bf16 v[40:43], v[194:197], v[170:173], v[40:43]
	v_mfma_f32_16x16x32_bf16 v[36:39], v[202:205], v[170:173], v[36:39]
	v_mfma_f32_16x16x32_bf16 v[24:27], v[194:197], v[178:181], v[24:27]
	v_mfma_f32_16x16x32_bf16 v[20:23], v[202:205], v[178:181], v[20:23]
	v_mfma_f32_16x16x32_bf16 v[8:11], v[194:197], v[186:189], v[8:11]
	v_mfma_f32_16x16x32_bf16 v[4:7], v[202:205], v[186:189], v[4:7]
	v_mfma_f32_16x16x32_bf16 v[56:59], v[198:201], v[166:169], v[56:59]
	v_mfma_f32_16x16x32_bf16 v[52:55], v[206:209], v[166:169], v[52:55]
	v_mfma_f32_16x16x32_bf16 v[40:43], v[198:201], v[174:177], v[40:43]
	v_mfma_f32_16x16x32_bf16 v[36:39], v[206:209], v[174:177], v[36:39]
	v_mfma_f32_16x16x32_bf16 v[24:27], v[198:201], v[182:185], v[24:27]
	v_mfma_f32_16x16x32_bf16 v[20:23], v[206:209], v[182:185], v[20:23]
	v_mfma_f32_16x16x32_bf16 v[8:11], v[198:201], v[190:193], v[8:11]
	v_mfma_f32_16x16x32_bf16 v[4:7], v[206:209], v[190:193], v[4:7]
	s_setprio 0
	s_add_i32 s55, s55, 2
	s_add_u32 s6, s6, 0x100
	s_addc_u32 s7, s7, 0
	s_add_u32 s53, s53, 0x100
	s_addc_u32 s54, s54, 0
	s_cmp_gt_u32 s55, 29
	s_barrier
	s_cbranch_scc0 .LBB0_352
	s_lshl_b32 s1, s50, 8
	s_lshl_b32 s6, s44, 8
	s_add_i32 s1, s1, s38
	s_or_b32 s6, s6, s39
	s_cmp_eq_u32 s44, 8
	s_mov_b32 s7, 0x3bcb0000
	s_cselect_b32 s15, s7, 0x3ccb4000
	s_lshl_b32 s7, s45, 10
	v_mov_b32_e32 v2, v0
	s_and_b32 s7, s7, 0x400
	s_add_i32 s7, s46, s7
	v_and_b32_e32 v144, 15, v2
	v_or_b32_e32 v148, s1, v144
	v_lshl_add_u32 v144, v144, 2, s7
	v_lshrrev_b32_e32 v2, 1, v2
	ds_read2_b32 v[164:165], v144 offset1:16
	ds_read2_b32 v[160:161], v144 offset0:32 offset1:48
	ds_read2_b32 v[156:157], v144 offset0:128 offset1:144
	ds_read2_b32 v[152:153], v144 offset0:160 offset1:176
	v_and_b32_e32 v2, 24, v2
	v_or_b32_e32 v146, s6, v2
	s_and_b32 s6, s44, -2
	s_cmp_lg_u32 s6, 8
	s_cselect_b64 s[6:7], -1, 0
	s_add_u32 s24, s47, s15
	s_waitcnt lgkmcnt(0)
	v_mov_b32_e32 v162, v165
	v_mov_b32_e32 v158, v161
	v_mov_b32_e32 v154, v157
	v_mov_b32_e32 v144, v153
	v_ashrrev_i32_e32 v147, 31, v146
	s_addc_u32 s25, s48, 0
	s_mov_b64 s[20:21], -1
	s_and_b64 vcc, exec, s[6:7]
	s_cbranch_vccz .LBB0_355
	v_mov_b64_e32 v[150:151], s[92:93]
	s_movk_i32 s15, 0x3600
	v_mad_i64_i32 v[150:151], s[20:21], v148, s15, v[150:151]
	v_lshl_add_u64 v[170:171], v[146:147], 1, v[150:151]
	s_mov_b64 s[20:21], 0

; #define PG8_STAGE(bufoff, gbase, voff) do { _Pragma("unroll") for (int _i = 0; _i < 2; ++_i) \
;         __builtin_amdgcn_global_load_lds((const unsigned*)((const char*)(gbase) + (voff)[_i]), (LAS unsigned*)(lds + (bufoff) + ldsw + _i * 8192), 16, 0, 0); } while (0)
; #define PG8_WAIT_V(n) asm volatile("s_waitcnt vmcnt(" #n ")" ::: "memory")
; #define PG8_BAR __builtin_amdgcn_s_barrier()
; template <class Epi, class Sched>
; __device__ __forceinline__ void gemm_phase(LAS unsigned char* lds, const Gemm g, const Sched& S, const Epi& E) {
;     ...
;     const char* cA = (const char*)g.A + (size_t)cur.pm * tstepA; const char* cB = (const char*)g.Bt + (size_t)cur.pn * tstepB;
;     S.a_ready(cur);
;     PG8_STAGE(PG8_SB(0, 0), cB, voffB); PG8_STAGE(PG8_SA(0, 0), cA, voffA); PG8_STAGE(PG8_SB(0, 1), cB + hstepB, voffB); PG8_STAGE(PG8_SA(0, 1), cA + hstepA, voffA);
;     if (wr == 1) PG8_BAR;
;     PG8_WAIT_V(4); PG8_BAR;
;     PG8_STAGE(PG8_SB(1, 0), cB + kstep, voffB); PG8_STAGE(PG8_SA(1, 0), cA + kstep, voffA); PG8_STAGE(PG8_SB(1, 1), cB + hstepB + kstep, voffB);
;     PG8_WAIT_V(6); PG8_BAR;
.LBB0_483:
	s_lshl_b32 s60, s6, 6
	v_and_b32_e32 v18, 48, v1
	s_lshl_b32 s1, s6, 13
	v_lshlrev_b32_e32 v19, 6, v1
	s_movk_i32 s6, 0x3c0
	v_lshlrev_b32_e32 v1, 2, v1
	v_and_or_b32 v18, v19, s6, v18
	v_and_b32_e32 v1, 32, v1
	v_bitop3_b32 v19, v18, s1, v1 bitop3:0xde
	s_lshl_b32 s1, s7, 5
	s_and_b32 s61, s1, 0x60
	s_add_i32 m0, s30, 0x18000
	v_lshl_add_u64 v[10:11], v[10:11], 0, s[8:9]
	s_lshl_b32 s1, s61, 7
	s_waitcnt vmcnt(2)
	s_barrier
	global_load_lds_dwordx4 v[10:11], off
	v_lshl_add_u64 v[8:9], v[8:9], 0, s[8:9]
	s_add_i32 m0, s30, 0x1a000
	s_add_i32 s62, s30, 0x8000
	s_add_i32 s63, s30, 0xa000
	global_load_lds_dwordx4 v[8:9], off
	v_lshl_add_u64 v[6:7], v[6:7], 0, s[8:9]
	s_mov_b32 m0, s62
	s_add_u32 s6, s44, 0x100080
	global_load_lds_dwordx4 v[6:7], off
	v_lshl_add_u64 v[4:5], v[4:5], 0, s[8:9]
	s_mov_b32 m0, s63
	s_addc_u32 s7, s45, 0
	global_load_lds_dwordx4 v[4:5], off
	s_add_i32 m0, s30, 0x1c000
	v_lshl_add_u64 v[4:5], s[6:7], 0, v[2:3]
	global_load_lds_dwordx4 v[4:5], off
	v_lshl_add_u64 v[4:5], s[6:7], 0, v[136:137]
	s_add_i32 m0, s30, 0x1e000
	v_bitop3_b32 v1, s1, v18, v1 bitop3:0xf6
	global_load_lds_dwordx4 v[4:5], off
	v_lshlrev_b32_e32 v4, 15, v12
	v_and_b32_e32 v4, 0xffff0000, v4
	v_lshl_add_u32 v4, v13, 12, v4
	v_and_b32_e32 v5, 1, v12
	v_lshl_or_b32 v4, v5, 6, v4
	v_lshl_add_u32 v138, v14, 1, v4
	v_lshlrev_b32_e32 v4, 15, v15
	s_lshl_b32 s1, s20, 13
	v_and_b32_e32 v4, 0xffff0000, v4
	s_add_i32 s6, s35, s1
	s_mov_b32 s7, s3
	v_readlane_b32 s48, v252, 0
	s_waitcnt vmcnt(6)
	v_lshl_add_u32 v4, v16, 12, v4
	v_and_b32_e32 v5, 1, v15
	s_lshl_b64 s[6:7], s[6:7], 2
	v_readlane_b32 s50, v252, 2
	v_lshl_or_b32 v4, v5, 6, v4
	v_readlane_b32 s51, v252, 3
	s_add_u32 s46, s50, s6
	v_mov_b32_e32 v139, v3
	v_lshl_add_u32 v140, v17, 1, v4
	v_mov_b32_e32 v141, v3
	s_addc_u32 s47, s51, s7
	s_mov_b32 s1, 0
	v_add_u32_e32 v156, 0, v19
	s_mov_b64 s[6:7], s[44:45]
	s_mov_b32 s64, 0
	s_barrier
	v_readlane_b32 s49, v252, 1

; #define PG8_STAGE(bufoff, gbase, voff) do { _Pragma("unroll") for (int _i = 0; _i < 2; ++_i) \
;         __builtin_amdgcn_global_load_lds((const unsigned*)((const char*)(gbase) + (voff)[_i]), (LAS unsigned*)(lds + (bufoff) + ldsw + _i * 8192), 16, 0, 0); } while (0)
; #define PG8_LDA(dst, b, h) do { _Pragma("unroll") for (int m = 0; m < 4; ++m) _Pragma("unroll") for (int k = 0; k < 2; ++k) dst[m][k] = *(const LAS bf16x8*)(lds + PG8_SA(b, h) + aoff + m * 2048 + k * 1024); } while (0)
; #define PG8_LDB(dst, b, h) do { _Pragma("unroll") for (int n = 0; n < 2; ++n) _Pragma("unroll") for (int k = 0; k < 2; ++k) dst[n][k] = *(const LAS bf16x8*)(lds + PG8_SB(b, h) + boff + n * 2048 + k * 1024); } while (0)
; #define PG8_MMA(ai, bj, At, Bt) do { __builtin_amdgcn_s_setprio(1); _Pragma("unroll") for (int m = 0; m < 4; ++m) _Pragma("unroll") for (int n = 0; n < 2; ++n) _Pragma("unroll") for (int k = 0; k < 2; ++k) \
;         acc[ai][bj][m][n] = __builtin_amdgcn_mfma_f32_16x16x32_bf16(Bt[n][k], At[m][k], acc[ai][bj][m][n], 0, 0, 0); __builtin_amdgcn_s_setprio(0); } while (0)
; #define PG8_WAIT_V(n) asm volatile("s_waitcnt vmcnt(" #n ")" ::: "memory")
; #define PG8_WAIT_L(n) asm volatile("s_waitcnt lgkmcnt(" #n ")" ::: "memory")
; template <class Epi, class Sched>
; __device__ __forceinline__ void gemm_phase(LAS unsigned char* lds, const Gemm g, const Sched& S, const Epi& E) {
;     ...
;             const bool last = (t == nt - 2);
;             const char* a1 = cA + (size_t)(t + 1) * kstep;
;             const char* a2 = last ? nA : cA + (size_t)(t + 2) * kstep; const char* b2 = last ? nB : cB + (size_t)(t + 2) * kstep;
;             const char* a3 = a2 + kstep; const char* b3 = b2 + kstep;
;             if (last && has_next) S.a_ready(nxt);
;             PG8_LDB(B0, 0, 0); PG8_SCHED; PG8_LDA(At, 0, 0); PG8_STAGE(PG8_SA(1, 1), a1 + hstepA, voffA);
;             PG8_WAIT_L(8); PG8_BAR; PG8_WAIT_L(0); PG8_MMA(0, 0, At, B0); PG8_BAR; PG8_SCHED;
;             PG8_LDB(B1, 0, 1); PG8_STAGE(PG8_SB(0, 0), b2, voffB);
;             PG8_BAR; PG8_WAIT_L(0); PG8_MMA(0, 1, At, B1); PG8_BAR;
;             PG8_LDA(At, 0, 1); PG8_STAGE(PG8_SA(0, 0), a2, voffA);
;             PG8_BAR; PG8_WAIT_L(0); PG8_MMA(1, 0, At, B0); PG8_BAR; PG8_SCHED;
;             PG8_STAGE(PG8_SB(0, 1), b2 + hstepB, voffB);
;             PG8_WAIT_V(6); PG8_BAR; PG8_MMA(1, 1, At, B1); PG8_BAR;
.LBB0_491:
	s_add_u32 s6, s4, 0xfff80080
	s_addc_u32 s7, s5, -1
	s_add_i32 s68, 0, 0x10000
	v_add_u32_e32 v154, s68, v1
	ds_read_b128 v[142:145], v154
	ds_read_b128 v[146:149], v154 offset:1024
	ds_read_b128 v[150:153], v154 offset:2048
	ds_read_b128 v[158:161], v154 offset:3072
	s_cmp_eq_u32 s67, 60
	s_cselect_b32 s15, s18, s7
	s_cselect_b32 s14, s19, s6
	s_cselect_b32 s7, s51, s66
	s_cselect_b32 s6, s53, s65
	ds_read_b128 v[162:165], v156
	ds_read_b128 v[166:169], v156 offset:1024
	ds_read_b128 v[170:173], v156 offset:2048
	ds_read_b128 v[174:177], v156 offset:3072
	ds_read_b128 v[178:181], v156 offset:4096
	ds_read_b128 v[182:185], v156 offset:5120
	ds_read_b128 v[186:189], v156 offset:6144
	ds_read_b128 v[190:193], v156 offset:7168
	s_add_i32 s70, 0, 0x14000
	v_add_u32_e32 v154, s70, v1
	ds_read_b128 v[194:197], v154
	ds_read_b128 v[198:201], v154 offset:1024
	ds_read_b128 v[202:205], v154 offset:2048
	ds_read_b128 v[206:209], v154 offset:3072
	s_add_i32 m0, s30, 0xc000
	s_nop 0
	global_load_lds_dwordx4 v138, s[4:5]
	s_add_i32 m0, s30, 0xe000
	s_nop 0
	global_load_lds_dwordx4 v140, s[4:5]
	s_waitcnt lgkmcnt(0)
	s_barrier
	s_setprio 1
	v_mfma_f32_16x16x32_bf16 v[128:131], v[142:145], v[162:165], v[128:131]
	v_mfma_f32_16x16x32_bf16 v[124:127], v[150:153], v[162:165], v[124:127]
	v_mfma_f32_16x16x32_bf16 v[120:123], v[142:145], v[170:173], v[120:123]
	v_mfma_f32_16x16x32_bf16 v[116:119], v[150:153], v[170:173], v[116:119]
	v_mfma_f32_16x16x32_bf16 v[112:115], v[142:145], v[178:181], v[112:115]
	v_mfma_f32_16x16x32_bf16 v[108:111], v[150:153], v[178:181], v[108:111]
	v_mfma_f32_16x16x32_bf16 v[104:107], v[142:145], v[186:189], v[104:107]
	v_mfma_f32_16x16x32_bf16 v[100:103], v[150:153], v[186:189], v[100:103]
	v_mfma_f32_16x16x32_bf16 v[128:131], v[146:149], v[166:169], v[128:131]
	v_mfma_f32_16x16x32_bf16 v[124:127], v[158:161], v[166:169], v[124:127]
	v_mfma_f32_16x16x32_bf16 v[120:123], v[146:149], v[174:177], v[120:123]
	v_mfma_f32_16x16x32_bf16 v[116:119], v[158:161], v[174:177], v[116:119]
	v_mfma_f32_16x16x32_bf16 v[112:115], v[146:149], v[182:185], v[112:115]
	v_mfma_f32_16x16x32_bf16 v[108:111], v[158:161], v[182:185], v[108:111]
	v_mfma_f32_16x16x32_bf16 v[104:107], v[146:149], v[190:193], v[104:107]
	v_mfma_f32_16x16x32_bf16 v[100:103], v[158:161], v[190:193], v[100:103]
	v_mfma_f32_16x16x32_bf16 v[64:67], v[194:197], v[162:165], v[64:67]
	v_mfma_f32_16x16x32_bf16 v[60:63], v[202:205], v[162:165], v[60:63]
	v_mfma_f32_16x16x32_bf16 v[56:59], v[194:197], v[170:173], v[56:59]
	v_mfma_f32_16x16x32_bf16 v[52:55], v[202:205], v[170:173], v[52:55]
	v_mfma_f32_16x16x32_bf16 v[48:51], v[194:197], v[178:181], v[48:51]
	v_mfma_f32_16x16x32_bf16 v[44:47], v[202:205], v[178:181], v[44:47]
	v_mfma_f32_16x16x32_bf16 v[40:43], v[194:197], v[186:189], v[40:43]
	v_mfma_f32_16x16x32_bf16 v[36:39], v[202:205], v[186:189], v[36:39]
	v_mfma_f32_16x16x32_bf16 v[64:67], v[198:201], v[166:169], v[64:67]
	v_mfma_f32_16x16x32_bf16 v[60:63], v[206:209], v[166:169], v[60:63]
	v_mfma_f32_16x16x32_bf16 v[56:59], v[198:201], v[174:177], v[56:59]
	v_mfma_f32_16x16x32_bf16 v[52:55], v[206:209], v[174:177], v[52:55]
	v_mfma_f32_16x16x32_bf16 v[48:51], v[198:201], v[182:185], v[48:51]
	v_mfma_f32_16x16x32_bf16 v[44:47], v[206:209], v[182:185], v[44:47]
	v_mfma_f32_16x16x32_bf16 v[40:43], v[198:201], v[190:193], v[40:43]
	v_mfma_f32_16x16x32_bf16 v[36:39], v[206:209], v[190:193], v[36:39]
	s_setprio 0
	s_barrier
	ds_read_b128 v[162:165], v156 offset:16384
	ds_read_b128 v[166:169], v156 offset:17408
	ds_read_b128 v[170:173], v156 offset:18432
	ds_read_b128 v[174:177], v156 offset:19456
	ds_read_b128 v[178:181], v156 offset:20480
	ds_read_b128 v[182:185], v156 offset:21504
	ds_read_b128 v[186:189], v156 offset:22528
	ds_read_b128 v[190:193], v156 offset:23552
	s_add_i32 s68, s68, s29
	v_lshl_add_u64 v[154:155], s[6:7], 0, v[2:3]
	s_mov_b32 m0, s68
	v_lshl_add_u64 v[210:211], s[6:7], 0, v[136:137]
	global_load_lds_dwordx4 v[154:155], off
	s_add_i32 m0, s68, 0x2000
	s_nop 0
	global_load_lds_dwordx4 v[210:211], off
	s_mov_b32 m0, s30
	v_lshl_add_u64 v[212:213], s[14:15], 0, v[132:133]
	global_load_lds_dwordx4 v[212:213], off
	v_lshl_add_u64 v[216:217], s[14:15], 0, v[134:135]
	s_mov_b32 m0, s31
	s_nop 0
	global_load_lds_dwordx4 v[216:217], off
	s_add_u32 s68, s6, 0x100000
	s_addc_u32 s69, s7, 0
	s_add_i32 s70, s70, s29
	s_mov_b32 m0, s70
	s_nop 0
	global_load_lds_dwordx4 v2, s[68:69]
	s_add_i32 m0, s70, 0x2000
	s_nop 0
	global_load_lds_dwordx4 v136, s[68:69]
	s_waitcnt lgkmcnt(0)
	s_waitcnt vmcnt(6)
	s_barrier
; #define PG8_STAGE(bufoff, gbase, voff) do { _Pragma("unroll") for (int _i = 0; _i < 2; ++_i) \
;         __builtin_amdgcn_global_load_lds((const unsigned*)((const char*)(gbase) + (voff)[_i]), (LAS unsigned*)(lds + (bufoff) + ldsw + _i * 8192), 16, 0, 0); } while (0)
; #define PG8_LDA(dst, b, h) do { _Pragma("unroll") for (int m = 0; m < 4; ++m) _Pragma("unroll") for (int k = 0; k < 2; ++k) dst[m][k] = *(const LAS bf16x8*)(lds + PG8_SA(b, h) + aoff + m * 2048 + k * 1024); } while (0)
; #define PG8_WAIT_V(n) asm volatile("s_waitcnt vmcnt(" #n ")" ::: "memory")
; template <class Epi, class Sched>
; __device__ __forceinline__ void gemm_phase(LAS unsigned char* lds, const Gemm g, const Sched& S, const Epi& E) {
;     ...
;         for (int t = 0; t < nt; t += 2) {
;             const bool last = (t == nt - 2);
;             const char* a1 = cA + (size_t)(t + 1) * kstep;
;             const char* a2 = last ? nA : cA + (size_t)(t + 2) * kstep; const char* b2 = last ? nB : cB + (size_t)(t + 2) * kstep;
;             const char* a3 = a2 + kstep; const char* b3 = b2 + kstep;
;             if (last && has_next) S.a_ready(nxt);
;             PG8_LDB(B0, 0, 0); PG8_SCHED; PG8_LDA(At, 0, 0); PG8_STAGE(PG8_SA(1, 1), a1 + hstepA, voffA);
;             PG8_WAIT_L(8); PG8_BAR; PG8_WAIT_L(0); PG8_MMA(0, 0, At, B0); PG8_BAR; PG8_SCHED;
;             PG8_LDB(B1, 0, 1); PG8_STAGE(PG8_SB(0, 0), b2, voffB);
;             PG8_BAR; PG8_WAIT_L(0); PG8_MMA(0, 1, At, B1); PG8_BAR;
;             PG8_LDA(At, 0, 1); PG8_STAGE(PG8_SA(0, 0), a2, voffA);
;             PG8_BAR; PG8_WAIT_L(0); PG8_MMA(1, 0, At, B0); PG8_BAR; PG8_SCHED;
;             PG8_STAGE(PG8_SB(0, 1), b2 + hstepB, voffB);
;             PG8_WAIT_V(6); PG8_BAR; PG8_MMA(1, 1, At, B1); PG8_BAR;
;             PG8_LDB(B0, 1, 0); PG8_SCHED; PG8_LDA(At, 1, 0); PG8_STAGE(PG8_SA(0, 1), a2 + hstepA, voffA);
;             PG8_WAIT_L(8); PG8_BAR; PG8_WAIT_L(0); PG8_MMA(0, 0, At, B0); PG8_BAR; PG8_SCHED;
;             PG8_LDB(B1, 1, 1); PG8_STAGE(PG8_SB(1, 0), b3, voffB);
;             PG8_BAR; PG8_WAIT_L(0); PG8_MMA(0, 1, At, B1); PG8_BAR;
;             PG8_LDA(At, 1, 1); PG8_STAGE(PG8_SA(1, 0), a3, voffA);
;             PG8_BAR; PG8_WAIT_L(0); PG8_MMA(1, 0, At, B0); PG8_BAR; PG8_SCHED;
;             PG8_STAGE(PG8_SB(1, 1), b3 + hstepB, voffB);
;             PG8_WAIT_V(6); PG8_BAR; PG8_MMA(1, 1, At, B1); PG8_BAR;
	s_setprio 1
	v_mfma_f32_16x16x32_bf16 v[96:99], v[142:145], v[162:165], v[96:99]
	v_mfma_f32_16x16x32_bf16 v[92:95], v[150:153], v[162:165], v[92:95]
	v_mfma_f32_16x16x32_bf16 v[88:91], v[142:145], v[170:173], v[88:91]
	v_mfma_f32_16x16x32_bf16 v[84:87], v[150:153], v[170:173], v[84:87]
	v_mfma_f32_16x16x32_bf16 v[80:83], v[142:145], v[178:181], v[80:83]
	v_mfma_f32_16x16x32_bf16 v[76:79], v[150:153], v[178:181], v[76:79]
	v_mfma_f32_16x16x32_bf16 v[72:75], v[142:145], v[186:189], v[72:75]
	v_mfma_f32_16x16x32_bf16 v[68:71], v[150:153], v[186:189], v[68:71]
	v_mfma_f32_16x16x32_bf16 v[96:99], v[146:149], v[166:169], v[96:99]
	v_mfma_f32_16x16x32_bf16 v[92:95], v[158:161], v[166:169], v[92:95]
	v_mfma_f32_16x16x32_bf16 v[88:91], v[146:149], v[174:177], v[88:91]
	v_mfma_f32_16x16x32_bf16 v[84:87], v[158:161], v[174:177], v[84:87]
	v_mfma_f32_16x16x32_bf16 v[80:83], v[146:149], v[182:185], v[80:83]
	v_mfma_f32_16x16x32_bf16 v[76:79], v[158:161], v[182:185], v[76:79]
	v_mfma_f32_16x16x32_bf16 v[72:75], v[146:149], v[190:193], v[72:75]
	v_mfma_f32_16x16x32_bf16 v[68:71], v[158:161], v[190:193], v[68:71]
	v_mfma_f32_16x16x32_bf16 v[32:35], v[194:197], v[162:165], v[32:35]
	v_mfma_f32_16x16x32_bf16 v[28:31], v[202:205], v[162:165], v[28:31]
	v_mfma_f32_16x16x32_bf16 v[24:27], v[194:197], v[170:173], v[24:27]
	v_mfma_f32_16x16x32_bf16 v[20:23], v[202:205], v[170:173], v[20:23]
	v_mfma_f32_16x16x32_bf16 v[16:19], v[194:197], v[178:181], v[16:19]
	v_mfma_f32_16x16x32_bf16 v[12:15], v[202:205], v[178:181], v[12:15]
	v_mfma_f32_16x16x32_bf16 v[8:11], v[194:197], v[186:189], v[8:11]
	v_mfma_f32_16x16x32_bf16 v[4:7], v[202:205], v[186:189], v[4:7]
	v_mfma_f32_16x16x32_bf16 v[32:35], v[198:201], v[166:169], v[32:35]
	v_mfma_f32_16x16x32_bf16 v[28:31], v[206:209], v[166:169], v[28:31]
	v_mfma_f32_16x16x32_bf16 v[24:27], v[198:201], v[174:177], v[24:27]
	v_mfma_f32_16x16x32_bf16 v[20:23], v[206:209], v[174:177], v[20:23]
	v_mfma_f32_16x16x32_bf16 v[16:19], v[198:201], v[182:185], v[16:19]
	v_mfma_f32_16x16x32_bf16 v[12:15], v[206:209], v[182:185], v[12:15]
	v_mfma_f32_16x16x32_bf16 v[8:11], v[198:201], v[190:193], v[8:11]
	v_mfma_f32_16x16x32_bf16 v[4:7], v[206:209], v[190:193], v[4:7]
	s_setprio 0
	s_add_i32 s68, 0, 0x18000
	v_add_u32_e32 v157, s68, v1
	s_barrier
	ds_read_b128 v[142:145], v157
	ds_read_b128 v[146:149], v157 offset:1024
	ds_read_b128 v[150:153], v157 offset:2048
	ds_read_b128 v[158:161], v157 offset:3072
	s_add_u32 s14, s14, 0x80000
	s_addc_u32 s15, s15, 0
	ds_read_b128 v[162:165], v156 offset:32768
	ds_read_b128 v[166:169], v156 offset:33792
	ds_read_b128 v[170:173], v156 offset:34816
	ds_read_b128 v[174:177], v156 offset:35840
	ds_read_b128 v[178:181], v156 offset:36864
	ds_read_b128 v[182:185], v156 offset:37888
	ds_read_b128 v[186:189], v156 offset:38912
	ds_read_b128 v[190:193], v156 offset:39936
	s_mov_b32 m0, s38
	s_nop 0
	global_load_lds_dwordx4 v132, s[14:15]
	s_mov_b32 m0, s39
	s_nop 0
	global_load_lds_dwordx4 v134, s[14:15]
	s_add_i32 s14, 0, 0x1c000
	v_add_u32_e32 v157, s14, v1
	ds_read_b128 v[194:197], v157
	ds_read_b128 v[198:201], v157 offset:1024
	ds_read_b128 v[202:205], v157 offset:2048
	ds_read_b128 v[206:209], v157 offset:3072
	s_waitcnt lgkmcnt(0)
	s_barrier
	s_setprio 1
	v_mfma_f32_16x16x32_bf16 v[128:131], v[142:145], v[162:165], v[128:131]
	v_mfma_f32_16x16x32_bf16 v[124:127], v[150:153], v[162:165], v[124:127]
	v_mfma_f32_16x16x32_bf16 v[120:123], v[142:145], v[170:173], v[120:123]
	v_mfma_f32_16x16x32_bf16 v[116:119], v[150:153], v[170:173], v[116:119]
	v_mfma_f32_16x16x32_bf16 v[112:115], v[142:145], v[178:181], v[112:115]
	v_mfma_f32_16x16x32_bf16 v[108:111], v[150:153], v[178:181], v[108:111]
	v_mfma_f32_16x16x32_bf16 v[104:107], v[142:145], v[186:189], v[104:107]
	v_mfma_f32_16x16x32_bf16 v[100:103], v[150:153], v[186:189], v[100:103]
	v_mfma_f32_16x16x32_bf16 v[128:131], v[146:149], v[166:169], v[128:131]
	v_mfma_f32_16x16x32_bf16 v[124:127], v[158:161], v[166:169], v[124:127]
	v_mfma_f32_16x16x32_bf16 v[120:123], v[146:149], v[174:177], v[120:123]
	v_mfma_f32_16x16x32_bf16 v[116:119], v[158:161], v[174:177], v[116:119]
	v_mfma_f32_16x16x32_bf16 v[112:115], v[146:149], v[182:185], v[112:115]
	v_mfma_f32_16x16x32_bf16 v[108:111], v[158:161], v[182:185], v[108:111]
	v_mfma_f32_16x16x32_bf16 v[104:107], v[146:149], v[190:193], v[104:107]
	v_mfma_f32_16x16x32_bf16 v[100:103], v[158:161], v[190:193], v[100:103]
	v_mfma_f32_16x16x32_bf16 v[64:67], v[194:197], v[162:165], v[64:67]
	v_mfma_f32_16x16x32_bf16 v[60:63], v[202:205], v[162:165], v[60:63]
	v_mfma_f32_16x16x32_bf16 v[56:59], v[194:197], v[170:173], v[56:59]
	v_mfma_f32_16x16x32_bf16 v[52:55], v[202:205], v[170:173], v[52:55]
	v_mfma_f32_16x16x32_bf16 v[48:51], v[194:197], v[178:181], v[48:51]
	v_mfma_f32_16x16x32_bf16 v[44:47], v[202:205], v[178:181], v[44:47]
	v_mfma_f32_16x16x32_bf16 v[40:43], v[194:197], v[186:189], v[40:43]
	v_mfma_f32_16x16x32_bf16 v[36:39], v[202:205], v[186:189], v[36:39]
	v_mfma_f32_16x16x32_bf16 v[64:67], v[198:201], v[166:169], v[64:67]
	v_mfma_f32_16x16x32_bf16 v[60:63], v[206:209], v[166:169], v[60:63]
	v_mfma_f32_16x16x32_bf16 v[56:59], v[198:201], v[174:177], v[56:59]
	v_mfma_f32_16x16x32_bf16 v[52:55], v[206:209], v[174:177], v[52:55]
	v_mfma_f32_16x16x32_bf16 v[48:51], v[198:201], v[182:185], v[48:51]
	v_mfma_f32_16x16x32_bf16 v[44:47], v[206:209], v[182:185], v[44:47]
	v_mfma_f32_16x16x32_bf16 v[40:43], v[198:201], v[190:193], v[40:43]
	v_mfma_f32_16x16x32_bf16 v[36:39], v[206:209], v[190:193], v[36:39]
	s_setprio 0
	s_barrier
; #define PG8_WAIT_V(n) asm volatile("s_waitcnt vmcnt(" #n ")" ::: "memory")
; #define PG8_WAIT_L(n) asm volatile("s_waitcnt lgkmcnt(" #n ")" ::: "memory")
; template <class Epi, class Sched>
; __device__ __forceinline__ void gemm_phase(LAS unsigned char* lds, const Gemm g, const Sched& S, const Epi& E) {
;     ...
;         for (int t = 0; t < nt; t += 2) {
;             const bool last = (t == nt - 2);
;             const char* a1 = cA + (size_t)(t + 1) * kstep;
;             const char* a2 = last ? nA : cA + (size_t)(t + 2) * kstep; const char* b2 = last ? nB : cB + (size_t)(t + 2) * kstep;
;             const char* a3 = a2 + kstep; const char* b3 = b2 + kstep;
;             if (last && has_next) S.a_ready(nxt);
;             PG8_LDB(B0, 0, 0); PG8_SCHED; PG8_LDA(At, 0, 0); PG8_STAGE(PG8_SA(1, 1), a1 + hstepA, voffA);
;             PG8_WAIT_L(8); PG8_BAR; PG8_WAIT_L(0); PG8_MMA(0, 0, At, B0); PG8_BAR; PG8_SCHED;
;             PG8_LDB(B1, 0, 1); PG8_STAGE(PG8_SB(0, 0), b2, voffB);
;             PG8_BAR; PG8_WAIT_L(0); PG8_MMA(0, 1, At, B1); PG8_BAR;
;             PG8_LDA(At, 0, 1); PG8_STAGE(PG8_SA(0, 0), a2, voffA);
;             PG8_BAR; PG8_WAIT_L(0); PG8_MMA(1, 0, At, B0); PG8_BAR; PG8_SCHED;
;             PG8_STAGE(PG8_SB(0, 1), b2 + hstepB, voffB);
;             PG8_WAIT_V(6); PG8_BAR; PG8_MMA(1, 1, At, B1); PG8_BAR;
;             PG8_LDB(B0, 1, 0); PG8_SCHED; PG8_LDA(At, 1, 0); PG8_STAGE(PG8_SA(0, 1), a2 + hstepA, voffA);
;             PG8_WAIT_L(8); PG8_BAR; PG8_WAIT_L(0); PG8_MMA(0, 0, At, B0); PG8_BAR; PG8_SCHED;
;             PG8_LDB(B1, 1, 1); PG8_STAGE(PG8_SB(1, 0), b3, voffB);
;             PG8_BAR; PG8_WAIT_L(0); PG8_MMA(0, 1, At, B1); PG8_BAR;
;             PG8_LDA(At, 1, 1); PG8_STAGE(PG8_SA(1, 0), a3, voffA);
;             PG8_BAR; PG8_WAIT_L(0); PG8_MMA(1, 0, At, B0); PG8_BAR; PG8_SCHED;
;             PG8_STAGE(PG8_SB(1, 1), b3 + hstepB, voffB);
;             PG8_WAIT_V(6); PG8_BAR; PG8_MMA(1, 1, At, B1); PG8_BAR;
;     __device__ __forceinline__ void operator()(const f32x4 (&acc)[2][2][4][2], const Unit& u, int wr, int wc, int, int) const {
;     ...
;         for (int bj = 0; bj < 2; ++bj) { f32x4 b0 = (f32x4){0.f, 0.f, 0.f, 0.f}, b1 = b0;
; #pragma unroll 8
;             for (int pp = 0; pp < 32; ++pp) { b0 += *(const f32x4*)(bias + pp * 256 + col0 + bj * HALF); b1 += *(const f32x4*)(bias + pp * 256 + col0 + bj * HALF + 4); }
	ds_read_b128 v[162:165], v156 offset:49152
	ds_read_b128 v[166:169], v156 offset:50176
	ds_read_b128 v[170:173], v156 offset:51200
	ds_read_b128 v[174:177], v156 offset:52224
	ds_read_b128 v[178:181], v156 offset:53248
	ds_read_b128 v[182:185], v156 offset:54272
	ds_read_b128 v[186:189], v156 offset:55296
	ds_read_b128 v[190:193], v156 offset:56320
	s_add_i32 s15, s68, s29
	v_lshl_add_u64 v[154:155], v[154:155], 0, s[8:9]
	s_mov_b32 m0, s15
	s_nop 0
	global_load_lds_dwordx4 v[154:155], off
	v_lshl_add_u64 v[154:155], v[210:211], 0, s[8:9]
	s_add_i32 m0, s15, 0x2000
	s_nop 0
	global_load_lds_dwordx4 v[154:155], off
	s_mov_b32 m0, s62
	v_lshl_add_u64 v[154:155], v[212:213], 0, s[8:9]
	global_load_lds_dwordx4 v[154:155], off
	v_lshl_add_u64 v[154:155], v[216:217], 0, s[8:9]
	s_mov_b32 m0, s63
	s_nop 0
	global_load_lds_dwordx4 v[154:155], off
	s_add_u32 s6, s6, 0x100080
	s_addc_u32 s7, s7, 0
	s_add_i32 s14, s14, s29
	s_mov_b32 m0, s14
	s_nop 0
	global_load_lds_dwordx4 v2, s[6:7]
	s_add_i32 m0, s14, 0x2000
	s_nop 0
	global_load_lds_dwordx4 v136, s[6:7]
	s_waitcnt lgkmcnt(0)
	s_waitcnt vmcnt(6)
	s_barrier
	s_setprio 1
	v_mfma_f32_16x16x32_bf16 v[96:99], v[142:145], v[162:165], v[96:99]
	v_mfma_f32_16x16x32_bf16 v[92:95], v[150:153], v[162:165], v[92:95]
	v_mfma_f32_16x16x32_bf16 v[88:91], v[142:145], v[170:173], v[88:91]
	v_mfma_f32_16x16x32_bf16 v[84:87], v[150:153], v[170:173], v[84:87]
	v_mfma_f32_16x16x32_bf16 v[80:83], v[142:145], v[178:181], v[80:83]
	v_mfma_f32_16x16x32_bf16 v[76:79], v[150:153], v[178:181], v[76:79]
	v_mfma_f32_16x16x32_bf16 v[72:75], v[142:145], v[186:189], v[72:75]
	v_mfma_f32_16x16x32_bf16 v[68:71], v[150:153], v[186:189], v[68:71]
	v_mfma_f32_16x16x32_bf16 v[96:99], v[146:149], v[166:169], v[96:99]
	v_mfma_f32_16x16x32_bf16 v[92:95], v[158:161], v[166:169], v[92:95]
	v_mfma_f32_16x16x32_bf16 v[88:91], v[146:149], v[174:177], v[88:91]
	v_mfma_f32_16x16x32_bf16 v[84:87], v[158:161], v[174:177], v[84:87]
	v_mfma_f32_16x16x32_bf16 v[80:83], v[146:149], v[182:185], v[80:83]
	v_mfma_f32_16x16x32_bf16 v[76:79], v[158:161], v[182:185], v[76:79]
	v_mfma_f32_16x16x32_bf16 v[72:75], v[146:149], v[190:193], v[72:75]
	v_mfma_f32_16x16x32_bf16 v[68:71], v[158:161], v[190:193], v[68:71]
	v_mfma_f32_16x16x32_bf16 v[32:35], v[194:197], v[162:165], v[32:35]
	v_mfma_f32_16x16x32_bf16 v[28:31], v[202:205], v[162:165], v[28:31]
	v_mfma_f32_16x16x32_bf16 v[24:27], v[194:197], v[170:173], v[24:27]
	v_mfma_f32_16x16x32_bf16 v[20:23], v[202:205], v[170:173], v[20:23]
	v_mfma_f32_16x16x32_bf16 v[16:19], v[194:197], v[178:181], v[16:19]
	v_mfma_f32_16x16x32_bf16 v[12:15], v[202:205], v[178:181], v[12:15]
	v_mfma_f32_16x16x32_bf16 v[8:11], v[194:197], v[186:189], v[8:11]
	v_mfma_f32_16x16x32_bf16 v[4:7], v[202:205], v[186:189], v[4:7]
	v_mfma_f32_16x16x32_bf16 v[32:35], v[198:201], v[166:169], v[32:35]
	v_mfma_f32_16x16x32_bf16 v[28:31], v[206:209], v[166:169], v[28:31]
	v_mfma_f32_16x16x32_bf16 v[24:27], v[198:201], v[174:177], v[24:27]
	v_mfma_f32_16x16x32_bf16 v[20:23], v[206:209], v[174:177], v[20:23]
	v_mfma_f32_16x16x32_bf16 v[16:19], v[198:201], v[182:185], v[16:19]
	v_mfma_f32_16x16x32_bf16 v[12:15], v[206:209], v[182:185], v[12:15]
	v_mfma_f32_16x16x32_bf16 v[8:11], v[198:201], v[190:193], v[8:11]
	v_mfma_f32_16x16x32_bf16 v[4:7], v[206:209], v[190:193], v[4:7]
	s_setprio 0
	s_add_i32 s67, s67, 2
	s_add_u32 s4, s4, 0x100
	s_addc_u32 s5, s5, 0
	s_add_u32 s65, s65, 0x100
	s_addc_u32 s66, s66, 0
	s_cmp_gt_u32 s67, 61
	s_barrier
	s_cbranch_scc0 .LBB0_491
	v_mov_b32_e32 v157, v0
	s_lshl_b32 s1, s1, 8
	v_lshrrev_b32_e32 v142, 1, v157
	v_and_or_b32 v142, v142, 24, s1
	v_or_b32_e32 v154, s61, v142
	v_ashrrev_i32_e32 v155, 31, v154
	v_mov_b32_e32 v144, 0
	v_lshl_add_u64 v[142:143], v[154:155], 2, s[46:47]
	s_mov_b64 s[4:5], 0
	v_mov_b32_e32 v145, v144
	v_mov_b32_e32 v146, v144
	v_mov_b32_e32 v147, v144
	v_mov_b32_e32 v148, v144
	v_mov_b32_e32 v149, v144
	v_mov_b32_e32 v150, v144
	v_mov_b32_e32 v151, v144

; #define PG8_STAGE(bufoff, gbase, voff) do { _Pragma("unroll") for (int _i = 0; _i < 2; ++_i) \
;         __builtin_amdgcn_global_load_lds((const unsigned*)((const char*)(gbase) + (voff)[_i]), (LAS unsigned*)(lds + (bufoff) + ldsw + _i * 8192), 16, 0, 0); } while (0)
; #define PG8_LDA(dst, b, h) do { _Pragma("unroll") for (int m = 0; m < 4; ++m) _Pragma("unroll") for (int k = 0; k < 2; ++k) dst[m][k] = *(const LAS bf16x8*)(lds + PG8_SA(b, h) + aoff + m * 2048 + k * 1024); } while (0)
; #define PG8_LDB(dst, b, h) do { _Pragma("unroll") for (int n = 0; n < 2; ++n) _Pragma("unroll") for (int k = 0; k < 2; ++k) dst[n][k] = *(const LAS bf16x8*)(lds + PG8_SB(b, h) + boff + n * 2048 + k * 1024); } while (0)
; #define PG8_MMA(ai, bj, At, Bt) do { __builtin_amdgcn_s_setprio(1); _Pragma("unroll") for (int m = 0; m < 4; ++m) _Pragma("unroll") for (int n = 0; n < 2; ++n) _Pragma("unroll") for (int k = 0; k < 2; ++k) \
;         acc[ai][bj][m][n] = __builtin_amdgcn_mfma_f32_16x16x32_bf16(Bt[n][k], At[m][k], acc[ai][bj][m][n], 0, 0, 0); __builtin_amdgcn_s_setprio(0); } while (0)
; #define PG8_WAIT_L(n) asm volatile("s_waitcnt lgkmcnt(" #n ")" ::: "memory")
; #define PG8_BAR __builtin_amdgcn_s_barrier()
; #define PG8_SCHED __builtin_amdgcn_sched_barrier(0)
; template <class Epi, class Sched>
; __device__ __forceinline__ void gemm_phase(LAS unsigned char* lds, const Gemm g, const Sched& S, const Epi& E) {
;     ...
;         for (int t = 0; t < nt; t += 2) {
;             const bool last = (t == nt - 2);
;             const char* a1 = cA + (size_t)(t + 1) * kstep;
;             const char* a2 = last ? nA : cA + (size_t)(t + 2) * kstep; const char* b2 = last ? nB : cB + (size_t)(t + 2) * kstep;
;             const char* a3 = a2 + kstep; const char* b3 = b2 + kstep;
;             if (last && has_next) S.a_ready(nxt);
;             PG8_LDB(B0, 0, 0); PG8_SCHED; PG8_LDA(At, 0, 0); PG8_STAGE(PG8_SA(1, 1), a1 + hstepA, voffA);
;             PG8_WAIT_L(8); PG8_BAR; PG8_WAIT_L(0); PG8_MMA(0, 0, At, B0); PG8_BAR; PG8_SCHED;
;             PG8_LDB(B1, 0, 1); PG8_STAGE(PG8_SB(0, 0), b2, voffB);
;             PG8_BAR; PG8_WAIT_L(0); PG8_MMA(0, 1, At, B1); PG8_BAR;
;             PG8_LDA(At, 0, 1); PG8_STAGE(PG8_SA(0, 0), a2, voffA);
;             PG8_BAR; PG8_WAIT_L(0); PG8_MMA(1, 0, At, B0); PG8_BAR; PG8_SCHED;
;             PG8_STAGE(PG8_SB(0, 1), b2 + hstepB, voffB);
.LBB0_966:
	s_add_u32 s20, s6, 0xfff80080
	s_addc_u32 s21, s7, -1
	s_add_i32 s52, 0, 0x10000
	v_add_u32_e32 v144, s52, v1
	ds_read_b128 v[132:135], v144
	ds_read_b128 v[136:139], v144 offset:1024
	ds_read_b128 v[140:143], v144 offset:2048
	ds_read_b128 v[144:147], v144 offset:3072
	s_cmp_eq_u32 s51, 28
	s_cselect_b32 s25, s15, s21
	s_cselect_b32 s24, s47, s20
	s_cselect_b32 s21, s1, s50
	s_cselect_b32 s20, s48, s49
	ds_read_b128 v[148:151], v224
	ds_read_b128 v[152:155], v224 offset:1024
	ds_read_b128 v[156:159], v224 offset:2048
	ds_read_b128 v[160:163], v224 offset:3072
	ds_read_b128 v[164:167], v224 offset:4096
	ds_read_b128 v[168:171], v224 offset:5120
	ds_read_b128 v[172:175], v224 offset:6144
	ds_read_b128 v[176:179], v224 offset:7168
	s_add_i32 s54, 0, 0x14000
	v_add_u32_e32 v202, s54, v1
	ds_read_b128 v[180:183], v202
	ds_read_b128 v[184:187], v202 offset:1024
	ds_read_b128 v[188:191], v202 offset:2048
	ds_read_b128 v[202:205], v202 offset:3072
	s_add_i32 m0, s31, 0xc000
	s_nop 0
	global_load_lds_dwordx4 v198, s[6:7]
	s_add_i32 m0, s31, 0xe000
	s_nop 0
	global_load_lds_dwordx4 v200, s[6:7]
	s_waitcnt lgkmcnt(0)
	s_barrier
	s_setprio 1
	v_mfma_f32_16x16x32_bf16 v[128:131], v[132:135], v[148:151], v[128:131]
	v_mfma_f32_16x16x32_bf16 v[124:127], v[140:143], v[148:151], v[124:127]
	v_mfma_f32_16x16x32_bf16 v[112:115], v[132:135], v[156:159], v[112:115]
	v_mfma_f32_16x16x32_bf16 v[108:111], v[140:143], v[156:159], v[108:111]
	v_mfma_f32_16x16x32_bf16 v[100:103], v[132:135], v[164:167], v[100:103]
	v_mfma_f32_16x16x32_bf16 v[92:95], v[140:143], v[164:167], v[92:95]
	v_mfma_f32_16x16x32_bf16 v[84:87], v[132:135], v[172:175], v[84:87]
	v_mfma_f32_16x16x32_bf16 v[76:79], v[140:143], v[172:175], v[76:79]
	v_mfma_f32_16x16x32_bf16 v[128:131], v[136:139], v[152:155], v[128:131]
	v_mfma_f32_16x16x32_bf16 v[124:127], v[144:147], v[152:155], v[124:127]
	v_mfma_f32_16x16x32_bf16 v[112:115], v[136:139], v[160:163], v[112:115]
	v_mfma_f32_16x16x32_bf16 v[108:111], v[144:147], v[160:163], v[108:111]
	v_mfma_f32_16x16x32_bf16 v[100:103], v[136:139], v[168:171], v[100:103]
	v_mfma_f32_16x16x32_bf16 v[92:95], v[144:147], v[168:171], v[92:95]
	v_mfma_f32_16x16x32_bf16 v[84:87], v[136:139], v[176:179], v[84:87]
	v_mfma_f32_16x16x32_bf16 v[76:79], v[144:147], v[176:179], v[76:79]
	v_mfma_f32_16x16x32_bf16 v[120:123], v[180:183], v[148:151], v[120:123]
	v_mfma_f32_16x16x32_bf16 v[116:119], v[188:191], v[148:151], v[116:119]
	v_mfma_f32_16x16x32_bf16 v[104:107], v[180:183], v[156:159], v[104:107]
	v_mfma_f32_16x16x32_bf16 v[96:99], v[188:191], v[156:159], v[96:99]
	v_mfma_f32_16x16x32_bf16 v[88:91], v[180:183], v[164:167], v[88:91]
	v_mfma_f32_16x16x32_bf16 v[80:83], v[188:191], v[164:167], v[80:83]
	v_mfma_f32_16x16x32_bf16 v[72:75], v[180:183], v[172:175], v[72:75]
	v_mfma_f32_16x16x32_bf16 v[68:71], v[188:191], v[172:175], v[68:71]
	v_mfma_f32_16x16x32_bf16 v[120:123], v[184:187], v[152:155], v[120:123]
	v_mfma_f32_16x16x32_bf16 v[116:119], v[202:205], v[152:155], v[116:119]
	v_mfma_f32_16x16x32_bf16 v[104:107], v[184:187], v[160:163], v[104:107]
	v_mfma_f32_16x16x32_bf16 v[96:99], v[202:205], v[160:163], v[96:99]
	v_mfma_f32_16x16x32_bf16 v[88:91], v[184:187], v[168:171], v[88:91]
	v_mfma_f32_16x16x32_bf16 v[80:83], v[202:205], v[168:171], v[80:83]
	v_mfma_f32_16x16x32_bf16 v[72:75], v[184:187], v[176:179], v[72:75]
	v_mfma_f32_16x16x32_bf16 v[68:71], v[202:205], v[176:179], v[68:71]
	s_setprio 0
	s_barrier
	ds_read_b128 v[148:151], v224 offset:16384
	ds_read_b128 v[152:155], v224 offset:17408
	ds_read_b128 v[156:159], v224 offset:18432
	ds_read_b128 v[160:163], v224 offset:19456
	ds_read_b128 v[164:167], v224 offset:20480
	ds_read_b128 v[168:171], v224 offset:21504
	ds_read_b128 v[172:175], v224 offset:22528
	ds_read_b128 v[176:179], v224 offset:23552
	s_add_i32 s52, s52, s30
	v_lshl_add_u64 v[206:207], s[20:21], 0, v[2:3]
	s_mov_b32 m0, s52
	s_nop 0
	global_load_lds_dwordx4 v[206:207], off
	v_lshl_add_u64 v[208:209], s[20:21], 0, v[192:193]
	s_add_i32 m0, s52, 0x2000
	s_nop 0
	global_load_lds_dwordx4 v[208:209], off
	s_mov_b32 m0, s31
	v_lshl_add_u64 v[210:211], s[24:25], 0, v[196:197]
	global_load_lds_dwordx4 v[210:211], off
	v_lshl_add_u64 v[212:213], s[24:25], 0, v[194:195]
	s_mov_b32 m0, s35
	s_nop 0
	global_load_lds_dwordx4 v[212:213], off
	s_add_u32 s52, s20, 0x80000
	s_addc_u32 s53, s21, 0
	s_add_i32 s54, s54, s30
	s_mov_b32 m0, s54
	s_nop 0
	global_load_lds_dwordx4 v2, s[52:53]
	s_add_i32 m0, s54, 0x2000
	s_nop 0
	global_load_lds_dwordx4 v192, s[52:53]
	s_waitcnt lgkmcnt(0)
	s_waitcnt vmcnt(6)
	s_barrier
; #define PG8_STAGE(bufoff, gbase, voff) do { _Pragma("unroll") for (int _i = 0; _i < 2; ++_i) \
;         __builtin_amdgcn_global_load_lds((const unsigned*)((const char*)(gbase) + (voff)[_i]), (LAS unsigned*)(lds + (bufoff) + ldsw + _i * 8192), 16, 0, 0); } while (0)
; #define PG8_LDA(dst, b, h) do { _Pragma("unroll") for (int m = 0; m < 4; ++m) _Pragma("unroll") for (int k = 0; k < 2; ++k) dst[m][k] = *(const LAS bf16x8*)(lds + PG8_SA(b, h) + aoff + m * 2048 + k * 1024); } while (0)
; #define PG8_LDB(dst, b, h) do { _Pragma("unroll") for (int n = 0; n < 2; ++n) _Pragma("unroll") for (int k = 0; k < 2; ++k) dst[n][k] = *(const LAS bf16x8*)(lds + PG8_SB(b, h) + boff + n * 2048 + k * 1024); } while (0)
; #define PG8_MMA(ai, bj, At, Bt) do { __builtin_amdgcn_s_setprio(1); _Pragma("unroll") for (int m = 0; m < 4; ++m) _Pragma("unroll") for (int n = 0; n < 2; ++n) _Pragma("unroll") for (int k = 0; k < 2; ++k) \
;         acc[ai][bj][m][n] = __builtin_amdgcn_mfma_f32_16x16x32_bf16(Bt[n][k], At[m][k], acc[ai][bj][m][n], 0, 0, 0); __builtin_amdgcn_s_setprio(0); } while (0)
; #define PG8_WAIT_V(n) asm volatile("s_waitcnt vmcnt(" #n ")" ::: "memory")
; #define PG8_WAIT_L(n) asm volatile("s_waitcnt lgkmcnt(" #n ")" ::: "memory")
; #define PG8_BAR __builtin_amdgcn_s_barrier()
; #define PG8_SCHED __builtin_amdgcn_sched_barrier(0)
; template <class Epi, class Sched>
; __device__ __forceinline__ void gemm_phase(LAS unsigned char* lds, const Gemm g, const Sched& S, const Epi& E) {
;     ...
;             PG8_WAIT_V(6); PG8_BAR; PG8_MMA(1, 1, At, B1); PG8_BAR;
;             PG8_LDB(B0, 1, 0); PG8_SCHED; PG8_LDA(At, 1, 0); PG8_STAGE(PG8_SA(0, 1), a2 + hstepA, voffA);
;             PG8_WAIT_L(8); PG8_BAR; PG8_WAIT_L(0); PG8_MMA(0, 0, At, B0); PG8_BAR; PG8_SCHED;
;             PG8_LDB(B1, 1, 1); PG8_STAGE(PG8_SB(1, 0), b3, voffB);
;             PG8_BAR; PG8_WAIT_L(0); PG8_MMA(0, 1, At, B1); PG8_BAR;
;             PG8_LDA(At, 1, 1); PG8_STAGE(PG8_SA(1, 0), a3, voffA);
;             PG8_BAR; PG8_WAIT_L(0); PG8_MMA(1, 0, At, B0); PG8_BAR; PG8_SCHED;
	s_setprio 1
	v_mfma_f32_16x16x32_bf16 v[64:67], v[132:135], v[148:151], v[64:67]
	v_mfma_f32_16x16x32_bf16 v[60:63], v[140:143], v[148:151], v[60:63]
	v_mfma_f32_16x16x32_bf16 v[52:55], v[132:135], v[156:159], v[52:55]
	v_mfma_f32_16x16x32_bf16 v[44:47], v[140:143], v[156:159], v[44:47]
	v_mfma_f32_16x16x32_bf16 v[36:39], v[132:135], v[164:167], v[36:39]
	v_mfma_f32_16x16x32_bf16 v[28:31], v[140:143], v[164:167], v[28:31]
	v_mfma_f32_16x16x32_bf16 v[20:23], v[132:135], v[172:175], v[20:23]
	v_mfma_f32_16x16x32_bf16 v[12:15], v[140:143], v[172:175], v[12:15]
	v_mfma_f32_16x16x32_bf16 v[64:67], v[136:139], v[152:155], v[64:67]
	v_mfma_f32_16x16x32_bf16 v[60:63], v[144:147], v[152:155], v[60:63]
	v_mfma_f32_16x16x32_bf16 v[52:55], v[136:139], v[160:163], v[52:55]
	v_mfma_f32_16x16x32_bf16 v[44:47], v[144:147], v[160:163], v[44:47]
	v_mfma_f32_16x16x32_bf16 v[36:39], v[136:139], v[168:171], v[36:39]
	v_mfma_f32_16x16x32_bf16 v[28:31], v[144:147], v[168:171], v[28:31]
	v_mfma_f32_16x16x32_bf16 v[20:23], v[136:139], v[176:179], v[20:23]
	v_mfma_f32_16x16x32_bf16 v[12:15], v[144:147], v[176:179], v[12:15]
	v_mfma_f32_16x16x32_bf16 v[56:59], v[180:183], v[148:151], v[56:59]
	v_mfma_f32_16x16x32_bf16 v[48:51], v[188:191], v[148:151], v[48:51]
	v_mfma_f32_16x16x32_bf16 v[40:43], v[180:183], v[156:159], v[40:43]
	v_mfma_f32_16x16x32_bf16 v[32:35], v[188:191], v[156:159], v[32:35]
	v_mfma_f32_16x16x32_bf16 v[24:27], v[180:183], v[164:167], v[24:27]
	v_mfma_f32_16x16x32_bf16 v[16:19], v[188:191], v[164:167], v[16:19]
	v_mfma_f32_16x16x32_bf16 v[8:11], v[180:183], v[172:175], v[8:11]
	v_mfma_f32_16x16x32_bf16 v[4:7], v[188:191], v[172:175], v[4:7]
	v_mfma_f32_16x16x32_bf16 v[56:59], v[184:187], v[152:155], v[56:59]
	v_mfma_f32_16x16x32_bf16 v[48:51], v[202:205], v[152:155], v[48:51]
	v_mfma_f32_16x16x32_bf16 v[40:43], v[184:187], v[160:163], v[40:43]
	v_mfma_f32_16x16x32_bf16 v[32:35], v[202:205], v[160:163], v[32:35]
	v_mfma_f32_16x16x32_bf16 v[24:27], v[184:187], v[168:171], v[24:27]
	v_mfma_f32_16x16x32_bf16 v[16:19], v[202:205], v[168:171], v[16:19]
	v_mfma_f32_16x16x32_bf16 v[8:11], v[184:187], v[176:179], v[8:11]
	v_mfma_f32_16x16x32_bf16 v[4:7], v[202:205], v[176:179], v[4:7]
	s_setprio 0
	s_add_i32 s52, 0, 0x18000
	v_add_u32_e32 v144, s52, v1
	s_barrier
	ds_read_b128 v[132:135], v144
	ds_read_b128 v[136:139], v144 offset:1024
	ds_read_b128 v[140:143], v144 offset:2048
	ds_read_b128 v[144:147], v144 offset:3072
	s_add_u32 s24, s24, 0x80000
	s_addc_u32 s25, s25, 0
	ds_read_b128 v[148:151], v224 offset:32768
	ds_read_b128 v[152:155], v224 offset:33792
	ds_read_b128 v[156:159], v224 offset:34816
	ds_read_b128 v[160:163], v224 offset:35840
	ds_read_b128 v[164:167], v224 offset:36864
	ds_read_b128 v[168:171], v224 offset:37888
	ds_read_b128 v[172:175], v224 offset:38912
	ds_read_b128 v[176:179], v224 offset:39936
	s_mov_b32 m0, s36
	s_nop 0
	global_load_lds_dwordx4 v196, s[24:25]
	s_mov_b32 m0, s37
	s_nop 0
	global_load_lds_dwordx4 v194, s[24:25]
	s_add_i32 s24, 0, 0x1c000
	v_add_u32_e32 v202, s24, v1
	ds_read_b128 v[180:183], v202
	ds_read_b128 v[184:187], v202 offset:1024
	ds_read_b128 v[188:191], v202 offset:2048
	ds_read_b128 v[202:205], v202 offset:3072
	s_waitcnt lgkmcnt(0)
	s_barrier
	s_setprio 1
	v_mfma_f32_16x16x32_bf16 v[128:131], v[132:135], v[148:151], v[128:131]
	v_mfma_f32_16x16x32_bf16 v[124:127], v[140:143], v[148:151], v[124:127]
	v_mfma_f32_16x16x32_bf16 v[112:115], v[132:135], v[156:159], v[112:115]
	v_mfma_f32_16x16x32_bf16 v[108:111], v[140:143], v[156:159], v[108:111]
	v_mfma_f32_16x16x32_bf16 v[100:103], v[132:135], v[164:167], v[100:103]
	v_mfma_f32_16x16x32_bf16 v[92:95], v[140:143], v[164:167], v[92:95]
	v_mfma_f32_16x16x32_bf16 v[84:87], v[132:135], v[172:175], v[84:87]
	v_mfma_f32_16x16x32_bf16 v[76:79], v[140:143], v[172:175], v[76:79]
	v_mfma_f32_16x16x32_bf16 v[128:131], v[136:139], v[152:155], v[128:131]
	v_mfma_f32_16x16x32_bf16 v[124:127], v[144:147], v[152:155], v[124:127]
	v_mfma_f32_16x16x32_bf16 v[112:115], v[136:139], v[160:163], v[112:115]
	v_mfma_f32_16x16x32_bf16 v[108:111], v[144:147], v[160:163], v[108:111]
	v_mfma_f32_16x16x32_bf16 v[100:103], v[136:139], v[168:171], v[100:103]
	v_mfma_f32_16x16x32_bf16 v[92:95], v[144:147], v[168:171], v[92:95]
	v_mfma_f32_16x16x32_bf16 v[84:87], v[136:139], v[176:179], v[84:87]
	v_mfma_f32_16x16x32_bf16 v[76:79], v[144:147], v[176:179], v[76:79]
	v_mfma_f32_16x16x32_bf16 v[120:123], v[180:183], v[148:151], v[120:123]
	v_mfma_f32_16x16x32_bf16 v[116:119], v[188:191], v[148:151], v[116:119]
	v_mfma_f32_16x16x32_bf16 v[104:107], v[180:183], v[156:159], v[104:107]
	v_mfma_f32_16x16x32_bf16 v[96:99], v[188:191], v[156:159], v[96:99]
	v_mfma_f32_16x16x32_bf16 v[88:91], v[180:183], v[164:167], v[88:91]
	v_mfma_f32_16x16x32_bf16 v[80:83], v[188:191], v[164:167], v[80:83]
	v_mfma_f32_16x16x32_bf16 v[72:75], v[180:183], v[172:175], v[72:75]
	v_mfma_f32_16x16x32_bf16 v[68:71], v[188:191], v[172:175], v[68:71]
	v_mfma_f32_16x16x32_bf16 v[120:123], v[184:187], v[152:155], v[120:123]
	v_mfma_f32_16x16x32_bf16 v[116:119], v[202:205], v[152:155], v[116:119]
	v_mfma_f32_16x16x32_bf16 v[104:107], v[184:187], v[160:163], v[104:107]
	v_mfma_f32_16x16x32_bf16 v[96:99], v[202:205], v[160:163], v[96:99]
	v_mfma_f32_16x16x32_bf16 v[88:91], v[184:187], v[168:171], v[88:91]
	v_mfma_f32_16x16x32_bf16 v[80:83], v[202:205], v[168:171], v[80:83]
	v_mfma_f32_16x16x32_bf16 v[72:75], v[184:187], v[176:179], v[72:75]
	v_mfma_f32_16x16x32_bf16 v[68:71], v[202:205], v[176:179], v[68:71]
	s_setprio 0
	s_barrier
; #define PG8_STAGE(bufoff, gbase, voff) do { _Pragma("unroll") for (int _i = 0; _i < 2; ++_i) \
;         __builtin_amdgcn_global_load_lds((const unsigned*)((const char*)(gbase) + (voff)[_i]), (LAS unsigned*)(lds + (bufoff) + ldsw + _i * 8192), 16, 0, 0); } while (0)
; #define PG8_LDA(dst, b, h) do { _Pragma("unroll") for (int m = 0; m < 4; ++m) _Pragma("unroll") for (int k = 0; k < 2; ++k) dst[m][k] = *(const LAS bf16x8*)(lds + PG8_SA(b, h) + aoff + m * 2048 + k * 1024); } while (0)
; #define PG8_MMA(ai, bj, At, Bt) do { __builtin_amdgcn_s_setprio(1); _Pragma("unroll") for (int m = 0; m < 4; ++m) _Pragma("unroll") for (int n = 0; n < 2; ++n) _Pragma("unroll") for (int k = 0; k < 2; ++k) \
;         acc[ai][bj][m][n] = __builtin_amdgcn_mfma_f32_16x16x32_bf16(Bt[n][k], At[m][k], acc[ai][bj][m][n], 0, 0, 0); __builtin_amdgcn_s_setprio(0); } while (0)
; #define PG8_WAIT_V(n) asm volatile("s_waitcnt vmcnt(" #n ")" ::: "memory")
; #define PG8_WAIT_L(n) asm volatile("s_waitcnt lgkmcnt(" #n ")" ::: "memory")
; #define PG8_BAR __builtin_amdgcn_s_barrier()
; #define PG8_SCHED __builtin_amdgcn_sched_barrier(0)
;     __device__ __forceinline__ void operator()(const f32x4 (&acc)[2][2][4][2], const Unit& u, int wr, int wc, int, int) const {
;     ...
;                 for (int bj = 0; bj < 2; ++bj) cin[ai][m][bj] = *(const u32x4*)(C + (size_t)(row0 + ai * HALF + m * 16) * ldc + col0 + bj * HALF);
; template <class Epi, class Sched>
; __device__ __forceinline__ void gemm_phase(LAS unsigned char* lds, const Gemm g, const Sched& S, const Epi& E) {
;     ...
;             PG8_LDA(At, 1, 1); PG8_STAGE(PG8_SA(1, 0), a3, voffA);
;             PG8_BAR; PG8_WAIT_L(0); PG8_MMA(1, 0, At, B0); PG8_BAR; PG8_SCHED;
;             PG8_STAGE(PG8_SB(1, 1), b3 + hstepB, voffB);
;             PG8_WAIT_V(6); PG8_BAR; PG8_MMA(1, 1, At, B1); PG8_BAR;
;         }
;         E(acc, cur, wr, wc, ui, fq);
;         S.done(cur);
;         if (!has_next) break;
	ds_read_b128 v[148:151], v224 offset:49152
	ds_read_b128 v[152:155], v224 offset:50176
	ds_read_b128 v[156:159], v224 offset:51200
	ds_read_b128 v[160:163], v224 offset:52224
	ds_read_b128 v[164:167], v224 offset:53248
	ds_read_b128 v[168:171], v224 offset:54272
	ds_read_b128 v[172:175], v224 offset:55296
	ds_read_b128 v[176:179], v224 offset:56320
	s_add_i32 s25, s52, s30
	v_lshl_add_u64 v[206:207], v[206:207], 0, s[8:9]
	s_mov_b32 m0, s25
	s_nop 0
	global_load_lds_dwordx4 v[206:207], off
	v_lshl_add_u64 v[206:207], v[208:209], 0, s[8:9]
	s_add_i32 m0, s25, 0x2000
	s_nop 0
	global_load_lds_dwordx4 v[206:207], off
	s_mov_b32 m0, s40
	v_lshl_add_u64 v[206:207], v[210:211], 0, s[8:9]
	global_load_lds_dwordx4 v[206:207], off
	v_lshl_add_u64 v[206:207], v[212:213], 0, s[8:9]
	s_mov_b32 m0, s41
	s_nop 0
	global_load_lds_dwordx4 v[206:207], off
	s_add_u32 s20, s20, 0x80080
	s_addc_u32 s21, s21, 0
	s_add_i32 s24, s24, s30
	s_mov_b32 m0, s24
	s_nop 0
	global_load_lds_dwordx4 v2, s[20:21]
	s_add_i32 m0, s24, 0x2000
	s_nop 0
	global_load_lds_dwordx4 v192, s[20:21]
	s_waitcnt lgkmcnt(0)
	s_waitcnt vmcnt(6)
	s_barrier
	s_setprio 1
	v_mfma_f32_16x16x32_bf16 v[64:67], v[132:135], v[148:151], v[64:67]
	v_mfma_f32_16x16x32_bf16 v[60:63], v[140:143], v[148:151], v[60:63]
	v_mfma_f32_16x16x32_bf16 v[52:55], v[132:135], v[156:159], v[52:55]
	v_mfma_f32_16x16x32_bf16 v[44:47], v[140:143], v[156:159], v[44:47]
	v_mfma_f32_16x16x32_bf16 v[36:39], v[132:135], v[164:167], v[36:39]
	v_mfma_f32_16x16x32_bf16 v[28:31], v[140:143], v[164:167], v[28:31]
	v_mfma_f32_16x16x32_bf16 v[20:23], v[132:135], v[172:175], v[20:23]
	v_mfma_f32_16x16x32_bf16 v[12:15], v[140:143], v[172:175], v[12:15]
	v_mfma_f32_16x16x32_bf16 v[64:67], v[136:139], v[152:155], v[64:67]
	v_mfma_f32_16x16x32_bf16 v[60:63], v[144:147], v[152:155], v[60:63]
	v_mfma_f32_16x16x32_bf16 v[52:55], v[136:139], v[160:163], v[52:55]
	v_mfma_f32_16x16x32_bf16 v[44:47], v[144:147], v[160:163], v[44:47]
	v_mfma_f32_16x16x32_bf16 v[36:39], v[136:139], v[168:171], v[36:39]
	v_mfma_f32_16x16x32_bf16 v[28:31], v[144:147], v[168:171], v[28:31]
	v_mfma_f32_16x16x32_bf16 v[20:23], v[136:139], v[176:179], v[20:23]
	v_mfma_f32_16x16x32_bf16 v[12:15], v[144:147], v[176:179], v[12:15]
	v_mfma_f32_16x16x32_bf16 v[56:59], v[180:183], v[148:151], v[56:59]
	v_mfma_f32_16x16x32_bf16 v[48:51], v[188:191], v[148:151], v[48:51]
	v_mfma_f32_16x16x32_bf16 v[40:43], v[180:183], v[156:159], v[40:43]
	v_mfma_f32_16x16x32_bf16 v[32:35], v[188:191], v[156:159], v[32:35]
	v_mfma_f32_16x16x32_bf16 v[24:27], v[180:183], v[164:167], v[24:27]
	v_mfma_f32_16x16x32_bf16 v[16:19], v[188:191], v[164:167], v[16:19]
	v_mfma_f32_16x16x32_bf16 v[8:11], v[180:183], v[172:175], v[8:11]
	v_mfma_f32_16x16x32_bf16 v[4:7], v[188:191], v[172:175], v[4:7]
	v_mfma_f32_16x16x32_bf16 v[56:59], v[184:187], v[152:155], v[56:59]
	v_mfma_f32_16x16x32_bf16 v[48:51], v[202:205], v[152:155], v[48:51]
	v_mfma_f32_16x16x32_bf16 v[40:43], v[184:187], v[160:163], v[40:43]
	v_mfma_f32_16x16x32_bf16 v[32:35], v[202:205], v[160:163], v[32:35]
	v_mfma_f32_16x16x32_bf16 v[24:27], v[184:187], v[168:171], v[24:27]
	v_mfma_f32_16x16x32_bf16 v[16:19], v[202:205], v[168:171], v[16:19]
	v_mfma_f32_16x16x32_bf16 v[8:11], v[184:187], v[176:179], v[8:11]
	v_mfma_f32_16x16x32_bf16 v[4:7], v[202:205], v[176:179], v[4:7]
	s_setprio 0
	s_add_i32 s51, s51, 2
	s_add_u32 s6, s6, 0x100
	s_addc_u32 s7, s7, 0
	s_add_u32 s49, s49, 0x100
	s_addc_u32 s50, s50, 0
	s_cmp_gt_u32 s51, 29
	s_barrier
	s_cbranch_scc0 .LBB0_966
	v_mov_b32_e32 v133, v0
	s_lshl_b32 s1, s46, 8
	s_add_i32 s1, s1, s38
	v_and_or_b32 v132, v133, 15, s1
	s_lshl_b32 s1, s45, 8
	v_lshrrev_b32_e32 v133, 1, v133
	v_and_or_b32 v133, v133, 24, s1
	v_or_b32_e32 v134, s39, v133
	v_ashrrev_i32_e32 v135, 31, v134
	v_lshlrev_b64 v[202:203], 1, v[134:135]
	v_ashrrev_i32_e32 v133, 31, v132
	v_lshl_add_u64 v[134:135], s[88:89], 0, v[202:203]
	v_lshlrev_b64 v[226:227], 12, v[132:133]
	v_lshl_add_u64 v[136:137], v[134:135], 0, v[226:227]
	global_load_dwordx4 v[216:219], v[136:137], off
	global_load_dwordx4 v[188:191], v[136:137], off offset:256
	v_or_b32_e32 v136, 16, v132
	v_ashrrev_i32_e32 v137, 31, v136
	v_lshlrev_b64 v[222:223], 12, v[136:137]
	v_lshl_add_u64 v[136:137], v[134:135], 0, v[222:223]
	global_load_dwordx4 v[184:187], v[136:137], off
	global_load_dwordx4 v[180:183], v[136:137], off offset:256
	v_or_b32_e32 v136, 32, v132
	v_ashrrev_i32_e32 v137, 31, v136
	v_lshlrev_b64 v[220:221], 12, v[136:137]
	v_lshl_add_u64 v[136:137], v[134:135], 0, v[220:221]
	global_load_dwordx4 v[176:179], v[136:137], off
	global_load_dwordx4 v[168:171], v[136:137], off offset:256
	v_or_b32_e32 v132, 48, v132
	v_ashrrev_i32_e32 v133, 31, v132
	v_lshlrev_b64 v[212:213], 12, v[132:133]
	v_lshl_add_u64 v[132:133], v[134:135], 0, v[212:213]
	global_load_dwordx4 v[172:175], v[132:133], off
	global_load_dwordx4 v[164:167], v[132:133], off offset:256
	s_mov_b64 s[6:7], 0x80000
	v_lshl_add_u64 v[210:211], v[226:227], 0, s[6:7]
	v_lshl_add_u64 v[132:133], v[134:135], 0, v[210:211]
	global_load_dwordx4 v[160:163], v[132:133], off
	global_load_dwordx4 v[156:159], v[132:133], off offset:256
	s_mov_b64 s[6:7], 0x90000
	v_lshl_add_u64 v[208:209], v[226:227], 0, s[6:7]
	v_lshl_add_u64 v[132:133], v[134:135], 0, v[208:209]
	global_load_dwordx4 v[152:155], v[132:133], off
	global_load_dwordx4 v[148:151], v[132:133], off offset:256
	s_mov_b64 s[6:7], 0xa0000
	v_lshl_add_u64 v[206:207], v[226:227], 0, s[6:7]
	v_lshl_add_u64 v[132:133], v[134:135], 0, v[206:207]
	global_load_dwordx4 v[144:147], v[132:133], off
	global_load_dwordx4 v[140:143], v[132:133], off offset:256
	s_mov_b64 s[6:7], 0xb0000
	v_lshl_add_u64 v[204:205], v[226:227], 0, s[6:7]
	v_lshl_add_u64 v[132:133], v[134:135], 0, v[204:205]
	global_load_dwordx4 v[136:139], v[132:133], off
	s_nop 0
	global_load_dwordx4 v[132:135], v[132:133], off offset:256
	s_and_b64 vcc, exec, s[42:43]
	s_mov_b32 s45, s0
	s_mov_b32 s46, s14
	s_mov_b64 s[20:21], s[18:19]
	s_mov_b64 s[6:7], s[4:5]
	s_waitcnt vmcnt(0)
; __device__ __forceinline__ unsigned cvt_pk_bf16(float lo, float hi) { const f32x2 v = {lo, hi}; const bf16v2_ r = __builtin_convertvector(v, bf16v2_); return __builtin_bit_cast(unsigned, r); }
; __device__ __forceinline__ float bflo(unsigned w) { return __uint_as_float(w << 16); }
; __device__ __forceinline__ float bfhi(unsigned w) { return __uint_as_float(w & 0xffff0000u); }
;     __device__ __forceinline__ void operator()(const f32x4 (&acc)[2][2][4][2], const Unit& u, int wr, int wc, int, int) const {
;     ...
;                 for (int bj = 0; bj < 2; ++bj) { const u32x4 c = cin[ai][m][bj]; const f32x4 v0 = acc[ai][bj][m][0], v1 = acc[ai][bj][m][1];
;                     u32x4 w; w.x = cvt_pk_bf16(bflo(c.x) + v0[0], bfhi(c.x) + v0[1]); w.y = cvt_pk_bf16(bflo(c.y) + v0[2], bfhi(c.y) + v0[3]);
;                     w.z = cvt_pk_bf16(bflo(c.z) + v1[0], bfhi(c.z) + v1[1]); w.w = cvt_pk_bf16(bflo(c.w) + v1[2], bfhi(c.w) + v1[3]);
;                     *(u32x4*)(C + (size_t)(row0 + ai * HALF + m * 16) * ldc + col0 + bj * HALF) = w; }
	v_lshlrev_b32_e32 v228, 16, v216
	v_and_b32_e32 v229, 0xffff0000, v216
	v_lshlrev_b32_e32 v216, 16, v217
	v_and_b32_e32 v217, 0xffff0000, v217
	v_pk_add_f32 v[128:129], v[128:129], v[228:229]
	v_pk_add_f32 v[130:131], v[130:131], v[216:217]
	v_cvt_pk_bf16_f32 v128, v128, v129
	v_cvt_pk_bf16_f32 v129, v130, v131
	v_lshlrev_b32_e32 v130, 16, v218
	v_and_b32_e32 v131, 0xffff0000, v218
	v_pk_add_f32 v[124:125], v[124:125], v[130:131]
	s_nop 0
	v_cvt_pk_bf16_f32 v130, v124, v125
	v_lshlrev_b32_e32 v124, 16, v219
	v_and_b32_e32 v125, 0xffff0000, v219
	v_pk_add_f32 v[124:125], v[126:127], v[124:125]
	v_lshlrev_b32_e32 v126, 16, v188
	v_and_b32_e32 v127, 0xffff0000, v188
	v_pk_add_f32 v[120:121], v[120:121], v[126:127]
	v_lshlrev_b32_e32 v126, 16, v189
	v_and_b32_e32 v127, 0xffff0000, v189
	v_pk_add_f32 v[122:123], v[122:123], v[126:127]
	v_cvt_pk_bf16_f32 v120, v120, v121
	v_cvt_pk_bf16_f32 v121, v122, v123
	v_lshlrev_b32_e32 v122, 16, v190
	v_and_b32_e32 v123, 0xffff0000, v190
	v_pk_add_f32 v[116:117], v[116:117], v[122:123]
	v_cvt_pk_bf16_f32 v131, v124, v125
	v_cvt_pk_bf16_f32 v122, v116, v117
	v_lshlrev_b32_e32 v116, 16, v191
	v_and_b32_e32 v117, 0xffff0000, v191
	v_pk_add_f32 v[116:117], v[118:119], v[116:117]
	v_lshl_add_u64 v[124:125], s[88:89], 0, v[226:227]
	v_cvt_pk_bf16_f32 v123, v116, v117
	v_lshlrev_b32_e32 v116, 16, v184
	v_and_b32_e32 v117, 0xffff0000, v184
	v_pk_add_f32 v[112:113], v[112:113], v[116:117]
	v_lshlrev_b32_e32 v116, 16, v185
	v_and_b32_e32 v117, 0xffff0000, v185
	v_pk_add_f32 v[114:115], v[114:115], v[116:117]
	v_cvt_pk_bf16_f32 v112, v112, v113
	v_cvt_pk_bf16_f32 v113, v114, v115
	v_lshlrev_b32_e32 v114, 16, v186
	v_and_b32_e32 v115, 0xffff0000, v186
	v_pk_add_f32 v[108:109], v[108:109], v[114:115]
	v_lshl_add_u64 v[124:125], v[124:125], 0, v[202:203]
	v_cvt_pk_bf16_f32 v114, v108, v109
	v_lshlrev_b32_e32 v108, 16, v187
	v_and_b32_e32 v109, 0xffff0000, v187
	v_pk_add_f32 v[108:109], v[110:111], v[108:109]
	v_lshlrev_b32_e32 v110, 16, v180
	v_and_b32_e32 v111, 0xffff0000, v180
	v_pk_add_f32 v[104:105], v[104:105], v[110:111]
	v_lshlrev_b32_e32 v110, 16, v181
	v_and_b32_e32 v111, 0xffff0000, v181
	v_pk_add_f32 v[106:107], v[106:107], v[110:111]
	v_cvt_pk_bf16_f32 v104, v104, v105
	v_cvt_pk_bf16_f32 v105, v106, v107
	v_lshlrev_b32_e32 v106, 16, v182
	v_and_b32_e32 v107, 0xffff0000, v182
	v_pk_add_f32 v[96:97], v[96:97], v[106:107]
	v_cvt_pk_bf16_f32 v115, v108, v109
	v_cvt_pk_bf16_f32 v106, v96, v97
	v_lshlrev_b32_e32 v96, 16, v183
	v_and_b32_e32 v97, 0xffff0000, v183
	v_pk_add_f32 v[96:97], v[98:99], v[96:97]
	v_lshlrev_b32_e32 v98, 16, v177
	v_cvt_pk_bf16_f32 v107, v96, v97
	v_lshlrev_b32_e32 v96, 16, v176
	v_and_b32_e32 v97, 0xffff0000, v176
	v_and_b32_e32 v99, 0xffff0000, v177
	v_pk_add_f32 v[96:97], v[100:101], v[96:97]
	v_pk_add_f32 v[98:99], v[102:103], v[98:99]
	v_cvt_pk_bf16_f32 v96, v96, v97
	v_cvt_pk_bf16_f32 v97, v98, v99
	v_lshlrev_b32_e32 v98, 16, v178
	v_and_b32_e32 v99, 0xffff0000, v178
	v_pk_add_f32 v[92:93], v[92:93], v[98:99]
	v_lshl_add_u64 v[108:109], s[88:89], 0, v[222:223]
	v_cvt_pk_bf16_f32 v98, v92, v93
	v_lshlrev_b32_e32 v92, 16, v179
	v_and_b32_e32 v93, 0xffff0000, v179
	v_pk_add_f32 v[92:93], v[94:95], v[92:93]
	v_lshlrev_b32_e32 v94, 16, v168
	v_and_b32_e32 v95, 0xffff0000, v168
	v_pk_add_f32 v[88:89], v[88:89], v[94:95]
	v_lshlrev_b32_e32 v94, 16, v169
	v_and_b32_e32 v95, 0xffff0000, v169
	v_pk_add_f32 v[90:91], v[90:91], v[94:95]
	v_cvt_pk_bf16_f32 v88, v88, v89
	v_cvt_pk_bf16_f32 v89, v90, v91
	v_lshlrev_b32_e32 v90, 16, v170
	v_and_b32_e32 v91, 0xffff0000, v170
	v_pk_add_f32 v[80:81], v[80:81], v[90:91]
	v_cvt_pk_bf16_f32 v99, v92, v93
	v_cvt_pk_bf16_f32 v90, v80, v81
	v_lshlrev_b32_e32 v80, 16, v171
	v_and_b32_e32 v81, 0xffff0000, v171
	v_pk_add_f32 v[80:81], v[82:83], v[80:81]
	v_lshlrev_b32_e32 v82, 16, v173
	v_cvt_pk_bf16_f32 v91, v80, v81
	v_lshlrev_b32_e32 v80, 16, v172
	v_and_b32_e32 v81, 0xffff0000, v172
	v_and_b32_e32 v83, 0xffff0000, v173
	v_pk_add_f32 v[80:81], v[84:85], v[80:81]
	v_pk_add_f32 v[82:83], v[86:87], v[82:83]
	v_cvt_pk_bf16_f32 v80, v80, v81
	v_cvt_pk_bf16_f32 v81, v82, v83
	v_lshlrev_b32_e32 v82, 16, v174
	v_and_b32_e32 v83, 0xffff0000, v174
	v_pk_add_f32 v[76:77], v[76:77], v[82:83]
	v_lshl_add_u64 v[92:93], s[88:89], 0, v[220:221]
	v_cvt_pk_bf16_f32 v82, v76, v77
	v_lshlrev_b32_e32 v76, 16, v175
	v_and_b32_e32 v77, 0xffff0000, v175
	v_pk_add_f32 v[76:77], v[78:79], v[76:77]
	v_lshlrev_b32_e32 v78, 16, v164
	v_and_b32_e32 v79, 0xffff0000, v164
	v_pk_add_f32 v[72:73], v[72:73], v[78:79]
	v_lshlrev_b32_e32 v78, 16, v165
	v_and_b32_e32 v79, 0xffff0000, v165
	v_pk_add_f32 v[74:75], v[74:75], v[78:79]
	v_cvt_pk_bf16_f32 v72, v72, v73
	v_cvt_pk_bf16_f32 v73, v74, v75
	v_lshlrev_b32_e32 v74, 16, v166
	v_and_b32_e32 v75, 0xffff0000, v166
	v_pk_add_f32 v[68:69], v[68:69], v[74:75]
	v_cvt_pk_bf16_f32 v83, v76, v77
	v_cvt_pk_bf16_f32 v74, v68, v69
	v_lshlrev_b32_e32 v68, 16, v167
	v_and_b32_e32 v69, 0xffff0000, v167
	v_pk_add_f32 v[68:69], v[70:71], v[68:69]
	v_lshl_add_u64 v[76:77], s[88:89], 0, v[212:213]
	v_cvt_pk_bf16_f32 v75, v68, v69
	v_lshlrev_b32_e32 v68, 16, v160
	v_and_b32_e32 v69, 0xffff0000, v160
	v_pk_add_f32 v[64:65], v[64:65], v[68:69]
	v_lshlrev_b32_e32 v68, 16, v161
	v_and_b32_e32 v69, 0xffff0000, v161
	v_pk_add_f32 v[66:67], v[66:67], v[68:69]
	v_cvt_pk_bf16_f32 v64, v64, v65
	v_cvt_pk_bf16_f32 v65, v66, v67
	v_lshlrev_b32_e32 v66, 16, v162
	v_and_b32_e32 v67, 0xffff0000, v162
	v_pk_add_f32 v[60:61], v[60:61], v[66:67]
	v_lshl_add_u64 v[108:109], v[108:109], 0, v[202:203]
	v_cvt_pk_bf16_f32 v66, v60, v61
	v_lshlrev_b32_e32 v60, 16, v163
; __device__ __forceinline__ unsigned cvt_pk_bf16(float lo, float hi) { const f32x2 v = {lo, hi}; const bf16v2_ r = __builtin_convertvector(v, bf16v2_); return __builtin_bit_cast(unsigned, r); }
; __device__ __forceinline__ float bflo(unsigned w) { return __uint_as_float(w << 16); }
; __device__ __forceinline__ float bfhi(unsigned w) { return __uint_as_float(w & 0xffff0000u); }
; #define PG8_WAIT_V(n) asm volatile("s_waitcnt vmcnt(" #n ")" ::: "memory")
; #define PG8_BAR __builtin_amdgcn_s_barrier()
;     __device__ __forceinline__ void operator()(const f32x4 (&acc)[2][2][4][2], const Unit& u, int wr, int wc, int, int) const {
;     ...
;                 for (int bj = 0; bj < 2; ++bj) { const u32x4 c = cin[ai][m][bj]; const f32x4 v0 = acc[ai][bj][m][0], v1 = acc[ai][bj][m][1];
;                     u32x4 w; w.x = cvt_pk_bf16(bflo(c.x) + v0[0], bfhi(c.x) + v0[1]); w.y = cvt_pk_bf16(bflo(c.y) + v0[2], bfhi(c.y) + v0[3]);
;                     w.z = cvt_pk_bf16(bflo(c.z) + v1[0], bfhi(c.z) + v1[1]); w.w = cvt_pk_bf16(bflo(c.w) + v1[2], bfhi(c.w) + v1[3]);
;                     *(u32x4*)(C + (size_t)(row0 + ai * HALF + m * 16) * ldc + col0 + bj * HALF) = w; }
; template <class Epi, class Sched>
; __device__ __forceinline__ void gemm_phase(LAS unsigned char* lds, const Gemm g, const Sched& S, const Epi& E) {
;     ...
;         S.done(cur);
;         if (!has_next) break;
; #pragma unroll
;         for (int a = 0; a < 2; ++a)
; #pragma unroll
;             for (int b = 0; b < 2; ++b)
; #pragma unroll
;                 for (int m = 0; m < 4; ++m)
; #pragma unroll
;                     for (int n = 0; n < 2; ++n) acc[a][b][m][n] = (f32x4){0.f, 0.f, 0.f, 0.f};
;         cur = nxt; cA = nA; cB = nB; ++ui;
;     }
;     PG8_WAIT_V(0);
;     if (wr == 0) PG8_BAR;
;     PG8_BAR;
	v_and_b32_e32 v61, 0xffff0000, v163
	v_pk_add_f32 v[60:61], v[62:63], v[60:61]
	v_lshlrev_b32_e32 v62, 16, v156
	v_and_b32_e32 v63, 0xffff0000, v156
	v_pk_add_f32 v[56:57], v[56:57], v[62:63]
	v_lshlrev_b32_e32 v62, 16, v157
	v_and_b32_e32 v63, 0xffff0000, v157
	v_pk_add_f32 v[58:59], v[58:59], v[62:63]
	v_cvt_pk_bf16_f32 v56, v56, v57
	v_cvt_pk_bf16_f32 v57, v58, v59
	v_lshlrev_b32_e32 v58, 16, v158
	v_and_b32_e32 v59, 0xffff0000, v158
	v_pk_add_f32 v[48:49], v[48:49], v[58:59]
	v_cvt_pk_bf16_f32 v67, v60, v61
	v_cvt_pk_bf16_f32 v58, v48, v49
	v_lshlrev_b32_e32 v48, 16, v159
	v_and_b32_e32 v49, 0xffff0000, v159
	v_pk_add_f32 v[48:49], v[50:51], v[48:49]
	v_lshlrev_b32_e32 v50, 16, v153
	v_cvt_pk_bf16_f32 v59, v48, v49
	v_lshlrev_b32_e32 v48, 16, v152
	v_and_b32_e32 v49, 0xffff0000, v152
	v_and_b32_e32 v51, 0xffff0000, v153
	v_pk_add_f32 v[48:49], v[52:53], v[48:49]
	v_pk_add_f32 v[50:51], v[54:55], v[50:51]
	v_cvt_pk_bf16_f32 v48, v48, v49
	v_cvt_pk_bf16_f32 v49, v50, v51
	v_lshlrev_b32_e32 v50, 16, v154
	v_and_b32_e32 v51, 0xffff0000, v154
	v_pk_add_f32 v[44:45], v[44:45], v[50:51]
	v_lshl_add_u64 v[60:61], s[88:89], 0, v[210:211]
	v_cvt_pk_bf16_f32 v50, v44, v45
	v_lshlrev_b32_e32 v44, 16, v155
	v_and_b32_e32 v45, 0xffff0000, v155
	v_pk_add_f32 v[44:45], v[46:47], v[44:45]
	v_lshlrev_b32_e32 v46, 16, v148
	v_and_b32_e32 v47, 0xffff0000, v148
	v_pk_add_f32 v[40:41], v[40:41], v[46:47]
	v_lshlrev_b32_e32 v46, 16, v149
	v_and_b32_e32 v47, 0xffff0000, v149
	v_pk_add_f32 v[42:43], v[42:43], v[46:47]
	v_cvt_pk_bf16_f32 v40, v40, v41
	v_cvt_pk_bf16_f32 v41, v42, v43
	v_lshlrev_b32_e32 v42, 16, v150
	v_and_b32_e32 v43, 0xffff0000, v150
	v_pk_add_f32 v[32:33], v[32:33], v[42:43]
	v_cvt_pk_bf16_f32 v51, v44, v45
	v_cvt_pk_bf16_f32 v42, v32, v33
	v_lshlrev_b32_e32 v32, 16, v151
	v_and_b32_e32 v33, 0xffff0000, v151
	v_pk_add_f32 v[32:33], v[34:35], v[32:33]
	v_lshlrev_b32_e32 v34, 16, v145
	v_cvt_pk_bf16_f32 v43, v32, v33
	v_lshlrev_b32_e32 v32, 16, v144
	v_and_b32_e32 v33, 0xffff0000, v144
	v_and_b32_e32 v35, 0xffff0000, v145
	v_pk_add_f32 v[32:33], v[36:37], v[32:33]
	v_pk_add_f32 v[34:35], v[38:39], v[34:35]
	v_cvt_pk_bf16_f32 v32, v32, v33
	v_cvt_pk_bf16_f32 v33, v34, v35
	v_lshlrev_b32_e32 v34, 16, v146
	v_and_b32_e32 v35, 0xffff0000, v146
	v_pk_add_f32 v[28:29], v[28:29], v[34:35]
	v_lshl_add_u64 v[44:45], s[88:89], 0, v[208:209]
	v_cvt_pk_bf16_f32 v34, v28, v29
	v_lshlrev_b32_e32 v28, 16, v147
	v_and_b32_e32 v29, 0xffff0000, v147
	v_pk_add_f32 v[28:29], v[30:31], v[28:29]
	v_lshlrev_b32_e32 v30, 16, v140
	v_and_b32_e32 v31, 0xffff0000, v140
	v_pk_add_f32 v[24:25], v[24:25], v[30:31]
	v_lshlrev_b32_e32 v30, 16, v141
	v_and_b32_e32 v31, 0xffff0000, v141
	v_pk_add_f32 v[26:27], v[26:27], v[30:31]
	v_cvt_pk_bf16_f32 v24, v24, v25
	v_cvt_pk_bf16_f32 v25, v26, v27
	v_lshlrev_b32_e32 v26, 16, v142
	v_and_b32_e32 v27, 0xffff0000, v142
	v_pk_add_f32 v[16:17], v[16:17], v[26:27]
	v_cvt_pk_bf16_f32 v35, v28, v29
	v_cvt_pk_bf16_f32 v26, v16, v17
	v_lshlrev_b32_e32 v16, 16, v143
	v_and_b32_e32 v17, 0xffff0000, v143
	v_pk_add_f32 v[16:17], v[18:19], v[16:17]
	v_lshlrev_b32_e32 v18, 16, v137
	v_cvt_pk_bf16_f32 v27, v16, v17
	v_lshlrev_b32_e32 v16, 16, v136
	v_and_b32_e32 v17, 0xffff0000, v136
	v_and_b32_e32 v19, 0xffff0000, v137
	v_pk_add_f32 v[16:17], v[20:21], v[16:17]
	v_pk_add_f32 v[18:19], v[22:23], v[18:19]
	v_cvt_pk_bf16_f32 v16, v16, v17
	v_cvt_pk_bf16_f32 v17, v18, v19
	v_lshlrev_b32_e32 v18, 16, v138
	v_and_b32_e32 v19, 0xffff0000, v138
	v_pk_add_f32 v[12:13], v[12:13], v[18:19]
	v_lshl_add_u64 v[28:29], s[88:89], 0, v[206:207]
	v_cvt_pk_bf16_f32 v18, v12, v13
	v_lshlrev_b32_e32 v12, 16, v139
	v_and_b32_e32 v13, 0xffff0000, v139
	v_pk_add_f32 v[12:13], v[14:15], v[12:13]
	v_lshlrev_b32_e32 v14, 16, v132
	v_and_b32_e32 v15, 0xffff0000, v132
	v_pk_add_f32 v[8:9], v[8:9], v[14:15]
	v_lshlrev_b32_e32 v14, 16, v133
	v_and_b32_e32 v15, 0xffff0000, v133
	v_pk_add_f32 v[10:11], v[10:11], v[14:15]
	v_cvt_pk_bf16_f32 v8, v8, v9
	v_cvt_pk_bf16_f32 v9, v10, v11
	v_lshlrev_b32_e32 v10, 16, v134
	v_and_b32_e32 v11, 0xffff0000, v134
	v_pk_add_f32 v[4:5], v[4:5], v[10:11]
	v_cvt_pk_bf16_f32 v19, v12, v13
	v_cvt_pk_bf16_f32 v10, v4, v5
	v_lshlrev_b32_e32 v4, 16, v135
	v_and_b32_e32 v5, 0xffff0000, v135
	v_lshl_add_u64 v[12:13], s[88:89], 0, v[204:205]
	v_pk_add_f32 v[4:5], v[6:7], v[4:5]
	v_lshl_add_u64 v[92:93], v[92:93], 0, v[202:203]
	v_lshl_add_u64 v[76:77], v[76:77], 0, v[202:203]
	v_lshl_add_u64 v[60:61], v[60:61], 0, v[202:203]
	v_lshl_add_u64 v[44:45], v[44:45], 0, v[202:203]
	v_lshl_add_u64 v[28:29], v[28:29], 0, v[202:203]
	v_lshl_add_u64 v[12:13], v[12:13], 0, v[202:203]
	v_cvt_pk_bf16_f32 v11, v4, v5
	global_store_dwordx4 v[124:125], v[128:131], off
	global_store_dwordx4 v[124:125], v[120:123], off offset:256
	global_store_dwordx4 v[108:109], v[112:115], off
	global_store_dwordx4 v[108:109], v[104:107], off offset:256
	global_store_dwordx4 v[92:93], v[96:99], off
	global_store_dwordx4 v[92:93], v[88:91], off offset:256
	global_store_dwordx4 v[76:77], v[80:83], off
	global_store_dwordx4 v[76:77], v[72:75], off offset:256
	global_store_dwordx4 v[60:61], v[64:67], off
	global_store_dwordx4 v[60:61], v[56:59], off offset:256
	global_store_dwordx4 v[44:45], v[48:51], off
	global_store_dwordx4 v[44:45], v[40:43], off offset:256
	global_store_dwordx4 v[28:29], v[32:35], off
	global_store_dwordx4 v[28:29], v[24:27], off offset:256
	global_store_dwordx4 v[12:13], v[16:19], off
	global_store_dwordx4 v[12:13], v[8:11], off offset:256
	s_cbranch_vccz .LBB0_959
	s_waitcnt vmcnt(0)
	s_cmpk_gt_u32 s2, 0xff
	s_cbranch_scc1 .LBB0_970
	s_barrier

; #define PG8_STAGE(bufoff, gbase, voff) do { _Pragma("unroll") for (int _i = 0; _i < 2; ++_i) \
;         __builtin_amdgcn_global_load_lds((const unsigned*)((const char*)(gbase) + (voff)[_i]), (LAS unsigned*)(lds + (bufoff) + ldsw + _i * 8192), 16, 0, 0); } while (0)
; #define PG8_WAIT_V(n) asm volatile("s_waitcnt vmcnt(" #n ")" ::: "memory")
; #define PG8_BAR __builtin_amdgcn_s_barrier()
; template <class Epi, class Sched>
; __device__ __forceinline__ void gemm_phase(LAS unsigned char* lds, const Gemm g, const Sched& S, const Epi& E) {
;     ...
;     PG8_STAGE(PG8_SB(0, 0), cB, voffB); PG8_STAGE(PG8_SA(0, 0), cA, voffA); PG8_STAGE(PG8_SB(0, 1), cB + hstepB, voffB); PG8_STAGE(PG8_SA(0, 1), cA + hstepA, voffA);
;     if (wr == 1) PG8_BAR;
;     PG8_WAIT_V(4); PG8_BAR;
;     PG8_STAGE(PG8_SB(1, 0), cB + kstep, voffB); PG8_STAGE(PG8_SA(1, 0), cA + kstep, voffA); PG8_STAGE(PG8_SB(1, 1), cB + hstepB + kstep, voffB);
;     PG8_WAIT_V(6); PG8_BAR;
.LBB0_1088:
	v_readlane_b32 s18, v254, 14
	s_lshl_b32 s0, s0, 5
	v_mov_b32_e32 v137, v3
	v_readlane_b32 s19, v254, 15
	s_and_b32 s39, s0, 0x60
	s_add_i32 m0, s31, 0x18000
	v_lshl_add_u64 v[4:5], v[4:5], 0, s[8:9]
	v_lshl_add_u64 v[14:15], s[18:19], 0, v[136:137]
	v_mov_b32_e32 v135, v3
	s_lshl_b32 s38, s1, 6
	s_lshl_b32 s4, s1, 13
	s_lshl_b32 s5, s39, 7
	s_waitcnt vmcnt(2)
	s_barrier
	global_load_lds_dwordx4 v[4:5], off
	v_lshl_add_u64 v[4:5], v[6:7], 0, s[8:9]
	s_add_i32 m0, s31, 0x1a000
	s_add_i32 s42, s31, 0x8000
	s_add_i32 s43, s31, 0xa000
	v_lshl_add_u64 v[16:17], s[18:19], 0, v[134:135]
	global_load_lds_dwordx4 v[4:5], off
	v_lshl_add_u64 v[4:5], v[14:15], 0, s[8:9]
	s_mov_b32 m0, s42
	s_add_u32 s0, s20, 0x80080
	global_load_lds_dwordx4 v[4:5], off
	v_lshl_add_u64 v[4:5], v[16:17], 0, s[8:9]
	s_mov_b32 m0, s43
	s_addc_u32 s1, s21, 0
	global_load_lds_dwordx4 v[4:5], off
	s_add_i32 m0, s31, 0x1c000
	v_lshl_add_u64 v[4:5], s[0:1], 0, v[2:3]
	global_load_lds_dwordx4 v[4:5], off
	v_lshl_add_u64 v[4:5], s[0:1], 0, v[132:133]
	s_add_i32 m0, s31, 0x1e000
	s_movk_i32 s0, 0x3c0
	global_load_lds_dwordx4 v[4:5], off
	v_and_b32_e32 v4, 48, v1
	v_lshlrev_b32_e32 v5, 6, v1
	v_lshlrev_b32_e32 v1, 2, v1
	v_and_or_b32 v4, v5, s0, v4
	v_and_b32_e32 v1, 32, v1
	v_bitop3_b32 v5, v4, s4, v1 bitop3:0xde
	v_bitop3_b32 v1, s5, v4, v1 bitop3:0xf6
	v_lshlrev_b32_e32 v4, 15, v12
	v_and_b32_e32 v4, 0xffff0000, v4
	v_lshl_add_u32 v4, v11, 12, v4
	v_and_b32_e32 v6, 1, v12
	v_lshl_or_b32 v4, v6, 6, v4
	v_lshl_add_u32 v138, v13, 1, v4
	v_lshlrev_b32_e32 v4, 15, v8
	v_and_b32_e32 v4, 0xffff0000, v4
	s_waitcnt vmcnt(6)
	s_and_b32 s0, s2, 0xffffff00
	v_lshl_add_u32 v4, v9, 12, v4
	v_and_b32_e32 v6, 1, v8
	s_add_i32 s44, s0, 0
	v_lshl_or_b32 v4, v6, 6, v4
	v_readlane_b32 s0, v254, 12
	s_add_i32 s44, s44, 0x21000
	v_mov_b32_e32 v139, v3
	v_lshl_add_u32 v140, v10, 1, v4
	v_mov_b32_e32 v141, v3
	s_mov_b32 s48, 0
	v_add_u32_e32 v148, 0, v5
	v_readlane_b32 s47, v254, 9
	s_mov_b32 s46, s0
	s_barrier
	v_readlane_b32 s1, v254, 13
	s_waitcnt vmcnt(0)

; #define PG8_STAGE(bufoff, gbase, voff) do { _Pragma("unroll") for (int _i = 0; _i < 2; ++_i) \
;         __builtin_amdgcn_global_load_lds((const unsigned*)((const char*)(gbase) + (voff)[_i]), (LAS unsigned*)(lds + (bufoff) + ldsw + _i * 8192), 16, 0, 0); } while (0)
; #define PG8_LDA(dst, b, h) do { _Pragma("unroll") for (int m = 0; m < 4; ++m) _Pragma("unroll") for (int k = 0; k < 2; ++k) dst[m][k] = *(const LAS bf16x8*)(lds + PG8_SA(b, h) + aoff + m * 2048 + k * 1024); } while (0)
; #define PG8_LDB(dst, b, h) do { _Pragma("unroll") for (int n = 0; n < 2; ++n) _Pragma("unroll") for (int k = 0; k < 2; ++k) dst[n][k] = *(const LAS bf16x8*)(lds + PG8_SB(b, h) + boff + n * 2048 + k * 1024); } while (0)
; #define PG8_MMA(ai, bj, At, Bt) do { __builtin_amdgcn_s_setprio(1); _Pragma("unroll") for (int m = 0; m < 4; ++m) _Pragma("unroll") for (int n = 0; n < 2; ++n) _Pragma("unroll") for (int k = 0; k < 2; ++k) \
;         acc[ai][bj][m][n] = __builtin_amdgcn_mfma_f32_16x16x32_bf16(Bt[n][k], At[m][k], acc[ai][bj][m][n], 0, 0, 0); __builtin_amdgcn_s_setprio(0); } while (0)
; #define PG8_WAIT_V(n) asm volatile("s_waitcnt vmcnt(" #n ")" ::: "memory")
; #define PG8_WAIT_L(n) asm volatile("s_waitcnt lgkmcnt(" #n ")" ::: "memory")
; #define PG8_BAR __builtin_amdgcn_s_barrier()
; #define PG8_SCHED __builtin_amdgcn_sched_barrier(0)
; template <class Epi, class Sched>
; __device__ __forceinline__ void gemm_phase(LAS unsigned char* lds, const Gemm g, const Sched& S, const Epi& E) {
;     ...
;             PG8_LDB(B0, 0, 0); PG8_SCHED; PG8_LDA(At, 0, 0); PG8_STAGE(PG8_SA(1, 1), a1 + hstepA, voffA);
;             PG8_WAIT_L(8); PG8_BAR; PG8_WAIT_L(0); PG8_MMA(0, 0, At, B0); PG8_BAR; PG8_SCHED;
;             PG8_LDB(B1, 0, 1); PG8_STAGE(PG8_SB(0, 0), b2, voffB);
;             PG8_BAR; PG8_WAIT_L(0); PG8_MMA(0, 1, At, B1); PG8_BAR;
;             PG8_LDA(At, 0, 1); PG8_STAGE(PG8_SA(0, 0), a2, voffA);
;             PG8_BAR; PG8_WAIT_L(0); PG8_MMA(1, 0, At, B0); PG8_BAR; PG8_SCHED;
;             PG8_STAGE(PG8_SB(0, 1), b2 + hstepB, voffB);
;             PG8_WAIT_V(6); PG8_BAR; PG8_MMA(1, 1, At, B1); PG8_BAR;
.LBB0_1094:
	s_add_u32 s20, s18, 0xfff80080
	s_addc_u32 s21, s19, -1
	s_add_i32 s54, 0, 0x10000
	v_add_u32_e32 v146, s54, v1
	ds_read_b128 v[142:145], v146
	ds_read_b128 v[150:153], v146 offset:1024
	ds_read_b128 v[154:157], v146 offset:2048
	ds_read_b128 v[158:161], v146 offset:3072
	s_cmp_eq_u32 s53, 28
	s_cselect_b32 s25, s5, s21
	s_cselect_b32 s24, s49, s20
	s_cselect_b32 s21, s1, s52
	s_cselect_b32 s20, s50, s51
	ds_read_b128 v[162:165], v148
	ds_read_b128 v[166:169], v148 offset:1024
	ds_read_b128 v[170:173], v148 offset:2048
	ds_read_b128 v[174:177], v148 offset:3072
	ds_read_b128 v[178:181], v148 offset:4096
	ds_read_b128 v[182:185], v148 offset:5120
	ds_read_b128 v[186:189], v148 offset:6144
	ds_read_b128 v[190:193], v148 offset:7168
	s_add_i32 s56, 0, 0x14000
	v_add_u32_e32 v146, s56, v1
	ds_read_b128 v[194:197], v146
	ds_read_b128 v[198:201], v146 offset:1024
	ds_read_b128 v[202:205], v146 offset:2048
	ds_read_b128 v[206:209], v146 offset:3072
	s_add_i32 m0, s31, 0xc000
	s_nop 0
	global_load_lds_dwordx4 v138, s[18:19]
	s_add_i32 m0, s31, 0xe000
	s_nop 0
	global_load_lds_dwordx4 v140, s[18:19]
	s_waitcnt lgkmcnt(0)
	s_barrier
	s_setprio 1
	v_mfma_f32_16x16x32_bf16 v[128:131], v[142:145], v[162:165], v[128:131]
	v_mfma_f32_16x16x32_bf16 v[124:127], v[154:157], v[162:165], v[124:127]
	v_mfma_f32_16x16x32_bf16 v[120:123], v[142:145], v[170:173], v[120:123]
	v_mfma_f32_16x16x32_bf16 v[112:115], v[154:157], v[170:173], v[112:115]
	v_mfma_f32_16x16x32_bf16 v[104:107], v[142:145], v[178:181], v[104:107]
	v_mfma_f32_16x16x32_bf16 v[96:99], v[154:157], v[178:181], v[96:99]
	v_mfma_f32_16x16x32_bf16 v[88:91], v[142:145], v[186:189], v[88:91]
	v_mfma_f32_16x16x32_bf16 v[80:83], v[154:157], v[186:189], v[80:83]
	v_mfma_f32_16x16x32_bf16 v[128:131], v[150:153], v[166:169], v[128:131]
	v_mfma_f32_16x16x32_bf16 v[124:127], v[158:161], v[166:169], v[124:127]
	v_mfma_f32_16x16x32_bf16 v[120:123], v[150:153], v[174:177], v[120:123]
	v_mfma_f32_16x16x32_bf16 v[112:115], v[158:161], v[174:177], v[112:115]
	v_mfma_f32_16x16x32_bf16 v[104:107], v[150:153], v[182:185], v[104:107]
	v_mfma_f32_16x16x32_bf16 v[96:99], v[158:161], v[182:185], v[96:99]
	v_mfma_f32_16x16x32_bf16 v[88:91], v[150:153], v[190:193], v[88:91]
	v_mfma_f32_16x16x32_bf16 v[80:83], v[158:161], v[190:193], v[80:83]
	v_mfma_f32_16x16x32_bf16 v[116:119], v[194:197], v[162:165], v[116:119]
	v_mfma_f32_16x16x32_bf16 v[108:111], v[202:205], v[162:165], v[108:111]
	v_mfma_f32_16x16x32_bf16 v[100:103], v[194:197], v[170:173], v[100:103]
	v_mfma_f32_16x16x32_bf16 v[92:95], v[202:205], v[170:173], v[92:95]
	v_mfma_f32_16x16x32_bf16 v[84:87], v[194:197], v[178:181], v[84:87]
	v_mfma_f32_16x16x32_bf16 v[76:79], v[202:205], v[178:181], v[76:79]
	v_mfma_f32_16x16x32_bf16 v[72:75], v[194:197], v[186:189], v[72:75]
	v_mfma_f32_16x16x32_bf16 v[68:71], v[202:205], v[186:189], v[68:71]
	v_mfma_f32_16x16x32_bf16 v[116:119], v[198:201], v[166:169], v[116:119]
	v_mfma_f32_16x16x32_bf16 v[108:111], v[206:209], v[166:169], v[108:111]
	v_mfma_f32_16x16x32_bf16 v[100:103], v[198:201], v[174:177], v[100:103]
	v_mfma_f32_16x16x32_bf16 v[92:95], v[206:209], v[174:177], v[92:95]
	v_mfma_f32_16x16x32_bf16 v[84:87], v[198:201], v[182:185], v[84:87]
	v_mfma_f32_16x16x32_bf16 v[76:79], v[206:209], v[182:185], v[76:79]
	v_mfma_f32_16x16x32_bf16 v[72:75], v[198:201], v[190:193], v[72:75]
	v_mfma_f32_16x16x32_bf16 v[68:71], v[206:209], v[190:193], v[68:71]
	s_setprio 0
	s_barrier
	ds_read_b128 v[162:165], v148 offset:16384
	ds_read_b128 v[166:169], v148 offset:17408
	ds_read_b128 v[170:173], v148 offset:18432
	ds_read_b128 v[174:177], v148 offset:19456
	ds_read_b128 v[178:181], v148 offset:20480
	ds_read_b128 v[182:185], v148 offset:21504
	ds_read_b128 v[186:189], v148 offset:22528
	ds_read_b128 v[190:193], v148 offset:23552
	s_add_i32 s54, s54, s30
	v_lshl_add_u64 v[146:147], s[20:21], 0, v[2:3]
	s_mov_b32 m0, s54
	v_lshl_add_u64 v[210:211], s[20:21], 0, v[132:133]
	global_load_lds_dwordx4 v[146:147], off
	s_add_i32 m0, s54, 0x2000
	s_nop 0
	global_load_lds_dwordx4 v[210:211], off
	s_mov_b32 m0, s31
	v_lshl_add_u64 v[212:213], s[24:25], 0, v[136:137]
	global_load_lds_dwordx4 v[212:213], off
	v_lshl_add_u64 v[216:217], s[24:25], 0, v[134:135]
	s_mov_b32 m0, s35
	s_nop 0
	global_load_lds_dwordx4 v[216:217], off
	s_add_u32 s54, s20, 0x80000
	s_addc_u32 s55, s21, 0
	s_add_i32 s56, s56, s30
	s_mov_b32 m0, s56
	s_nop 0
	global_load_lds_dwordx4 v2, s[54:55]
	s_add_i32 m0, s56, 0x2000
	s_nop 0
	global_load_lds_dwordx4 v132, s[54:55]
	s_waitcnt lgkmcnt(0)
	s_waitcnt vmcnt(6)
	s_barrier
; #define PG8_STAGE(bufoff, gbase, voff) do { _Pragma("unroll") for (int _i = 0; _i < 2; ++_i) \
;         __builtin_amdgcn_global_load_lds((const unsigned*)((const char*)(gbase) + (voff)[_i]), (LAS unsigned*)(lds + (bufoff) + ldsw + _i * 8192), 16, 0, 0); } while (0)
; #define PG8_LDA(dst, b, h) do { _Pragma("unroll") for (int m = 0; m < 4; ++m) _Pragma("unroll") for (int k = 0; k < 2; ++k) dst[m][k] = *(const LAS bf16x8*)(lds + PG8_SA(b, h) + aoff + m * 2048 + k * 1024); } while (0)
; #define PG8_LDB(dst, b, h) do { _Pragma("unroll") for (int n = 0; n < 2; ++n) _Pragma("unroll") for (int k = 0; k < 2; ++k) dst[n][k] = *(const LAS bf16x8*)(lds + PG8_SB(b, h) + boff + n * 2048 + k * 1024); } while (0)
; #define PG8_MMA(ai, bj, At, Bt) do { __builtin_amdgcn_s_setprio(1); _Pragma("unroll") for (int m = 0; m < 4; ++m) _Pragma("unroll") for (int n = 0; n < 2; ++n) _Pragma("unroll") for (int k = 0; k < 2; ++k) \
;         acc[ai][bj][m][n] = __builtin_amdgcn_mfma_f32_16x16x32_bf16(Bt[n][k], At[m][k], acc[ai][bj][m][n], 0, 0, 0); __builtin_amdgcn_s_setprio(0); } while (0)
; #define PG8_WAIT_V(n) asm volatile("s_waitcnt vmcnt(" #n ")" ::: "memory")
; #define PG8_WAIT_L(n) asm volatile("s_waitcnt lgkmcnt(" #n ")" ::: "memory")
; #define PG8_BAR __builtin_amdgcn_s_barrier()
; #define PG8_SCHED __builtin_amdgcn_sched_barrier(0)
; template <class Epi, class Sched>
; __device__ __forceinline__ void gemm_phase(LAS unsigned char* lds, const Gemm g, const Sched& S, const Epi& E) {
;     ...
;             PG8_WAIT_V(6); PG8_BAR; PG8_MMA(1, 1, At, B1); PG8_BAR;
;             PG8_LDB(B0, 1, 0); PG8_SCHED; PG8_LDA(At, 1, 0); PG8_STAGE(PG8_SA(0, 1), a2 + hstepA, voffA);
;             PG8_WAIT_L(8); PG8_BAR; PG8_WAIT_L(0); PG8_MMA(0, 0, At, B0); PG8_BAR; PG8_SCHED;
;             PG8_LDB(B1, 1, 1); PG8_STAGE(PG8_SB(1, 0), b3, voffB);
;             PG8_BAR; PG8_WAIT_L(0); PG8_MMA(0, 1, At, B1); PG8_BAR;
;             PG8_LDA(At, 1, 1); PG8_STAGE(PG8_SA(1, 0), a3, voffA);
;             PG8_BAR; PG8_WAIT_L(0); PG8_MMA(1, 0, At, B0); PG8_BAR; PG8_SCHED;
	s_setprio 1
	v_mfma_f32_16x16x32_bf16 v[64:67], v[142:145], v[162:165], v[64:67]
	v_mfma_f32_16x16x32_bf16 v[60:63], v[154:157], v[162:165], v[60:63]
	v_mfma_f32_16x16x32_bf16 v[56:59], v[142:145], v[170:173], v[56:59]
	v_mfma_f32_16x16x32_bf16 v[48:51], v[154:157], v[170:173], v[48:51]
	v_mfma_f32_16x16x32_bf16 v[40:43], v[142:145], v[178:181], v[40:43]
	v_mfma_f32_16x16x32_bf16 v[32:35], v[154:157], v[178:181], v[32:35]
	v_mfma_f32_16x16x32_bf16 v[24:27], v[142:145], v[186:189], v[24:27]
	v_mfma_f32_16x16x32_bf16 v[16:19], v[154:157], v[186:189], v[16:19]
	v_mfma_f32_16x16x32_bf16 v[64:67], v[150:153], v[166:169], v[64:67]
	v_mfma_f32_16x16x32_bf16 v[60:63], v[158:161], v[166:169], v[60:63]
	v_mfma_f32_16x16x32_bf16 v[56:59], v[150:153], v[174:177], v[56:59]
	v_mfma_f32_16x16x32_bf16 v[48:51], v[158:161], v[174:177], v[48:51]
	v_mfma_f32_16x16x32_bf16 v[40:43], v[150:153], v[182:185], v[40:43]
	v_mfma_f32_16x16x32_bf16 v[32:35], v[158:161], v[182:185], v[32:35]
	v_mfma_f32_16x16x32_bf16 v[24:27], v[150:153], v[190:193], v[24:27]
	v_mfma_f32_16x16x32_bf16 v[16:19], v[158:161], v[190:193], v[16:19]
	v_mfma_f32_16x16x32_bf16 v[52:55], v[194:197], v[162:165], v[52:55]
	v_mfma_f32_16x16x32_bf16 v[44:47], v[202:205], v[162:165], v[44:47]
	v_mfma_f32_16x16x32_bf16 v[36:39], v[194:197], v[170:173], v[36:39]
	v_mfma_f32_16x16x32_bf16 v[28:31], v[202:205], v[170:173], v[28:31]
	v_mfma_f32_16x16x32_bf16 v[20:23], v[194:197], v[178:181], v[20:23]
	v_mfma_f32_16x16x32_bf16 v[12:15], v[202:205], v[178:181], v[12:15]
	v_mfma_f32_16x16x32_bf16 v[8:11], v[194:197], v[186:189], v[8:11]
	v_mfma_f32_16x16x32_bf16 v[4:7], v[202:205], v[186:189], v[4:7]
	v_mfma_f32_16x16x32_bf16 v[52:55], v[198:201], v[166:169], v[52:55]
	v_mfma_f32_16x16x32_bf16 v[44:47], v[206:209], v[166:169], v[44:47]
	v_mfma_f32_16x16x32_bf16 v[36:39], v[198:201], v[174:177], v[36:39]
	v_mfma_f32_16x16x32_bf16 v[28:31], v[206:209], v[174:177], v[28:31]
	v_mfma_f32_16x16x32_bf16 v[20:23], v[198:201], v[182:185], v[20:23]
	v_mfma_f32_16x16x32_bf16 v[12:15], v[206:209], v[182:185], v[12:15]
	v_mfma_f32_16x16x32_bf16 v[8:11], v[198:201], v[190:193], v[8:11]
	v_mfma_f32_16x16x32_bf16 v[4:7], v[206:209], v[190:193], v[4:7]
	s_setprio 0
	s_add_i32 s54, 0, 0x18000
	v_add_u32_e32 v149, s54, v1
	s_barrier
	ds_read_b128 v[142:145], v149
	ds_read_b128 v[150:153], v149 offset:1024
	ds_read_b128 v[154:157], v149 offset:2048
	ds_read_b128 v[158:161], v149 offset:3072
	s_add_u32 s24, s24, 0x80000
	s_addc_u32 s25, s25, 0
	ds_read_b128 v[162:165], v148 offset:32768
	ds_read_b128 v[166:169], v148 offset:33792
	ds_read_b128 v[170:173], v148 offset:34816
	ds_read_b128 v[174:177], v148 offset:35840
	ds_read_b128 v[178:181], v148 offset:36864
	ds_read_b128 v[182:185], v148 offset:37888
	ds_read_b128 v[186:189], v148 offset:38912
	ds_read_b128 v[190:193], v148 offset:39936
	s_mov_b32 m0, s36
	s_nop 0
	global_load_lds_dwordx4 v136, s[24:25]
	s_mov_b32 m0, s37
	s_nop 0
	global_load_lds_dwordx4 v134, s[24:25]
	s_add_i32 s24, 0, 0x1c000
	v_add_u32_e32 v149, s24, v1
	ds_read_b128 v[194:197], v149
	ds_read_b128 v[198:201], v149 offset:1024
	ds_read_b128 v[202:205], v149 offset:2048
	ds_read_b128 v[206:209], v149 offset:3072
	s_waitcnt lgkmcnt(0)
	s_barrier
	s_setprio 1
	v_mfma_f32_16x16x32_bf16 v[128:131], v[142:145], v[162:165], v[128:131]
	v_mfma_f32_16x16x32_bf16 v[124:127], v[154:157], v[162:165], v[124:127]
	v_mfma_f32_16x16x32_bf16 v[120:123], v[142:145], v[170:173], v[120:123]
	v_mfma_f32_16x16x32_bf16 v[112:115], v[154:157], v[170:173], v[112:115]
	v_mfma_f32_16x16x32_bf16 v[104:107], v[142:145], v[178:181], v[104:107]
	v_mfma_f32_16x16x32_bf16 v[96:99], v[154:157], v[178:181], v[96:99]
	v_mfma_f32_16x16x32_bf16 v[88:91], v[142:145], v[186:189], v[88:91]
	v_mfma_f32_16x16x32_bf16 v[80:83], v[154:157], v[186:189], v[80:83]
	v_mfma_f32_16x16x32_bf16 v[128:131], v[150:153], v[166:169], v[128:131]
	v_mfma_f32_16x16x32_bf16 v[124:127], v[158:161], v[166:169], v[124:127]
	v_mfma_f32_16x16x32_bf16 v[120:123], v[150:153], v[174:177], v[120:123]
	v_mfma_f32_16x16x32_bf16 v[112:115], v[158:161], v[174:177], v[112:115]
	v_mfma_f32_16x16x32_bf16 v[104:107], v[150:153], v[182:185], v[104:107]
	v_mfma_f32_16x16x32_bf16 v[96:99], v[158:161], v[182:185], v[96:99]
	v_mfma_f32_16x16x32_bf16 v[88:91], v[150:153], v[190:193], v[88:91]
	v_mfma_f32_16x16x32_bf16 v[80:83], v[158:161], v[190:193], v[80:83]
	v_mfma_f32_16x16x32_bf16 v[116:119], v[194:197], v[162:165], v[116:119]
	v_mfma_f32_16x16x32_bf16 v[108:111], v[202:205], v[162:165], v[108:111]
	v_mfma_f32_16x16x32_bf16 v[100:103], v[194:197], v[170:173], v[100:103]
	v_mfma_f32_16x16x32_bf16 v[92:95], v[202:205], v[170:173], v[92:95]
	v_mfma_f32_16x16x32_bf16 v[84:87], v[194:197], v[178:181], v[84:87]
	v_mfma_f32_16x16x32_bf16 v[76:79], v[202:205], v[178:181], v[76:79]
	v_mfma_f32_16x16x32_bf16 v[72:75], v[194:197], v[186:189], v[72:75]
	v_mfma_f32_16x16x32_bf16 v[68:71], v[202:205], v[186:189], v[68:71]
	v_mfma_f32_16x16x32_bf16 v[116:119], v[198:201], v[166:169], v[116:119]
	v_mfma_f32_16x16x32_bf16 v[108:111], v[206:209], v[166:169], v[108:111]
	v_mfma_f32_16x16x32_bf16 v[100:103], v[198:201], v[174:177], v[100:103]
	v_mfma_f32_16x16x32_bf16 v[92:95], v[206:209], v[174:177], v[92:95]
	v_mfma_f32_16x16x32_bf16 v[84:87], v[198:201], v[182:185], v[84:87]
	v_mfma_f32_16x16x32_bf16 v[76:79], v[206:209], v[182:185], v[76:79]
	v_mfma_f32_16x16x32_bf16 v[72:75], v[198:201], v[190:193], v[72:75]
	v_mfma_f32_16x16x32_bf16 v[68:71], v[206:209], v[190:193], v[68:71]
	s_setprio 0
	s_barrier
; #define LAS __attribute__((address_space(3)))
; #define PG8_STAGE(bufoff, gbase, voff) do { _Pragma("unroll") for (int _i = 0; _i < 2; ++_i) \
;         __builtin_amdgcn_global_load_lds((const unsigned*)((const char*)(gbase) + (voff)[_i]), (LAS unsigned*)(lds + (bufoff) + ldsw + _i * 8192), 16, 0, 0); } while (0)
; #define PG8_LDA(dst, b, h) do { _Pragma("unroll") for (int m = 0; m < 4; ++m) _Pragma("unroll") for (int k = 0; k < 2; ++k) dst[m][k] = *(const LAS bf16x8*)(lds + PG8_SA(b, h) + aoff + m * 2048 + k * 1024); } while (0)
; #define PG8_MMA(ai, bj, At, Bt) do { __builtin_amdgcn_s_setprio(1); _Pragma("unroll") for (int m = 0; m < 4; ++m) _Pragma("unroll") for (int n = 0; n < 2; ++n) _Pragma("unroll") for (int k = 0; k < 2; ++k) \
;         acc[ai][bj][m][n] = __builtin_amdgcn_mfma_f32_16x16x32_bf16(Bt[n][k], At[m][k], acc[ai][bj][m][n], 0, 0, 0); __builtin_amdgcn_s_setprio(0); } while (0)
; #define PG8_WAIT_V(n) asm volatile("s_waitcnt vmcnt(" #n ")" ::: "memory")
; #define PG8_WAIT_L(n) asm volatile("s_waitcnt lgkmcnt(" #n ")" ::: "memory")
; #define PG8_BAR __builtin_amdgcn_s_barrier()
; #define PG8_SCHED __builtin_amdgcn_sched_barrier(0)
; __device__ __forceinline__ void rs_read(float (&r_)[2][4], int ui, int wr, int fr) {
;     extern __shared__ __attribute__((aligned(16))) unsigned char lds_dyn_[];
;     const LAS float* rl = (const LAS float*)((LAS unsigned char*)lds_dyn_ + L_RSPF + (ui & 1) * 1024) + wr * 64 + fr;
; #pragma unroll
;     for (int ai = 0; ai < 2; ++ai)
; #pragma unroll
;         for (int m = 0; m < 4; ++m) r_[ai][m] = rl[ai * HALF + m * 16];
; }
; template <class Epi, class Sched>
; __device__ __forceinline__ void gemm_phase(LAS unsigned char* lds, const Gemm g, const Sched& S, const Epi& E) {
;     ...
;             PG8_LDA(At, 1, 1); PG8_STAGE(PG8_SA(1, 0), a3, voffA);
;             PG8_BAR; PG8_WAIT_L(0); PG8_MMA(1, 0, At, B0); PG8_BAR; PG8_SCHED;
;             PG8_STAGE(PG8_SB(1, 1), b3 + hstepB, voffB);
;             PG8_WAIT_V(6); PG8_BAR; PG8_MMA(1, 1, At, B1); PG8_BAR;
;         }
;         E(acc, cur, wr, wc, ui, fq);
	ds_read_b128 v[162:165], v148 offset:49152
	ds_read_b128 v[166:169], v148 offset:50176
	ds_read_b128 v[170:173], v148 offset:51200
	ds_read_b128 v[174:177], v148 offset:52224
	ds_read_b128 v[178:181], v148 offset:53248
	ds_read_b128 v[182:185], v148 offset:54272
	ds_read_b128 v[186:189], v148 offset:55296
	ds_read_b128 v[190:193], v148 offset:56320
	s_add_i32 s25, s54, s30
	v_lshl_add_u64 v[146:147], v[146:147], 0, s[8:9]
	s_mov_b32 m0, s25
	s_nop 0
	global_load_lds_dwordx4 v[146:147], off
	v_lshl_add_u64 v[146:147], v[210:211], 0, s[8:9]
	s_add_i32 m0, s25, 0x2000
	s_nop 0
	global_load_lds_dwordx4 v[146:147], off
	s_mov_b32 m0, s42
	v_lshl_add_u64 v[146:147], v[212:213], 0, s[8:9]
	global_load_lds_dwordx4 v[146:147], off
	v_lshl_add_u64 v[146:147], v[216:217], 0, s[8:9]
	s_mov_b32 m0, s43
	s_nop 0
	global_load_lds_dwordx4 v[146:147], off
	s_add_u32 s20, s20, 0x80080
	s_addc_u32 s21, s21, 0
	s_add_i32 s24, s24, s30
	s_mov_b32 m0, s24
	s_nop 0
	global_load_lds_dwordx4 v2, s[20:21]
	s_add_i32 m0, s24, 0x2000
	s_nop 0
	global_load_lds_dwordx4 v132, s[20:21]
	s_waitcnt lgkmcnt(0)
	s_waitcnt vmcnt(6)
	s_barrier
	s_setprio 1
	v_mfma_f32_16x16x32_bf16 v[64:67], v[142:145], v[162:165], v[64:67]
	v_mfma_f32_16x16x32_bf16 v[60:63], v[154:157], v[162:165], v[60:63]
	v_mfma_f32_16x16x32_bf16 v[56:59], v[142:145], v[170:173], v[56:59]
	v_mfma_f32_16x16x32_bf16 v[48:51], v[154:157], v[170:173], v[48:51]
	v_mfma_f32_16x16x32_bf16 v[40:43], v[142:145], v[178:181], v[40:43]
	v_mfma_f32_16x16x32_bf16 v[32:35], v[154:157], v[178:181], v[32:35]
	v_mfma_f32_16x16x32_bf16 v[24:27], v[142:145], v[186:189], v[24:27]
	v_mfma_f32_16x16x32_bf16 v[16:19], v[154:157], v[186:189], v[16:19]
	v_mfma_f32_16x16x32_bf16 v[64:67], v[150:153], v[166:169], v[64:67]
	v_mfma_f32_16x16x32_bf16 v[60:63], v[158:161], v[166:169], v[60:63]
	v_mfma_f32_16x16x32_bf16 v[56:59], v[150:153], v[174:177], v[56:59]
	v_mfma_f32_16x16x32_bf16 v[48:51], v[158:161], v[174:177], v[48:51]
	v_mfma_f32_16x16x32_bf16 v[40:43], v[150:153], v[182:185], v[40:43]
	v_mfma_f32_16x16x32_bf16 v[32:35], v[158:161], v[182:185], v[32:35]
	v_mfma_f32_16x16x32_bf16 v[24:27], v[150:153], v[190:193], v[24:27]
	v_mfma_f32_16x16x32_bf16 v[16:19], v[158:161], v[190:193], v[16:19]
	v_mfma_f32_16x16x32_bf16 v[52:55], v[194:197], v[162:165], v[52:55]
	v_mfma_f32_16x16x32_bf16 v[44:47], v[202:205], v[162:165], v[44:47]
	v_mfma_f32_16x16x32_bf16 v[36:39], v[194:197], v[170:173], v[36:39]
	v_mfma_f32_16x16x32_bf16 v[28:31], v[202:205], v[170:173], v[28:31]
	v_mfma_f32_16x16x32_bf16 v[20:23], v[194:197], v[178:181], v[20:23]
	v_mfma_f32_16x16x32_bf16 v[12:15], v[202:205], v[178:181], v[12:15]
	v_mfma_f32_16x16x32_bf16 v[8:11], v[194:197], v[186:189], v[8:11]
	v_mfma_f32_16x16x32_bf16 v[4:7], v[202:205], v[186:189], v[4:7]
	v_mfma_f32_16x16x32_bf16 v[52:55], v[198:201], v[166:169], v[52:55]
	v_mfma_f32_16x16x32_bf16 v[44:47], v[206:209], v[166:169], v[44:47]
	v_mfma_f32_16x16x32_bf16 v[36:39], v[198:201], v[174:177], v[36:39]
	v_mfma_f32_16x16x32_bf16 v[28:31], v[206:209], v[174:177], v[28:31]
	v_mfma_f32_16x16x32_bf16 v[20:23], v[198:201], v[182:185], v[20:23]
	v_mfma_f32_16x16x32_bf16 v[12:15], v[206:209], v[182:185], v[12:15]
	v_mfma_f32_16x16x32_bf16 v[8:11], v[198:201], v[190:193], v[8:11]
	v_mfma_f32_16x16x32_bf16 v[4:7], v[206:209], v[190:193], v[4:7]
	s_setprio 0
	s_add_i32 s53, s53, 2
	s_add_u32 s18, s18, 0x100
	s_addc_u32 s19, s19, 0
	s_add_u32 s51, s51, 0x100
	s_addc_u32 s52, s52, 0
	s_cmp_gt_u32 s53, 29
	s_barrier
	s_cbranch_scc0 .LBB0_1094
	s_lshl_b32 s1, s48, 10
	v_mov_b32_e32 v144, v0
	s_and_b32 s1, s1, 0x400
	s_add_i32 s1, s44, s1
	v_and_b32_e32 v145, 15, v144
	v_lshl_add_u32 v142, v145, 2, s1
	s_lshl_b32 s1, s47, 8
	v_lshrrev_b32_e32 v144, 1, v144
	v_and_or_b32 v144, v144, 24, s1
	ds_read2_b32 v[150:151], v142 offset1:16
	ds_read2_b32 v[152:153], v142 offset0:32 offset1:48
	ds_read2_b32 v[154:155], v142 offset0:128 offset1:144
	ds_read2_b32 v[142:143], v142 offset0:160 offset1:176
	v_or_b32_e32 v146, s39, v144
	v_or_b32_e32 v144, s38, v145
	v_lshl_add_u32 v149, s46, 8, v144
	v_ashrrev_i32_e32 v147, 31, v146
	v_mov_b64_e32 v[144:145], s[92:93]
	v_mad_i64_i32 v[156:157], s[18:19], v149, s11, v[144:145]
	v_lshlrev_b64 v[146:147], 1, v[146:147]
	s_waitcnt lgkmcnt(0)
; __device__ __forceinline__ unsigned cvt_pk_bf16(float lo, float hi) { const f32x2 v = {lo, hi}; const bf16v2_ r = __builtin_convertvector(v, bf16v2_); return __builtin_bit_cast(unsigned, r); }
;     __device__ __forceinline__ void operator()(const f32x4 (&acc)[2][2][4][2], const Unit& u, int wr, int wc, int ui, int) const {
;     ...
;         for (int ai = 0; ai < 2; ++ai)
; #pragma unroll
;             for (int m = 0; m < 4; ++m) { bf16_t* rowp = O + (size_t)(row0 + ai * HALF + m * 16) * ldc + col0; const float r = r_[ai][m];
; #pragma unroll
;                 for (int bj = 0; bj < 2; ++bj) { const f32x4 v0 = acc[ai][bj][m][0] * r, v1 = acc[ai][bj][m][1] * r;
;                     u32x4 w; w.x = cvt_pk_bf16(v0[0], v0[1]); w.y = cvt_pk_bf16(v0[2], v0[3]); w.z = cvt_pk_bf16(v1[0], v1[1]); w.w = cvt_pk_bf16(v1[2], v1[3]);
;                     *(u32x4*)(rowp + bj * HALF) = w; } }
	v_pk_mul_f32 v[130:131], v[130:131], v[150:151] op_sel_hi:[1,0]
	v_pk_mul_f32 v[128:129], v[128:129], v[150:151] op_sel_hi:[1,0]
	v_pk_mul_f32 v[158:159], v[126:127], v[150:151] op_sel_hi:[1,0]
	v_pk_mul_f32 v[126:127], v[124:125], v[150:151] op_sel_hi:[1,0]
	v_lshl_add_u64 v[156:157], v[156:157], 0, v[146:147]
	v_cvt_pk_bf16_f32 v124, v128, v129
	v_cvt_pk_bf16_f32 v125, v130, v131
	v_cvt_pk_bf16_f32 v126, v126, v127
	v_cvt_pk_bf16_f32 v127, v158, v159
	global_store_dwordx4 v[156:157], v[124:127], off
	v_pk_mul_f32 v[118:119], v[118:119], v[150:151] op_sel_hi:[1,0]
	v_pk_mul_f32 v[116:117], v[116:117], v[150:151] op_sel_hi:[1,0]
	v_pk_mul_f32 v[124:125], v[110:111], v[150:151] op_sel_hi:[1,0]
	v_pk_mul_f32 v[110:111], v[108:109], v[150:151] op_sel_hi:[1,0]
	v_cvt_pk_bf16_f32 v108, v116, v117
	v_cvt_pk_bf16_f32 v109, v118, v119
	v_cvt_pk_bf16_f32 v110, v110, v111
	v_cvt_pk_bf16_f32 v111, v124, v125
	global_store_dwordx4 v[156:157], v[108:111], off offset:256
	v_mov_b32_e32 v118, v151
	v_pk_mul_f32 v[114:115], v[114:115], v[118:119] op_sel_hi:[1,0]
	v_or_b32_e32 v108, 16, v149
	v_mad_i64_i32 v[108:109], s[18:19], v108, s11, v[144:145]
	v_lshl_add_u64 v[116:117], v[108:109], 0, v[146:147]
	v_pk_mul_f32 v[110:111], v[122:123], v[118:119] op_sel_hi:[1,0]
	v_pk_mul_f32 v[108:109], v[120:121], v[118:119] op_sel_hi:[1,0]
	v_pk_mul_f32 v[112:113], v[112:113], v[118:119] op_sel_hi:[1,0]
	v_cvt_pk_bf16_f32 v108, v108, v109
	v_cvt_pk_bf16_f32 v109, v110, v111
	v_cvt_pk_bf16_f32 v110, v112, v113
	v_cvt_pk_bf16_f32 v111, v114, v115
	global_store_dwordx4 v[116:117], v[108:111], off
	v_pk_mul_f32 v[102:103], v[102:103], v[118:119] op_sel_hi:[1,0]
	v_pk_mul_f32 v[100:101], v[100:101], v[118:119] op_sel_hi:[1,0]
	v_pk_mul_f32 v[108:109], v[94:95], v[118:119] op_sel_hi:[1,0]
	v_pk_mul_f32 v[94:95], v[92:93], v[118:119] op_sel_hi:[1,0]
	v_cvt_pk_bf16_f32 v92, v100, v101
	v_cvt_pk_bf16_f32 v93, v102, v103
	v_cvt_pk_bf16_f32 v94, v94, v95
	v_cvt_pk_bf16_f32 v95, v108, v109
	global_store_dwordx4 v[116:117], v[92:95], off offset:256
	v_pk_mul_f32 v[98:99], v[98:99], v[152:153] op_sel_hi:[1,0]
	v_pk_mul_f32 v[96:97], v[96:97], v[152:153] op_sel_hi:[1,0]
	v_or_b32_e32 v92, 32, v149
	v_mad_i64_i32 v[92:93], s[18:19], v92, s11, v[144:145]
	v_lshl_add_u64 v[100:101], v[92:93], 0, v[146:147]
	v_pk_mul_f32 v[94:95], v[106:107], v[152:153] op_sel_hi:[1,0]
	v_pk_mul_f32 v[92:93], v[104:105], v[152:153] op_sel_hi:[1,0]
	v_pk_mul_f32 v[86:87], v[86:87], v[152:153] op_sel_hi:[1,0]
	v_cvt_pk_bf16_f32 v92, v92, v93
	v_cvt_pk_bf16_f32 v93, v94, v95
	v_cvt_pk_bf16_f32 v94, v96, v97
	v_cvt_pk_bf16_f32 v95, v98, v99
	global_store_dwordx4 v[100:101], v[92:95], off
	v_pk_mul_f32 v[84:85], v[84:85], v[152:153] op_sel_hi:[1,0]
	v_pk_mul_f32 v[66:67], v[66:67], v[154:155] op_sel_hi:[1,0]
	v_pk_mul_f32 v[92:93], v[78:79], v[152:153] op_sel_hi:[1,0]
	v_pk_mul_f32 v[78:79], v[76:77], v[152:153] op_sel_hi:[1,0]
	v_cvt_pk_bf16_f32 v76, v84, v85
	v_cvt_pk_bf16_f32 v77, v86, v87
	v_cvt_pk_bf16_f32 v78, v78, v79
	v_cvt_pk_bf16_f32 v79, v92, v93
	global_store_dwordx4 v[100:101], v[76:79], off offset:256
	v_mov_b32_e32 v86, v153
	v_pk_mul_f32 v[82:83], v[82:83], v[86:87] op_sel_hi:[1,0]
	v_or_b32_e32 v76, 48, v149
	v_mad_i64_i32 v[76:77], s[18:19], v76, s11, v[144:145]
	v_lshl_add_u64 v[84:85], v[76:77], 0, v[146:147]
	v_pk_mul_f32 v[78:79], v[90:91], v[86:87] op_sel_hi:[1,0]
	v_pk_mul_f32 v[76:77], v[88:89], v[86:87] op_sel_hi:[1,0]
	v_pk_mul_f32 v[80:81], v[80:81], v[86:87] op_sel_hi:[1,0]
	v_cvt_pk_bf16_f32 v76, v76, v77
	v_cvt_pk_bf16_f32 v77, v78, v79
	v_cvt_pk_bf16_f32 v78, v80, v81
	v_cvt_pk_bf16_f32 v79, v82, v83
	global_store_dwordx4 v[84:85], v[76:79], off
	v_pk_mul_f32 v[74:75], v[74:75], v[86:87] op_sel_hi:[1,0]
	v_pk_mul_f32 v[72:73], v[72:73], v[86:87] op_sel_hi:[1,0]
	v_pk_mul_f32 v[76:77], v[70:71], v[86:87] op_sel_hi:[1,0]
	v_pk_mul_f32 v[70:71], v[68:69], v[86:87] op_sel_hi:[1,0]
	v_cvt_pk_bf16_f32 v68, v72, v73
	v_cvt_pk_bf16_f32 v69, v74, v75
	v_cvt_pk_bf16_f32 v70, v70, v71
	v_cvt_pk_bf16_f32 v71, v76, v77
	global_store_dwordx4 v[84:85], v[68:71], off offset:256
; __device__ __forceinline__ unsigned cvt_pk_bf16(float lo, float hi) { const f32x2 v = {lo, hi}; const bf16v2_ r = __builtin_convertvector(v, bf16v2_); return __builtin_bit_cast(unsigned, r); }
; #define PG8_WAIT_V(n) asm volatile("s_waitcnt vmcnt(" #n ")" ::: "memory")
; #define PG8_BAR __builtin_amdgcn_s_barrier()
;     __device__ __forceinline__ void operator()(const f32x4 (&acc)[2][2][4][2], const Unit& u, int wr, int wc, int ui, int) const {
;     ...
;         for (int ai = 0; ai < 2; ++ai)
; #pragma unroll
;             for (int m = 0; m < 4; ++m) { bf16_t* rowp = O + (size_t)(row0 + ai * HALF + m * 16) * ldc + col0; const float r = r_[ai][m];
; #pragma unroll
;                 for (int bj = 0; bj < 2; ++bj) { const f32x4 v0 = acc[ai][bj][m][0] * r, v1 = acc[ai][bj][m][1] * r;
;                     u32x4 w; w.x = cvt_pk_bf16(v0[0], v0[1]); w.y = cvt_pk_bf16(v0[2], v0[3]); w.z = cvt_pk_bf16(v1[0], v1[1]); w.w = cvt_pk_bf16(v1[2], v1[3]);
;                     *(u32x4*)(rowp + bj * HALF) = w; } }
; template <class Epi, class Sched>
; __device__ __forceinline__ void gemm_phase(LAS unsigned char* lds, const Gemm g, const Sched& S, const Epi& E) {
;     ...
;         S.done(cur);
;         if (!has_next) break;
; #pragma unroll
;         for (int a = 0; a < 2; ++a)
; #pragma unroll
;             for (int b = 0; b < 2; ++b)
; #pragma unroll
;                 for (int m = 0; m < 4; ++m)
; #pragma unroll
;                     for (int n = 0; n < 2; ++n) acc[a][b][m][n] = (f32x4){0.f, 0.f, 0.f, 0.f};
;         cur = nxt; cA = nA; cB = nB; ++ui;
;     }
;     PG8_WAIT_V(0);
;     if (wr == 0) PG8_BAR;
;     PG8_BAR;
	v_pk_mul_f32 v[64:65], v[64:65], v[154:155] op_sel_hi:[1,0]
	v_pk_mul_f32 v[54:55], v[54:55], v[154:155] op_sel_hi:[1,0]
	v_add_u32_e32 v68, 0x80, v149
	v_mad_i64_i32 v[68:69], s[18:19], v68, s11, v[144:145]
	v_pk_mul_f32 v[70:71], v[62:63], v[154:155] op_sel_hi:[1,0]
	v_pk_mul_f32 v[62:63], v[60:61], v[154:155] op_sel_hi:[1,0]
	v_lshl_add_u64 v[68:69], v[68:69], 0, v[146:147]
	v_cvt_pk_bf16_f32 v60, v64, v65
	v_cvt_pk_bf16_f32 v61, v66, v67
	v_cvt_pk_bf16_f32 v62, v62, v63
	v_cvt_pk_bf16_f32 v63, v70, v71
	global_store_dwordx4 v[68:69], v[60:63], off
	v_pk_mul_f32 v[52:53], v[52:53], v[154:155] op_sel_hi:[1,0]
	v_pk_mul_f32 v[34:35], v[34:35], v[142:143] op_sel_hi:[1,0]
	v_pk_mul_f32 v[60:61], v[46:47], v[154:155] op_sel_hi:[1,0]
	v_pk_mul_f32 v[46:47], v[44:45], v[154:155] op_sel_hi:[1,0]
	v_cvt_pk_bf16_f32 v44, v52, v53
	v_cvt_pk_bf16_f32 v45, v54, v55
	v_cvt_pk_bf16_f32 v46, v46, v47
	v_cvt_pk_bf16_f32 v47, v60, v61
	global_store_dwordx4 v[68:69], v[44:47], off offset:256
	v_mov_b32_e32 v54, v155
	v_pk_mul_f32 v[50:51], v[50:51], v[54:55] op_sel_hi:[1,0]
	v_add_u32_e32 v44, 0x90, v149
	v_mad_i64_i32 v[44:45], s[18:19], v44, s11, v[144:145]
	v_lshl_add_u64 v[52:53], v[44:45], 0, v[146:147]
	v_pk_mul_f32 v[46:47], v[58:59], v[54:55] op_sel_hi:[1,0]
	v_pk_mul_f32 v[44:45], v[56:57], v[54:55] op_sel_hi:[1,0]
	v_pk_mul_f32 v[48:49], v[48:49], v[54:55] op_sel_hi:[1,0]
	v_cvt_pk_bf16_f32 v44, v44, v45
	v_cvt_pk_bf16_f32 v45, v46, v47
	v_cvt_pk_bf16_f32 v46, v48, v49
	v_cvt_pk_bf16_f32 v47, v50, v51
	global_store_dwordx4 v[52:53], v[44:47], off
	v_pk_mul_f32 v[38:39], v[38:39], v[54:55] op_sel_hi:[1,0]
	v_pk_mul_f32 v[36:37], v[36:37], v[54:55] op_sel_hi:[1,0]
	v_pk_mul_f32 v[44:45], v[30:31], v[54:55] op_sel_hi:[1,0]
	v_pk_mul_f32 v[30:31], v[28:29], v[54:55] op_sel_hi:[1,0]
	v_cvt_pk_bf16_f32 v28, v36, v37
	v_cvt_pk_bf16_f32 v29, v38, v39
	v_cvt_pk_bf16_f32 v30, v30, v31
	v_cvt_pk_bf16_f32 v31, v44, v45
	global_store_dwordx4 v[52:53], v[28:31], off offset:256
	v_pk_mul_f32 v[32:33], v[32:33], v[142:143] op_sel_hi:[1,0]
	v_pk_mul_f32 v[22:23], v[22:23], v[142:143] op_sel_hi:[1,0]
	v_add_u32_e32 v28, 0xa0, v149
	v_mad_i64_i32 v[28:29], s[18:19], v28, s11, v[144:145]
	v_lshl_add_u64 v[36:37], v[28:29], 0, v[146:147]
	v_pk_mul_f32 v[30:31], v[42:43], v[142:143] op_sel_hi:[1,0]
	v_pk_mul_f32 v[28:29], v[40:41], v[142:143] op_sel_hi:[1,0]
	v_pk_mul_f32 v[20:21], v[20:21], v[142:143] op_sel_hi:[1,0]
	v_cvt_pk_bf16_f32 v28, v28, v29
	v_cvt_pk_bf16_f32 v29, v30, v31
	v_cvt_pk_bf16_f32 v30, v32, v33
	v_cvt_pk_bf16_f32 v31, v34, v35
	global_store_dwordx4 v[36:37], v[28:31], off
	s_and_b64 vcc, exec, s[40:41]
	s_mov_b32 s47, s0
	v_pk_mul_f32 v[28:29], v[14:15], v[142:143] op_sel_hi:[1,0]
	v_pk_mul_f32 v[14:15], v[12:13], v[142:143] op_sel_hi:[1,0]
	v_cvt_pk_bf16_f32 v12, v20, v21
	v_cvt_pk_bf16_f32 v13, v22, v23
	v_cvt_pk_bf16_f32 v14, v14, v15
	v_cvt_pk_bf16_f32 v15, v28, v29
	global_store_dwordx4 v[36:37], v[12:15], off offset:256
	v_mov_b32_e32 v22, v143
	v_pk_mul_f32 v[18:19], v[18:19], v[22:23] op_sel_hi:[1,0]
	v_add_u32_e32 v12, 0xb0, v149
	v_mad_i64_i32 v[12:13], s[18:19], v12, s11, v[144:145]
	v_lshl_add_u64 v[20:21], v[12:13], 0, v[146:147]
	v_pk_mul_f32 v[14:15], v[26:27], v[22:23] op_sel_hi:[1,0]
	v_pk_mul_f32 v[12:13], v[24:25], v[22:23] op_sel_hi:[1,0]
	v_pk_mul_f32 v[16:17], v[16:17], v[22:23] op_sel_hi:[1,0]
	v_cvt_pk_bf16_f32 v12, v12, v13
	v_cvt_pk_bf16_f32 v13, v14, v15
	v_cvt_pk_bf16_f32 v14, v16, v17
	v_cvt_pk_bf16_f32 v15, v18, v19
	global_store_dwordx4 v[20:21], v[12:15], off
	v_pk_mul_f32 v[10:11], v[10:11], v[22:23] op_sel_hi:[1,0]
	v_pk_mul_f32 v[8:9], v[8:9], v[22:23] op_sel_hi:[1,0]
	v_pk_mul_f32 v[12:13], v[6:7], v[22:23] op_sel_hi:[1,0]
	v_pk_mul_f32 v[6:7], v[4:5], v[22:23] op_sel_hi:[1,0]
	v_cvt_pk_bf16_f32 v4, v8, v9
	v_cvt_pk_bf16_f32 v5, v10, v11
	v_cvt_pk_bf16_f32 v6, v6, v7
	v_cvt_pk_bf16_f32 v7, v12, v13
	s_mov_b32 s46, s4
	s_mov_b64 s[20:21], s[14:15]
	s_mov_b64 s[18:19], s[6:7]
	s_mov_b32 s48, s45
	global_store_dwordx4 v[20:21], v[4:7], off offset:256
	s_cbranch_vccz .LBB0_1089
	s_waitcnt vmcnt(0)
	s_cmpk_gt_u32 s2, 0xff
	s_cbranch_scc1 .LBB0_1098
	s_barrier

; #define PG8_STAGE(bufoff, gbase, voff) do { _Pragma("unroll") for (int _i = 0; _i < 2; ++_i) \
;         __builtin_amdgcn_global_load_lds((const unsigned*)((const char*)(gbase) + (voff)[_i]), (LAS unsigned*)(lds + (bufoff) + ldsw + _i * 8192), 16, 0, 0); } while (0)
; #define PG8_LDA(dst, b, h) do { _Pragma("unroll") for (int m = 0; m < 4; ++m) _Pragma("unroll") for (int k = 0; k < 2; ++k) dst[m][k] = *(const LAS bf16x8*)(lds + PG8_SA(b, h) + aoff + m * 2048 + k * 1024); } while (0)
; #define PG8_LDB(dst, b, h) do { _Pragma("unroll") for (int n = 0; n < 2; ++n) _Pragma("unroll") for (int k = 0; k < 2; ++k) dst[n][k] = *(const LAS bf16x8*)(lds + PG8_SB(b, h) + boff + n * 2048 + k * 1024); } while (0)
; #define PG8_MMA(ai, bj, At, Bt) do { __builtin_amdgcn_s_setprio(1); _Pragma("unroll") for (int m = 0; m < 4; ++m) _Pragma("unroll") for (int n = 0; n < 2; ++n) _Pragma("unroll") for (int k = 0; k < 2; ++k) \
;         acc[ai][bj][m][n] = __builtin_amdgcn_mfma_f32_16x16x32_bf16(Bt[n][k], At[m][k], acc[ai][bj][m][n], 0, 0, 0); __builtin_amdgcn_s_setprio(0); } while (0)
; #define PG8_WAIT_V(n) asm volatile("s_waitcnt vmcnt(" #n ")" ::: "memory")
; #define PG8_WAIT_L(n) asm volatile("s_waitcnt lgkmcnt(" #n ")" ::: "memory")
; #define PG8_BAR __builtin_amdgcn_s_barrier()
; #define PG8_SCHED __builtin_amdgcn_sched_barrier(0)
; template <class Epi, class Sched>
; __device__ __forceinline__ void gemm_phase(LAS unsigned char* lds, const Gemm g, const Sched& S, const Epi& E) {
;     ...
;             PG8_LDB(B0, 0, 0); PG8_SCHED; PG8_LDA(At, 0, 0); PG8_STAGE(PG8_SA(1, 1), a1 + hstepA, voffA);
;             PG8_WAIT_L(8); PG8_BAR; PG8_WAIT_L(0); PG8_MMA(0, 0, At, B0); PG8_BAR; PG8_SCHED;
;             PG8_LDB(B1, 0, 1); PG8_STAGE(PG8_SB(0, 0), b2, voffB);
;             PG8_BAR; PG8_WAIT_L(0); PG8_MMA(0, 1, At, B1); PG8_BAR;
;             PG8_LDA(At, 0, 1); PG8_STAGE(PG8_SA(0, 0), a2, voffA);
;             PG8_BAR; PG8_WAIT_L(0); PG8_MMA(1, 0, At, B0); PG8_BAR; PG8_SCHED;
;             PG8_STAGE(PG8_SB(0, 1), b2 + hstepB, voffB);
;             PG8_WAIT_V(6); PG8_BAR; PG8_MMA(1, 1, At, B1); PG8_BAR;
.LBB0_1396:
	s_add_u32 s20, s6, 0xfff80080
	s_addc_u32 s21, s7, -1
	s_add_i32 s52, 0, 0x10000
	v_add_u32_e32 v144, s52, v1
	ds_read_b128 v[132:135], v144
	ds_read_b128 v[136:139], v144 offset:1024
	ds_read_b128 v[140:143], v144 offset:2048
	ds_read_b128 v[144:147], v144 offset:3072
	s_cmp_eq_u32 s51, 28
	s_cselect_b32 s25, s15, s21
	s_cselect_b32 s24, s47, s20
	s_cselect_b32 s21, s1, s50
	s_cselect_b32 s20, s48, s49
	ds_read_b128 v[148:151], v224
	ds_read_b128 v[152:155], v224 offset:1024
	ds_read_b128 v[156:159], v224 offset:2048
	ds_read_b128 v[160:163], v224 offset:3072
	ds_read_b128 v[164:167], v224 offset:4096
	ds_read_b128 v[168:171], v224 offset:5120
	ds_read_b128 v[172:175], v224 offset:6144
	ds_read_b128 v[176:179], v224 offset:7168
	s_add_i32 s54, 0, 0x14000
	v_add_u32_e32 v202, s54, v1
	ds_read_b128 v[180:183], v202
	ds_read_b128 v[184:187], v202 offset:1024
	ds_read_b128 v[188:191], v202 offset:2048
	ds_read_b128 v[202:205], v202 offset:3072
	s_add_i32 m0, s31, 0xc000
	s_nop 0
	global_load_lds_dwordx4 v198, s[6:7]
	s_add_i32 m0, s31, 0xe000
	s_nop 0
	global_load_lds_dwordx4 v200, s[6:7]
	s_waitcnt lgkmcnt(0)
	s_barrier
	s_setprio 1
	v_mfma_f32_16x16x32_bf16 v[128:131], v[132:135], v[148:151], v[128:131]
	v_mfma_f32_16x16x32_bf16 v[124:127], v[140:143], v[148:151], v[124:127]
	v_mfma_f32_16x16x32_bf16 v[112:115], v[132:135], v[156:159], v[112:115]
	v_mfma_f32_16x16x32_bf16 v[108:111], v[140:143], v[156:159], v[108:111]
	v_mfma_f32_16x16x32_bf16 v[100:103], v[132:135], v[164:167], v[100:103]
	v_mfma_f32_16x16x32_bf16 v[92:95], v[140:143], v[164:167], v[92:95]
	v_mfma_f32_16x16x32_bf16 v[84:87], v[132:135], v[172:175], v[84:87]
	v_mfma_f32_16x16x32_bf16 v[76:79], v[140:143], v[172:175], v[76:79]
	v_mfma_f32_16x16x32_bf16 v[128:131], v[136:139], v[152:155], v[128:131]
	v_mfma_f32_16x16x32_bf16 v[124:127], v[144:147], v[152:155], v[124:127]
	v_mfma_f32_16x16x32_bf16 v[112:115], v[136:139], v[160:163], v[112:115]
	v_mfma_f32_16x16x32_bf16 v[108:111], v[144:147], v[160:163], v[108:111]
	v_mfma_f32_16x16x32_bf16 v[100:103], v[136:139], v[168:171], v[100:103]
	v_mfma_f32_16x16x32_bf16 v[92:95], v[144:147], v[168:171], v[92:95]
	v_mfma_f32_16x16x32_bf16 v[84:87], v[136:139], v[176:179], v[84:87]
	v_mfma_f32_16x16x32_bf16 v[76:79], v[144:147], v[176:179], v[76:79]
	v_mfma_f32_16x16x32_bf16 v[120:123], v[180:183], v[148:151], v[120:123]
	v_mfma_f32_16x16x32_bf16 v[116:119], v[188:191], v[148:151], v[116:119]
	v_mfma_f32_16x16x32_bf16 v[104:107], v[180:183], v[156:159], v[104:107]
	v_mfma_f32_16x16x32_bf16 v[96:99], v[188:191], v[156:159], v[96:99]
	v_mfma_f32_16x16x32_bf16 v[88:91], v[180:183], v[164:167], v[88:91]
	v_mfma_f32_16x16x32_bf16 v[80:83], v[188:191], v[164:167], v[80:83]
	v_mfma_f32_16x16x32_bf16 v[72:75], v[180:183], v[172:175], v[72:75]
	v_mfma_f32_16x16x32_bf16 v[68:71], v[188:191], v[172:175], v[68:71]
	v_mfma_f32_16x16x32_bf16 v[120:123], v[184:187], v[152:155], v[120:123]
	v_mfma_f32_16x16x32_bf16 v[116:119], v[202:205], v[152:155], v[116:119]
	v_mfma_f32_16x16x32_bf16 v[104:107], v[184:187], v[160:163], v[104:107]
	v_mfma_f32_16x16x32_bf16 v[96:99], v[202:205], v[160:163], v[96:99]
	v_mfma_f32_16x16x32_bf16 v[88:91], v[184:187], v[168:171], v[88:91]
	v_mfma_f32_16x16x32_bf16 v[80:83], v[202:205], v[168:171], v[80:83]
	v_mfma_f32_16x16x32_bf16 v[72:75], v[184:187], v[176:179], v[72:75]
	v_mfma_f32_16x16x32_bf16 v[68:71], v[202:205], v[176:179], v[68:71]
	s_setprio 0
	s_barrier
	ds_read_b128 v[148:151], v224 offset:16384
	ds_read_b128 v[152:155], v224 offset:17408
	ds_read_b128 v[156:159], v224 offset:18432
	ds_read_b128 v[160:163], v224 offset:19456
	ds_read_b128 v[164:167], v224 offset:20480
	ds_read_b128 v[168:171], v224 offset:21504
	ds_read_b128 v[172:175], v224 offset:22528
	ds_read_b128 v[176:179], v224 offset:23552
	s_add_i32 s52, s52, s30
	v_lshl_add_u64 v[206:207], s[20:21], 0, v[2:3]
	s_mov_b32 m0, s52
	s_nop 0
	global_load_lds_dwordx4 v[206:207], off
	v_lshl_add_u64 v[208:209], s[20:21], 0, v[192:193]
	s_add_i32 m0, s52, 0x2000
	s_nop 0
	global_load_lds_dwordx4 v[208:209], off
	s_mov_b32 m0, s31
	v_lshl_add_u64 v[210:211], s[24:25], 0, v[196:197]
	global_load_lds_dwordx4 v[210:211], off
	v_lshl_add_u64 v[212:213], s[24:25], 0, v[194:195]
	s_mov_b32 m0, s35
	s_nop 0
	global_load_lds_dwordx4 v[212:213], off
	s_add_u32 s52, s20, 0x80000
	s_addc_u32 s53, s21, 0
	s_add_i32 s54, s54, s30
	s_mov_b32 m0, s54
	s_nop 0
	global_load_lds_dwordx4 v2, s[52:53]
	s_add_i32 m0, s54, 0x2000
	s_nop 0
	global_load_lds_dwordx4 v192, s[52:53]
	s_waitcnt lgkmcnt(0)
	s_waitcnt vmcnt(6)
	s_barrier
; #define PG8_STAGE(bufoff, gbase, voff) do { _Pragma("unroll") for (int _i = 0; _i < 2; ++_i) \
;         __builtin_amdgcn_global_load_lds((const unsigned*)((const char*)(gbase) + (voff)[_i]), (LAS unsigned*)(lds + (bufoff) + ldsw + _i * 8192), 16, 0, 0); } while (0)
; #define PG8_LDA(dst, b, h) do { _Pragma("unroll") for (int m = 0; m < 4; ++m) _Pragma("unroll") for (int k = 0; k < 2; ++k) dst[m][k] = *(const LAS bf16x8*)(lds + PG8_SA(b, h) + aoff + m * 2048 + k * 1024); } while (0)
; #define PG8_LDB(dst, b, h) do { _Pragma("unroll") for (int n = 0; n < 2; ++n) _Pragma("unroll") for (int k = 0; k < 2; ++k) dst[n][k] = *(const LAS bf16x8*)(lds + PG8_SB(b, h) + boff + n * 2048 + k * 1024); } while (0)
; #define PG8_MMA(ai, bj, At, Bt) do { __builtin_amdgcn_s_setprio(1); _Pragma("unroll") for (int m = 0; m < 4; ++m) _Pragma("unroll") for (int n = 0; n < 2; ++n) _Pragma("unroll") for (int k = 0; k < 2; ++k) \
;         acc[ai][bj][m][n] = __builtin_amdgcn_mfma_f32_16x16x32_bf16(Bt[n][k], At[m][k], acc[ai][bj][m][n], 0, 0, 0); __builtin_amdgcn_s_setprio(0); } while (0)
; #define PG8_WAIT_V(n) asm volatile("s_waitcnt vmcnt(" #n ")" ::: "memory")
; #define PG8_WAIT_L(n) asm volatile("s_waitcnt lgkmcnt(" #n ")" ::: "memory")
; #define PG8_BAR __builtin_amdgcn_s_barrier()
; #define PG8_SCHED __builtin_amdgcn_sched_barrier(0)
; template <class Epi, class Sched>
; __device__ __forceinline__ void gemm_phase(LAS unsigned char* lds, const Gemm g, const Sched& S, const Epi& E) {
;     ...
;             PG8_WAIT_V(6); PG8_BAR; PG8_MMA(1, 1, At, B1); PG8_BAR;
;             PG8_LDB(B0, 1, 0); PG8_SCHED; PG8_LDA(At, 1, 0); PG8_STAGE(PG8_SA(0, 1), a2 + hstepA, voffA);
;             PG8_WAIT_L(8); PG8_BAR; PG8_WAIT_L(0); PG8_MMA(0, 0, At, B0); PG8_BAR; PG8_SCHED;
;             PG8_LDB(B1, 1, 1); PG8_STAGE(PG8_SB(1, 0), b3, voffB);
;             PG8_BAR; PG8_WAIT_L(0); PG8_MMA(0, 1, At, B1); PG8_BAR;
;             PG8_LDA(At, 1, 1); PG8_STAGE(PG8_SA(1, 0), a3, voffA);
;             PG8_BAR; PG8_WAIT_L(0); PG8_MMA(1, 0, At, B0); PG8_BAR; PG8_SCHED;
	s_setprio 1
	v_mfma_f32_16x16x32_bf16 v[64:67], v[132:135], v[148:151], v[64:67]
	v_mfma_f32_16x16x32_bf16 v[60:63], v[140:143], v[148:151], v[60:63]
	v_mfma_f32_16x16x32_bf16 v[52:55], v[132:135], v[156:159], v[52:55]
	v_mfma_f32_16x16x32_bf16 v[44:47], v[140:143], v[156:159], v[44:47]
	v_mfma_f32_16x16x32_bf16 v[36:39], v[132:135], v[164:167], v[36:39]
	v_mfma_f32_16x16x32_bf16 v[28:31], v[140:143], v[164:167], v[28:31]
	v_mfma_f32_16x16x32_bf16 v[20:23], v[132:135], v[172:175], v[20:23]
	v_mfma_f32_16x16x32_bf16 v[12:15], v[140:143], v[172:175], v[12:15]
	v_mfma_f32_16x16x32_bf16 v[64:67], v[136:139], v[152:155], v[64:67]
	v_mfma_f32_16x16x32_bf16 v[60:63], v[144:147], v[152:155], v[60:63]
	v_mfma_f32_16x16x32_bf16 v[52:55], v[136:139], v[160:163], v[52:55]
	v_mfma_f32_16x16x32_bf16 v[44:47], v[144:147], v[160:163], v[44:47]
	v_mfma_f32_16x16x32_bf16 v[36:39], v[136:139], v[168:171], v[36:39]
	v_mfma_f32_16x16x32_bf16 v[28:31], v[144:147], v[168:171], v[28:31]
	v_mfma_f32_16x16x32_bf16 v[20:23], v[136:139], v[176:179], v[20:23]
	v_mfma_f32_16x16x32_bf16 v[12:15], v[144:147], v[176:179], v[12:15]
	v_mfma_f32_16x16x32_bf16 v[56:59], v[180:183], v[148:151], v[56:59]
	v_mfma_f32_16x16x32_bf16 v[48:51], v[188:191], v[148:151], v[48:51]
	v_mfma_f32_16x16x32_bf16 v[40:43], v[180:183], v[156:159], v[40:43]
	v_mfma_f32_16x16x32_bf16 v[32:35], v[188:191], v[156:159], v[32:35]
	v_mfma_f32_16x16x32_bf16 v[24:27], v[180:183], v[164:167], v[24:27]
	v_mfma_f32_16x16x32_bf16 v[16:19], v[188:191], v[164:167], v[16:19]
	v_mfma_f32_16x16x32_bf16 v[8:11], v[180:183], v[172:175], v[8:11]
	v_mfma_f32_16x16x32_bf16 v[4:7], v[188:191], v[172:175], v[4:7]
	v_mfma_f32_16x16x32_bf16 v[56:59], v[184:187], v[152:155], v[56:59]
	v_mfma_f32_16x16x32_bf16 v[48:51], v[202:205], v[152:155], v[48:51]
	v_mfma_f32_16x16x32_bf16 v[40:43], v[184:187], v[160:163], v[40:43]
	v_mfma_f32_16x16x32_bf16 v[32:35], v[202:205], v[160:163], v[32:35]
	v_mfma_f32_16x16x32_bf16 v[24:27], v[184:187], v[168:171], v[24:27]
	v_mfma_f32_16x16x32_bf16 v[16:19], v[202:205], v[168:171], v[16:19]
	v_mfma_f32_16x16x32_bf16 v[8:11], v[184:187], v[176:179], v[8:11]
	v_mfma_f32_16x16x32_bf16 v[4:7], v[202:205], v[176:179], v[4:7]
	s_setprio 0
	s_add_i32 s52, 0, 0x18000
	v_add_u32_e32 v144, s52, v1
	s_barrier
	ds_read_b128 v[132:135], v144
	ds_read_b128 v[136:139], v144 offset:1024
	ds_read_b128 v[140:143], v144 offset:2048
	ds_read_b128 v[144:147], v144 offset:3072
	s_add_u32 s24, s24, 0x80000
	s_addc_u32 s25, s25, 0
	ds_read_b128 v[148:151], v224 offset:32768
	ds_read_b128 v[152:155], v224 offset:33792
	ds_read_b128 v[156:159], v224 offset:34816
	ds_read_b128 v[160:163], v224 offset:35840
	ds_read_b128 v[164:167], v224 offset:36864
	ds_read_b128 v[168:171], v224 offset:37888
	ds_read_b128 v[172:175], v224 offset:38912
	ds_read_b128 v[176:179], v224 offset:39936
	s_mov_b32 m0, s36
	s_nop 0
	global_load_lds_dwordx4 v196, s[24:25]
	s_mov_b32 m0, s37
	s_nop 0
	global_load_lds_dwordx4 v194, s[24:25]
	s_add_i32 s24, 0, 0x1c000
	v_add_u32_e32 v202, s24, v1
	ds_read_b128 v[180:183], v202
	ds_read_b128 v[184:187], v202 offset:1024
	ds_read_b128 v[188:191], v202 offset:2048
	ds_read_b128 v[202:205], v202 offset:3072
	s_waitcnt lgkmcnt(0)
	s_barrier
	s_setprio 1
	v_mfma_f32_16x16x32_bf16 v[128:131], v[132:135], v[148:151], v[128:131]
	v_mfma_f32_16x16x32_bf16 v[124:127], v[140:143], v[148:151], v[124:127]
	v_mfma_f32_16x16x32_bf16 v[112:115], v[132:135], v[156:159], v[112:115]
	v_mfma_f32_16x16x32_bf16 v[108:111], v[140:143], v[156:159], v[108:111]
	v_mfma_f32_16x16x32_bf16 v[100:103], v[132:135], v[164:167], v[100:103]
	v_mfma_f32_16x16x32_bf16 v[92:95], v[140:143], v[164:167], v[92:95]
	v_mfma_f32_16x16x32_bf16 v[84:87], v[132:135], v[172:175], v[84:87]
	v_mfma_f32_16x16x32_bf16 v[76:79], v[140:143], v[172:175], v[76:79]
	v_mfma_f32_16x16x32_bf16 v[128:131], v[136:139], v[152:155], v[128:131]
	v_mfma_f32_16x16x32_bf16 v[124:127], v[144:147], v[152:155], v[124:127]
	v_mfma_f32_16x16x32_bf16 v[112:115], v[136:139], v[160:163], v[112:115]
	v_mfma_f32_16x16x32_bf16 v[108:111], v[144:147], v[160:163], v[108:111]
	v_mfma_f32_16x16x32_bf16 v[100:103], v[136:139], v[168:171], v[100:103]
	v_mfma_f32_16x16x32_bf16 v[92:95], v[144:147], v[168:171], v[92:95]
	v_mfma_f32_16x16x32_bf16 v[84:87], v[136:139], v[176:179], v[84:87]
	v_mfma_f32_16x16x32_bf16 v[76:79], v[144:147], v[176:179], v[76:79]
	v_mfma_f32_16x16x32_bf16 v[120:123], v[180:183], v[148:151], v[120:123]
	v_mfma_f32_16x16x32_bf16 v[116:119], v[188:191], v[148:151], v[116:119]
	v_mfma_f32_16x16x32_bf16 v[104:107], v[180:183], v[156:159], v[104:107]
	v_mfma_f32_16x16x32_bf16 v[96:99], v[188:191], v[156:159], v[96:99]
	v_mfma_f32_16x16x32_bf16 v[88:91], v[180:183], v[164:167], v[88:91]
	v_mfma_f32_16x16x32_bf16 v[80:83], v[188:191], v[164:167], v[80:83]
	v_mfma_f32_16x16x32_bf16 v[72:75], v[180:183], v[172:175], v[72:75]
	v_mfma_f32_16x16x32_bf16 v[68:71], v[188:191], v[172:175], v[68:71]
	v_mfma_f32_16x16x32_bf16 v[120:123], v[184:187], v[152:155], v[120:123]
	v_mfma_f32_16x16x32_bf16 v[116:119], v[202:205], v[152:155], v[116:119]
	v_mfma_f32_16x16x32_bf16 v[104:107], v[184:187], v[160:163], v[104:107]
	v_mfma_f32_16x16x32_bf16 v[96:99], v[202:205], v[160:163], v[96:99]
	v_mfma_f32_16x16x32_bf16 v[88:91], v[184:187], v[168:171], v[88:91]
	v_mfma_f32_16x16x32_bf16 v[80:83], v[202:205], v[168:171], v[80:83]
	v_mfma_f32_16x16x32_bf16 v[72:75], v[184:187], v[176:179], v[72:75]
	v_mfma_f32_16x16x32_bf16 v[68:71], v[202:205], v[176:179], v[68:71]
	s_setprio 0
	s_barrier
; #define PG8_STAGE(bufoff, gbase, voff) do { _Pragma("unroll") for (int _i = 0; _i < 2; ++_i) \
;         __builtin_amdgcn_global_load_lds((const unsigned*)((const char*)(gbase) + (voff)[_i]), (LAS unsigned*)(lds + (bufoff) + ldsw + _i * 8192), 16, 0, 0); } while (0)
; #define PG8_LDA(dst, b, h) do { _Pragma("unroll") for (int m = 0; m < 4; ++m) _Pragma("unroll") for (int k = 0; k < 2; ++k) dst[m][k] = *(const LAS bf16x8*)(lds + PG8_SA(b, h) + aoff + m * 2048 + k * 1024); } while (0)
; #define PG8_MMA(ai, bj, At, Bt) do { __builtin_amdgcn_s_setprio(1); _Pragma("unroll") for (int m = 0; m < 4; ++m) _Pragma("unroll") for (int n = 0; n < 2; ++n) _Pragma("unroll") for (int k = 0; k < 2; ++k) \
;         acc[ai][bj][m][n] = __builtin_amdgcn_mfma_f32_16x16x32_bf16(Bt[n][k], At[m][k], acc[ai][bj][m][n], 0, 0, 0); __builtin_amdgcn_s_setprio(0); } while (0)
; #define PG8_WAIT_V(n) asm volatile("s_waitcnt vmcnt(" #n ")" ::: "memory")
; #define PG8_WAIT_L(n) asm volatile("s_waitcnt lgkmcnt(" #n ")" ::: "memory")
; #define PG8_BAR __builtin_amdgcn_s_barrier()
; #define PG8_SCHED __builtin_amdgcn_sched_barrier(0)
;     __device__ __forceinline__ void operator()(const f32x4 (&acc)[2][2][4][2], const Unit& u, int wr, int wc, int, int) const {
;     ...
;                 for (int bj = 0; bj < 2; ++bj) cin[ai][m][bj] = *(const u32x4*)(C + (size_t)(row0 + ai * HALF + m * 16) * ldc + col0 + bj * HALF);
; template <class Epi, class Sched>
; __device__ __forceinline__ void gemm_phase(LAS unsigned char* lds, const Gemm g, const Sched& S, const Epi& E) {
;     ...
;             PG8_LDA(At, 1, 1); PG8_STAGE(PG8_SA(1, 0), a3, voffA);
;             PG8_BAR; PG8_WAIT_L(0); PG8_MMA(1, 0, At, B0); PG8_BAR; PG8_SCHED;
;             PG8_STAGE(PG8_SB(1, 1), b3 + hstepB, voffB);
;             PG8_WAIT_V(6); PG8_BAR; PG8_MMA(1, 1, At, B1); PG8_BAR;
;         }
;         E(acc, cur, wr, wc, ui, fq);
;         S.done(cur);
;         if (!has_next) break;
	ds_read_b128 v[148:151], v224 offset:49152
	ds_read_b128 v[152:155], v224 offset:50176
	ds_read_b128 v[156:159], v224 offset:51200
	ds_read_b128 v[160:163], v224 offset:52224
	ds_read_b128 v[164:167], v224 offset:53248
	ds_read_b128 v[168:171], v224 offset:54272
	ds_read_b128 v[172:175], v224 offset:55296
	ds_read_b128 v[176:179], v224 offset:56320
	s_add_i32 s25, s52, s30
	v_lshl_add_u64 v[206:207], v[206:207], 0, s[8:9]
	s_mov_b32 m0, s25
	s_nop 0
	global_load_lds_dwordx4 v[206:207], off
	v_lshl_add_u64 v[206:207], v[208:209], 0, s[8:9]
	s_add_i32 m0, s25, 0x2000
	s_nop 0
	global_load_lds_dwordx4 v[206:207], off
	s_mov_b32 m0, s42
	v_lshl_add_u64 v[206:207], v[210:211], 0, s[8:9]
	global_load_lds_dwordx4 v[206:207], off
	v_lshl_add_u64 v[206:207], v[212:213], 0, s[8:9]
	s_mov_b32 m0, s43
	s_nop 0
	global_load_lds_dwordx4 v[206:207], off
	s_add_u32 s20, s20, 0x80080
	s_addc_u32 s21, s21, 0
	s_add_i32 s24, s24, s30
	s_mov_b32 m0, s24
	s_nop 0
	global_load_lds_dwordx4 v2, s[20:21]
	s_add_i32 m0, s24, 0x2000
	s_nop 0
	global_load_lds_dwordx4 v192, s[20:21]
	s_waitcnt lgkmcnt(0)
	s_waitcnt vmcnt(6)
	s_barrier
	s_setprio 1
	v_mfma_f32_16x16x32_bf16 v[64:67], v[132:135], v[148:151], v[64:67]
	v_mfma_f32_16x16x32_bf16 v[60:63], v[140:143], v[148:151], v[60:63]
	v_mfma_f32_16x16x32_bf16 v[52:55], v[132:135], v[156:159], v[52:55]
	v_mfma_f32_16x16x32_bf16 v[44:47], v[140:143], v[156:159], v[44:47]
	v_mfma_f32_16x16x32_bf16 v[36:39], v[132:135], v[164:167], v[36:39]
	v_mfma_f32_16x16x32_bf16 v[28:31], v[140:143], v[164:167], v[28:31]
	v_mfma_f32_16x16x32_bf16 v[20:23], v[132:135], v[172:175], v[20:23]
	v_mfma_f32_16x16x32_bf16 v[12:15], v[140:143], v[172:175], v[12:15]
	v_mfma_f32_16x16x32_bf16 v[64:67], v[136:139], v[152:155], v[64:67]
	v_mfma_f32_16x16x32_bf16 v[60:63], v[144:147], v[152:155], v[60:63]
	v_mfma_f32_16x16x32_bf16 v[52:55], v[136:139], v[160:163], v[52:55]
	v_mfma_f32_16x16x32_bf16 v[44:47], v[144:147], v[160:163], v[44:47]
	v_mfma_f32_16x16x32_bf16 v[36:39], v[136:139], v[168:171], v[36:39]
	v_mfma_f32_16x16x32_bf16 v[28:31], v[144:147], v[168:171], v[28:31]
	v_mfma_f32_16x16x32_bf16 v[20:23], v[136:139], v[176:179], v[20:23]
	v_mfma_f32_16x16x32_bf16 v[12:15], v[144:147], v[176:179], v[12:15]
	v_mfma_f32_16x16x32_bf16 v[56:59], v[180:183], v[148:151], v[56:59]
	v_mfma_f32_16x16x32_bf16 v[48:51], v[188:191], v[148:151], v[48:51]
	v_mfma_f32_16x16x32_bf16 v[40:43], v[180:183], v[156:159], v[40:43]
	v_mfma_f32_16x16x32_bf16 v[32:35], v[188:191], v[156:159], v[32:35]
	v_mfma_f32_16x16x32_bf16 v[24:27], v[180:183], v[164:167], v[24:27]
	v_mfma_f32_16x16x32_bf16 v[16:19], v[188:191], v[164:167], v[16:19]
	v_mfma_f32_16x16x32_bf16 v[8:11], v[180:183], v[172:175], v[8:11]
	v_mfma_f32_16x16x32_bf16 v[4:7], v[188:191], v[172:175], v[4:7]
	v_mfma_f32_16x16x32_bf16 v[56:59], v[184:187], v[152:155], v[56:59]
	v_mfma_f32_16x16x32_bf16 v[48:51], v[202:205], v[152:155], v[48:51]
	v_mfma_f32_16x16x32_bf16 v[40:43], v[184:187], v[160:163], v[40:43]
	v_mfma_f32_16x16x32_bf16 v[32:35], v[202:205], v[160:163], v[32:35]
	v_mfma_f32_16x16x32_bf16 v[24:27], v[184:187], v[168:171], v[24:27]
	v_mfma_f32_16x16x32_bf16 v[16:19], v[202:205], v[168:171], v[16:19]
	v_mfma_f32_16x16x32_bf16 v[8:11], v[184:187], v[176:179], v[8:11]
	v_mfma_f32_16x16x32_bf16 v[4:7], v[202:205], v[176:179], v[4:7]
	s_setprio 0
	s_add_i32 s51, s51, 2
	s_add_u32 s6, s6, 0x100
	s_addc_u32 s7, s7, 0
	s_add_u32 s49, s49, 0x100
	s_addc_u32 s50, s50, 0
	s_cmp_gt_u32 s51, 29
	s_barrier
	s_cbranch_scc0 .LBB0_1396
	v_mov_b32_e32 v133, v0
	s_lshl_b32 s1, s46, 8
	s_add_i32 s1, s1, s38
	v_and_or_b32 v132, v133, 15, s1
	s_lshl_b32 s1, s45, 8
	v_lshrrev_b32_e32 v133, 1, v133
	v_and_or_b32 v133, v133, 24, s1
	v_or_b32_e32 v134, s39, v133
	v_ashrrev_i32_e32 v135, 31, v134
	v_lshlrev_b64 v[202:203], 1, v[134:135]
	v_ashrrev_i32_e32 v133, 31, v132
	v_lshl_add_u64 v[134:135], s[88:89], 0, v[202:203]
	v_lshlrev_b64 v[216:217], 12, v[132:133]
	v_lshl_add_u64 v[136:137], v[134:135], 0, v[216:217]
	global_load_dwordx4 v[226:229], v[136:137], off
	global_load_dwordx4 v[188:191], v[136:137], off offset:256
	v_or_b32_e32 v136, 16, v132
	v_ashrrev_i32_e32 v137, 31, v136
	v_lshlrev_b64 v[222:223], 12, v[136:137]
	v_lshl_add_u64 v[136:137], v[134:135], 0, v[222:223]
	global_load_dwordx4 v[184:187], v[136:137], off
	global_load_dwordx4 v[180:183], v[136:137], off offset:256
	v_or_b32_e32 v136, 32, v132
	v_ashrrev_i32_e32 v137, 31, v136
	v_lshlrev_b64 v[220:221], 12, v[136:137]
	v_lshl_add_u64 v[136:137], v[134:135], 0, v[220:221]
	global_load_dwordx4 v[176:179], v[136:137], off
	global_load_dwordx4 v[168:171], v[136:137], off offset:256
	v_or_b32_e32 v132, 48, v132
	v_ashrrev_i32_e32 v133, 31, v132
	v_lshlrev_b64 v[212:213], 12, v[132:133]
	v_lshl_add_u64 v[132:133], v[134:135], 0, v[212:213]
	global_load_dwordx4 v[172:175], v[132:133], off
	global_load_dwordx4 v[164:167], v[132:133], off offset:256
	s_mov_b64 s[6:7], 0x80000
	v_lshl_add_u64 v[210:211], v[216:217], 0, s[6:7]
	v_lshl_add_u64 v[132:133], v[134:135], 0, v[210:211]
	global_load_dwordx4 v[160:163], v[132:133], off
	global_load_dwordx4 v[156:159], v[132:133], off offset:256
	s_mov_b64 s[6:7], 0x90000
	v_lshl_add_u64 v[208:209], v[216:217], 0, s[6:7]
	v_lshl_add_u64 v[132:133], v[134:135], 0, v[208:209]
	global_load_dwordx4 v[152:155], v[132:133], off
	global_load_dwordx4 v[148:151], v[132:133], off offset:256
	s_mov_b64 s[6:7], 0xa0000
	v_lshl_add_u64 v[206:207], v[216:217], 0, s[6:7]
	v_lshl_add_u64 v[132:133], v[134:135], 0, v[206:207]
	global_load_dwordx4 v[144:147], v[132:133], off
	global_load_dwordx4 v[140:143], v[132:133], off offset:256
	s_mov_b64 s[6:7], 0xb0000
	v_lshl_add_u64 v[204:205], v[216:217], 0, s[6:7]
	v_lshl_add_u64 v[132:133], v[134:135], 0, v[204:205]
	global_load_dwordx4 v[136:139], v[132:133], off
	s_nop 0
	global_load_dwordx4 v[132:135], v[132:133], off offset:256
	s_and_b64 vcc, exec, s[40:41]
	s_mov_b32 s45, s0
	s_mov_b32 s46, s14
	s_mov_b64 s[20:21], s[18:19]
	s_mov_b64 s[6:7], s[4:5]
	s_waitcnt vmcnt(0)
; __device__ __forceinline__ unsigned cvt_pk_bf16(float lo, float hi) { const f32x2 v = {lo, hi}; const bf16v2_ r = __builtin_convertvector(v, bf16v2_); return __builtin_bit_cast(unsigned, r); }
; __device__ __forceinline__ float bflo(unsigned w) { return __uint_as_float(w << 16); }
; __device__ __forceinline__ float bfhi(unsigned w) { return __uint_as_float(w & 0xffff0000u); }
;     __device__ __forceinline__ void operator()(const f32x4 (&acc)[2][2][4][2], const Unit& u, int wr, int wc, int, int) const {
;     ...
;                 for (int bj = 0; bj < 2; ++bj) { const u32x4 c = cin[ai][m][bj]; const f32x4 v0 = acc[ai][bj][m][0], v1 = acc[ai][bj][m][1];
;                     u32x4 w; w.x = cvt_pk_bf16(bflo(c.x) + v0[0], bfhi(c.x) + v0[1]); w.y = cvt_pk_bf16(bflo(c.y) + v0[2], bfhi(c.y) + v0[3]);
;                     w.z = cvt_pk_bf16(bflo(c.z) + v1[0], bfhi(c.z) + v1[1]); w.w = cvt_pk_bf16(bflo(c.w) + v1[2], bfhi(c.w) + v1[3]);
;                     *(u32x4*)(C + (size_t)(row0 + ai * HALF + m * 16) * ldc + col0 + bj * HALF) = w; }
	v_lshlrev_b32_e32 v218, 16, v226
	v_and_b32_e32 v219, 0xffff0000, v226
	v_pk_add_f32 v[128:129], v[128:129], v[218:219]
	v_lshlrev_b32_e32 v218, 16, v227
	v_and_b32_e32 v219, 0xffff0000, v227
	v_pk_add_f32 v[130:131], v[130:131], v[218:219]
	v_cvt_pk_bf16_f32 v128, v128, v129
	v_cvt_pk_bf16_f32 v129, v130, v131
	v_lshlrev_b32_e32 v130, 16, v228
	v_and_b32_e32 v131, 0xffff0000, v228
	v_pk_add_f32 v[124:125], v[124:125], v[130:131]
	s_nop 0
	v_cvt_pk_bf16_f32 v130, v124, v125
	v_lshlrev_b32_e32 v124, 16, v229
	v_and_b32_e32 v125, 0xffff0000, v229
	v_pk_add_f32 v[124:125], v[126:127], v[124:125]
	v_lshlrev_b32_e32 v126, 16, v188
	v_and_b32_e32 v127, 0xffff0000, v188
	v_pk_add_f32 v[120:121], v[120:121], v[126:127]
	v_lshlrev_b32_e32 v126, 16, v189
	v_and_b32_e32 v127, 0xffff0000, v189
	v_pk_add_f32 v[122:123], v[122:123], v[126:127]
	v_cvt_pk_bf16_f32 v120, v120, v121
	v_cvt_pk_bf16_f32 v121, v122, v123
	v_lshlrev_b32_e32 v122, 16, v190
	v_and_b32_e32 v123, 0xffff0000, v190
	v_pk_add_f32 v[116:117], v[116:117], v[122:123]
	v_cvt_pk_bf16_f32 v131, v124, v125
	v_cvt_pk_bf16_f32 v122, v116, v117
	v_lshlrev_b32_e32 v116, 16, v191
	v_and_b32_e32 v117, 0xffff0000, v191
	v_pk_add_f32 v[116:117], v[118:119], v[116:117]
	v_lshl_add_u64 v[124:125], s[88:89], 0, v[216:217]
	v_cvt_pk_bf16_f32 v123, v116, v117
	v_lshlrev_b32_e32 v116, 16, v184
	v_and_b32_e32 v117, 0xffff0000, v184
	v_pk_add_f32 v[112:113], v[112:113], v[116:117]
	v_lshlrev_b32_e32 v116, 16, v185
	v_and_b32_e32 v117, 0xffff0000, v185
	v_pk_add_f32 v[114:115], v[114:115], v[116:117]
	v_cvt_pk_bf16_f32 v112, v112, v113
	v_cvt_pk_bf16_f32 v113, v114, v115
	v_lshlrev_b32_e32 v114, 16, v186
	v_and_b32_e32 v115, 0xffff0000, v186
	v_pk_add_f32 v[108:109], v[108:109], v[114:115]
	v_lshl_add_u64 v[124:125], v[124:125], 0, v[202:203]
	v_cvt_pk_bf16_f32 v114, v108, v109
	v_lshlrev_b32_e32 v108, 16, v187
	v_and_b32_e32 v109, 0xffff0000, v187
	v_pk_add_f32 v[108:109], v[110:111], v[108:109]
	v_lshlrev_b32_e32 v110, 16, v180
	v_and_b32_e32 v111, 0xffff0000, v180
	v_pk_add_f32 v[104:105], v[104:105], v[110:111]
	v_lshlrev_b32_e32 v110, 16, v181
	v_and_b32_e32 v111, 0xffff0000, v181
	v_pk_add_f32 v[106:107], v[106:107], v[110:111]
	v_cvt_pk_bf16_f32 v104, v104, v105
	v_cvt_pk_bf16_f32 v105, v106, v107
	v_lshlrev_b32_e32 v106, 16, v182
	v_and_b32_e32 v107, 0xffff0000, v182
	v_pk_add_f32 v[96:97], v[96:97], v[106:107]
	v_cvt_pk_bf16_f32 v115, v108, v109
	v_cvt_pk_bf16_f32 v106, v96, v97
	v_lshlrev_b32_e32 v96, 16, v183
	v_and_b32_e32 v97, 0xffff0000, v183
	v_pk_add_f32 v[96:97], v[98:99], v[96:97]
	v_lshlrev_b32_e32 v98, 16, v177
	v_cvt_pk_bf16_f32 v107, v96, v97
	v_lshlrev_b32_e32 v96, 16, v176
	v_and_b32_e32 v97, 0xffff0000, v176
	v_and_b32_e32 v99, 0xffff0000, v177
	v_pk_add_f32 v[96:97], v[100:101], v[96:97]
	v_pk_add_f32 v[98:99], v[102:103], v[98:99]
	v_cvt_pk_bf16_f32 v96, v96, v97
	v_cvt_pk_bf16_f32 v97, v98, v99
	v_lshlrev_b32_e32 v98, 16, v178
	v_and_b32_e32 v99, 0xffff0000, v178
	v_pk_add_f32 v[92:93], v[92:93], v[98:99]
	v_lshl_add_u64 v[108:109], s[88:89], 0, v[222:223]
	v_cvt_pk_bf16_f32 v98, v92, v93
	v_lshlrev_b32_e32 v92, 16, v179
	v_and_b32_e32 v93, 0xffff0000, v179
	v_pk_add_f32 v[92:93], v[94:95], v[92:93]
	v_lshlrev_b32_e32 v94, 16, v168
	v_and_b32_e32 v95, 0xffff0000, v168
	v_pk_add_f32 v[88:89], v[88:89], v[94:95]
	v_lshlrev_b32_e32 v94, 16, v169
	v_and_b32_e32 v95, 0xffff0000, v169
	v_pk_add_f32 v[90:91], v[90:91], v[94:95]
	v_cvt_pk_bf16_f32 v88, v88, v89
	v_cvt_pk_bf16_f32 v89, v90, v91
	v_lshlrev_b32_e32 v90, 16, v170
	v_and_b32_e32 v91, 0xffff0000, v170
	v_pk_add_f32 v[80:81], v[80:81], v[90:91]
	v_cvt_pk_bf16_f32 v99, v92, v93
	v_cvt_pk_bf16_f32 v90, v80, v81
	v_lshlrev_b32_e32 v80, 16, v171
	v_and_b32_e32 v81, 0xffff0000, v171
	v_pk_add_f32 v[80:81], v[82:83], v[80:81]
	v_lshlrev_b32_e32 v82, 16, v173
	v_cvt_pk_bf16_f32 v91, v80, v81
	v_lshlrev_b32_e32 v80, 16, v172
	v_and_b32_e32 v81, 0xffff0000, v172
	v_and_b32_e32 v83, 0xffff0000, v173
	v_pk_add_f32 v[80:81], v[84:85], v[80:81]
	v_pk_add_f32 v[82:83], v[86:87], v[82:83]
	v_cvt_pk_bf16_f32 v80, v80, v81
	v_cvt_pk_bf16_f32 v81, v82, v83
	v_lshlrev_b32_e32 v82, 16, v174
	v_and_b32_e32 v83, 0xffff0000, v174
	v_pk_add_f32 v[76:77], v[76:77], v[82:83]
	v_lshl_add_u64 v[92:93], s[88:89], 0, v[220:221]
	v_cvt_pk_bf16_f32 v82, v76, v77
	v_lshlrev_b32_e32 v76, 16, v175
	v_and_b32_e32 v77, 0xffff0000, v175
	v_pk_add_f32 v[76:77], v[78:79], v[76:77]
	v_lshlrev_b32_e32 v78, 16, v164
	v_and_b32_e32 v79, 0xffff0000, v164
	v_pk_add_f32 v[72:73], v[72:73], v[78:79]
	v_lshlrev_b32_e32 v78, 16, v165
	v_and_b32_e32 v79, 0xffff0000, v165
	v_pk_add_f32 v[74:75], v[74:75], v[78:79]
	v_cvt_pk_bf16_f32 v72, v72, v73
	v_cvt_pk_bf16_f32 v73, v74, v75
	v_lshlrev_b32_e32 v74, 16, v166
	v_and_b32_e32 v75, 0xffff0000, v166
	v_pk_add_f32 v[68:69], v[68:69], v[74:75]
	v_cvt_pk_bf16_f32 v83, v76, v77
	v_cvt_pk_bf16_f32 v74, v68, v69
	v_lshlrev_b32_e32 v68, 16, v167
	v_and_b32_e32 v69, 0xffff0000, v167
	v_pk_add_f32 v[68:69], v[70:71], v[68:69]
	v_lshl_add_u64 v[76:77], s[88:89], 0, v[212:213]
	v_cvt_pk_bf16_f32 v75, v68, v69
	v_lshlrev_b32_e32 v68, 16, v160
	v_and_b32_e32 v69, 0xffff0000, v160
	v_pk_add_f32 v[64:65], v[64:65], v[68:69]
	v_lshlrev_b32_e32 v68, 16, v161
	v_and_b32_e32 v69, 0xffff0000, v161
	v_pk_add_f32 v[66:67], v[66:67], v[68:69]
	v_cvt_pk_bf16_f32 v64, v64, v65
	v_cvt_pk_bf16_f32 v65, v66, v67
	v_lshlrev_b32_e32 v66, 16, v162
	v_and_b32_e32 v67, 0xffff0000, v162
	v_pk_add_f32 v[60:61], v[60:61], v[66:67]
	v_lshl_add_u64 v[108:109], v[108:109], 0, v[202:203]
	v_cvt_pk_bf16_f32 v66, v60, v61
	v_lshlrev_b32_e32 v60, 16, v163
; __device__ __forceinline__ unsigned cvt_pk_bf16(float lo, float hi) { const f32x2 v = {lo, hi}; const bf16v2_ r = __builtin_convertvector(v, bf16v2_); return __builtin_bit_cast(unsigned, r); }
; __device__ __forceinline__ float bflo(unsigned w) { return __uint_as_float(w << 16); }
; __device__ __forceinline__ float bfhi(unsigned w) { return __uint_as_float(w & 0xffff0000u); }
; #define PG8_WAIT_V(n) asm volatile("s_waitcnt vmcnt(" #n ")" ::: "memory")
; #define PG8_BAR __builtin_amdgcn_s_barrier()
;     __device__ __forceinline__ void operator()(const f32x4 (&acc)[2][2][4][2], const Unit& u, int wr, int wc, int, int) const {
;     ...
;                 for (int bj = 0; bj < 2; ++bj) { const u32x4 c = cin[ai][m][bj]; const f32x4 v0 = acc[ai][bj][m][0], v1 = acc[ai][bj][m][1];
;                     u32x4 w; w.x = cvt_pk_bf16(bflo(c.x) + v0[0], bfhi(c.x) + v0[1]); w.y = cvt_pk_bf16(bflo(c.y) + v0[2], bfhi(c.y) + v0[3]);
;                     w.z = cvt_pk_bf16(bflo(c.z) + v1[0], bfhi(c.z) + v1[1]); w.w = cvt_pk_bf16(bflo(c.w) + v1[2], bfhi(c.w) + v1[3]);
;                     *(u32x4*)(C + (size_t)(row0 + ai * HALF + m * 16) * ldc + col0 + bj * HALF) = w; }
; template <class Epi, class Sched>
; __device__ __forceinline__ void gemm_phase(LAS unsigned char* lds, const Gemm g, const Sched& S, const Epi& E) {
;     ...
;         S.done(cur);
;         if (!has_next) break;
; #pragma unroll
;         for (int a = 0; a < 2; ++a)
; #pragma unroll
;             for (int b = 0; b < 2; ++b)
; #pragma unroll
;                 for (int m = 0; m < 4; ++m)
; #pragma unroll
;                     for (int n = 0; n < 2; ++n) acc[a][b][m][n] = (f32x4){0.f, 0.f, 0.f, 0.f};
;         cur = nxt; cA = nA; cB = nB; ++ui;
;     }
;     PG8_WAIT_V(0);
;     if (wr == 0) PG8_BAR;
;     PG8_BAR;
	v_and_b32_e32 v61, 0xffff0000, v163
	v_pk_add_f32 v[60:61], v[62:63], v[60:61]
	v_lshlrev_b32_e32 v62, 16, v156
	v_and_b32_e32 v63, 0xffff0000, v156
	v_pk_add_f32 v[56:57], v[56:57], v[62:63]
	v_lshlrev_b32_e32 v62, 16, v157
	v_and_b32_e32 v63, 0xffff0000, v157
	v_pk_add_f32 v[58:59], v[58:59], v[62:63]
	v_cvt_pk_bf16_f32 v56, v56, v57
	v_cvt_pk_bf16_f32 v57, v58, v59
	v_lshlrev_b32_e32 v58, 16, v158
	v_and_b32_e32 v59, 0xffff0000, v158
	v_pk_add_f32 v[48:49], v[48:49], v[58:59]
	v_cvt_pk_bf16_f32 v67, v60, v61
	v_cvt_pk_bf16_f32 v58, v48, v49
	v_lshlrev_b32_e32 v48, 16, v159
	v_and_b32_e32 v49, 0xffff0000, v159
	v_pk_add_f32 v[48:49], v[50:51], v[48:49]
	v_lshlrev_b32_e32 v50, 16, v153
	v_cvt_pk_bf16_f32 v59, v48, v49
	v_lshlrev_b32_e32 v48, 16, v152
	v_and_b32_e32 v49, 0xffff0000, v152
	v_and_b32_e32 v51, 0xffff0000, v153
	v_pk_add_f32 v[48:49], v[52:53], v[48:49]
	v_pk_add_f32 v[50:51], v[54:55], v[50:51]
	v_cvt_pk_bf16_f32 v48, v48, v49
	v_cvt_pk_bf16_f32 v49, v50, v51
	v_lshlrev_b32_e32 v50, 16, v154
	v_and_b32_e32 v51, 0xffff0000, v154
	v_pk_add_f32 v[44:45], v[44:45], v[50:51]
	v_lshl_add_u64 v[60:61], s[88:89], 0, v[210:211]
	v_cvt_pk_bf16_f32 v50, v44, v45
	v_lshlrev_b32_e32 v44, 16, v155
	v_and_b32_e32 v45, 0xffff0000, v155
	v_pk_add_f32 v[44:45], v[46:47], v[44:45]
	v_lshlrev_b32_e32 v46, 16, v148
	v_and_b32_e32 v47, 0xffff0000, v148
	v_pk_add_f32 v[40:41], v[40:41], v[46:47]
	v_lshlrev_b32_e32 v46, 16, v149
	v_and_b32_e32 v47, 0xffff0000, v149
	v_pk_add_f32 v[42:43], v[42:43], v[46:47]
	v_cvt_pk_bf16_f32 v40, v40, v41
	v_cvt_pk_bf16_f32 v41, v42, v43
	v_lshlrev_b32_e32 v42, 16, v150
	v_and_b32_e32 v43, 0xffff0000, v150
	v_pk_add_f32 v[32:33], v[32:33], v[42:43]
	v_cvt_pk_bf16_f32 v51, v44, v45
	v_cvt_pk_bf16_f32 v42, v32, v33
	v_lshlrev_b32_e32 v32, 16, v151
	v_and_b32_e32 v33, 0xffff0000, v151
	v_pk_add_f32 v[32:33], v[34:35], v[32:33]
	v_lshlrev_b32_e32 v34, 16, v145
	v_cvt_pk_bf16_f32 v43, v32, v33
	v_lshlrev_b32_e32 v32, 16, v144
	v_and_b32_e32 v33, 0xffff0000, v144
	v_and_b32_e32 v35, 0xffff0000, v145
	v_pk_add_f32 v[32:33], v[36:37], v[32:33]
	v_pk_add_f32 v[34:35], v[38:39], v[34:35]
	v_cvt_pk_bf16_f32 v32, v32, v33
	v_cvt_pk_bf16_f32 v33, v34, v35
	v_lshlrev_b32_e32 v34, 16, v146
	v_and_b32_e32 v35, 0xffff0000, v146
	v_pk_add_f32 v[28:29], v[28:29], v[34:35]
	v_lshl_add_u64 v[44:45], s[88:89], 0, v[208:209]
	v_cvt_pk_bf16_f32 v34, v28, v29
	v_lshlrev_b32_e32 v28, 16, v147
	v_and_b32_e32 v29, 0xffff0000, v147
	v_pk_add_f32 v[28:29], v[30:31], v[28:29]
	v_lshlrev_b32_e32 v30, 16, v140
	v_and_b32_e32 v31, 0xffff0000, v140
	v_pk_add_f32 v[24:25], v[24:25], v[30:31]
	v_lshlrev_b32_e32 v30, 16, v141
	v_and_b32_e32 v31, 0xffff0000, v141
	v_pk_add_f32 v[26:27], v[26:27], v[30:31]
	v_cvt_pk_bf16_f32 v24, v24, v25
	v_cvt_pk_bf16_f32 v25, v26, v27
	v_lshlrev_b32_e32 v26, 16, v142
	v_and_b32_e32 v27, 0xffff0000, v142
	v_pk_add_f32 v[16:17], v[16:17], v[26:27]
	v_cvt_pk_bf16_f32 v35, v28, v29
	v_cvt_pk_bf16_f32 v26, v16, v17
	v_lshlrev_b32_e32 v16, 16, v143
	v_and_b32_e32 v17, 0xffff0000, v143
	v_pk_add_f32 v[16:17], v[18:19], v[16:17]
	v_lshlrev_b32_e32 v18, 16, v137
	v_cvt_pk_bf16_f32 v27, v16, v17
	v_lshlrev_b32_e32 v16, 16, v136
	v_and_b32_e32 v17, 0xffff0000, v136
	v_and_b32_e32 v19, 0xffff0000, v137
	v_pk_add_f32 v[16:17], v[20:21], v[16:17]
	v_pk_add_f32 v[18:19], v[22:23], v[18:19]
	v_cvt_pk_bf16_f32 v16, v16, v17
	v_cvt_pk_bf16_f32 v17, v18, v19
	v_lshlrev_b32_e32 v18, 16, v138
	v_and_b32_e32 v19, 0xffff0000, v138
	v_pk_add_f32 v[12:13], v[12:13], v[18:19]
	v_lshl_add_u64 v[28:29], s[88:89], 0, v[206:207]
	v_cvt_pk_bf16_f32 v18, v12, v13
	v_lshlrev_b32_e32 v12, 16, v139
	v_and_b32_e32 v13, 0xffff0000, v139
	v_pk_add_f32 v[12:13], v[14:15], v[12:13]
	v_lshlrev_b32_e32 v14, 16, v132
	v_and_b32_e32 v15, 0xffff0000, v132
	v_pk_add_f32 v[8:9], v[8:9], v[14:15]
	v_lshlrev_b32_e32 v14, 16, v133
	v_and_b32_e32 v15, 0xffff0000, v133
	v_pk_add_f32 v[10:11], v[10:11], v[14:15]
	v_cvt_pk_bf16_f32 v8, v8, v9
	v_cvt_pk_bf16_f32 v9, v10, v11
	v_lshlrev_b32_e32 v10, 16, v134
	v_and_b32_e32 v11, 0xffff0000, v134
	v_pk_add_f32 v[4:5], v[4:5], v[10:11]
	v_cvt_pk_bf16_f32 v19, v12, v13
	v_cvt_pk_bf16_f32 v10, v4, v5
	v_lshlrev_b32_e32 v4, 16, v135
	v_and_b32_e32 v5, 0xffff0000, v135
	v_lshl_add_u64 v[12:13], s[88:89], 0, v[204:205]
	v_pk_add_f32 v[4:5], v[6:7], v[4:5]
	v_lshl_add_u64 v[92:93], v[92:93], 0, v[202:203]
	v_lshl_add_u64 v[76:77], v[76:77], 0, v[202:203]
	v_lshl_add_u64 v[60:61], v[60:61], 0, v[202:203]
	v_lshl_add_u64 v[44:45], v[44:45], 0, v[202:203]
	v_lshl_add_u64 v[28:29], v[28:29], 0, v[202:203]
	v_lshl_add_u64 v[12:13], v[12:13], 0, v[202:203]
	v_cvt_pk_bf16_f32 v11, v4, v5
	global_store_dwordx4 v[124:125], v[128:131], off
	global_store_dwordx4 v[124:125], v[120:123], off offset:256
	global_store_dwordx4 v[108:109], v[112:115], off
	global_store_dwordx4 v[108:109], v[104:107], off offset:256
	global_store_dwordx4 v[92:93], v[96:99], off
	global_store_dwordx4 v[92:93], v[88:91], off offset:256
	global_store_dwordx4 v[76:77], v[80:83], off
	global_store_dwordx4 v[76:77], v[72:75], off offset:256
	global_store_dwordx4 v[60:61], v[64:67], off
	global_store_dwordx4 v[60:61], v[56:59], off offset:256
	global_store_dwordx4 v[44:45], v[48:51], off
	global_store_dwordx4 v[44:45], v[40:43], off offset:256
	global_store_dwordx4 v[28:29], v[32:35], off
	global_store_dwordx4 v[28:29], v[24:27], off offset:256
	global_store_dwordx4 v[12:13], v[16:19], off
	global_store_dwordx4 v[12:13], v[8:11], off offset:256
	s_cbranch_vccz .LBB0_1389
	s_waitcnt vmcnt(0)
	s_cmpk_gt_u32 s2, 0xff
	s_cbranch_scc1 .LBB0_1400
	s_barrier

; #define PG8_STAGE(bufoff, gbase, voff) do { _Pragma("unroll") for (int _i = 0; _i < 2; ++_i) \
;         __builtin_amdgcn_global_load_lds((const unsigned*)((const char*)(gbase) + (voff)[_i]), (LAS unsigned*)(lds + (bufoff) + ldsw + _i * 8192), 16, 0, 0); } while (0)
; #define PG8_LDA(dst, b, h) do { _Pragma("unroll") for (int m = 0; m < 4; ++m) _Pragma("unroll") for (int k = 0; k < 2; ++k) dst[m][k] = *(const LAS bf16x8*)(lds + PG8_SA(b, h) + aoff + m * 2048 + k * 1024); } while (0)
; #define PG8_LDB(dst, b, h) do { _Pragma("unroll") for (int n = 0; n < 2; ++n) _Pragma("unroll") for (int k = 0; k < 2; ++k) dst[n][k] = *(const LAS bf16x8*)(lds + PG8_SB(b, h) + boff + n * 2048 + k * 1024); } while (0)
; #define PG8_MMA(ai, bj, At, Bt) do { __builtin_amdgcn_s_setprio(1); _Pragma("unroll") for (int m = 0; m < 4; ++m) _Pragma("unroll") for (int n = 0; n < 2; ++n) _Pragma("unroll") for (int k = 0; k < 2; ++k) \
;         acc[ai][bj][m][n] = __builtin_amdgcn_mfma_f32_16x16x32_bf16(Bt[n][k], At[m][k], acc[ai][bj][m][n], 0, 0, 0); __builtin_amdgcn_s_setprio(0); } while (0)
; #define PG8_WAIT_V(n) asm volatile("s_waitcnt vmcnt(" #n ")" ::: "memory")
; #define PG8_WAIT_L(n) asm volatile("s_waitcnt lgkmcnt(" #n ")" ::: "memory")
; #define PG8_BAR __builtin_amdgcn_s_barrier()
; #define PG8_SCHED __builtin_amdgcn_sched_barrier(0)
; template <class Epi, class Sched>
; __device__ __forceinline__ void gemm_phase(LAS unsigned char* lds, const Gemm g, const Sched& S, const Epi& E) {
;     ...
;             PG8_LDB(B0, 0, 0); PG8_SCHED; PG8_LDA(At, 0, 0); PG8_STAGE(PG8_SA(1, 1), a1 + hstepA, voffA);
;             PG8_WAIT_L(8); PG8_BAR; PG8_WAIT_L(0); PG8_MMA(0, 0, At, B0); PG8_BAR; PG8_SCHED;
;             PG8_LDB(B1, 0, 1); PG8_STAGE(PG8_SB(0, 0), b2, voffB);
;             PG8_BAR; PG8_WAIT_L(0); PG8_MMA(0, 1, At, B1); PG8_BAR;
;             PG8_LDA(At, 0, 1); PG8_STAGE(PG8_SA(0, 0), a2, voffA);
;             PG8_BAR; PG8_WAIT_L(0); PG8_MMA(1, 0, At, B0); PG8_BAR; PG8_SCHED;
;             PG8_STAGE(PG8_SB(0, 1), b2 + hstepB, voffB);
;             PG8_WAIT_V(6); PG8_BAR; PG8_MMA(1, 1, At, B1); PG8_BAR;
.LBB0_1526:
	s_add_u32 s6, s4, 0xfff80080
	s_addc_u32 s7, s5, -1
	s_add_i32 s72, 0, 0x10000
	v_add_u32_e32 v2, s72, v1
	ds_read_b128 v[132:135], v2
	ds_read_b128 v[136:139], v2 offset:1024
	ds_read_b128 v[140:143], v2 offset:2048
	ds_read_b128 v[144:147], v2 offset:3072
	s_cmp_eq_u32 s71, 28
	s_cselect_b32 s15, s57, s7
	s_cselect_b32 s14, s67, s6
	s_cselect_b32 s7, s55, s70
	s_cselect_b32 s6, s68, s69
	ds_read_b128 v[148:151], v207
	ds_read_b128 v[152:155], v207 offset:1024
	ds_read_b128 v[156:159], v207 offset:2048
	ds_read_b128 v[160:163], v207 offset:3072
	ds_read_b128 v[164:167], v207 offset:4096
	ds_read_b128 v[168:171], v207 offset:5120
	ds_read_b128 v[186:189], v207 offset:6144
	ds_read_b128 v[190:193], v207 offset:7168
	s_add_i32 s74, 0, 0x14000
	v_add_u32_e32 v2, s74, v1
	ds_read_b128 v[194:197], v2
	ds_read_b128 v[198:201], v2 offset:1024
	ds_read_b128 v[202:205], v2 offset:2048
	ds_read_b128 v[208:211], v2 offset:3072
	s_add_i32 m0, s20, 0xc000
	s_nop 0
	global_load_lds_dwordx4 v182, s[4:5]
	s_add_i32 m0, s20, 0xe000
	s_nop 0
	global_load_lds_dwordx4 v184, s[4:5]
	s_waitcnt lgkmcnt(0)
	s_barrier
	s_setprio 1
	v_mfma_f32_16x16x32_bf16 v[68:71], v[132:135], v[148:151], v[68:71]
	v_mfma_f32_16x16x32_bf16 v[72:75], v[140:143], v[148:151], v[72:75]
	v_mfma_f32_16x16x32_bf16 v[120:123], v[132:135], v[156:159], v[120:123]
	v_mfma_f32_16x16x32_bf16 v[116:119], v[140:143], v[156:159], v[116:119]
	v_mfma_f32_16x16x32_bf16 v[112:115], v[132:135], v[164:167], v[112:115]
	v_mfma_f32_16x16x32_bf16 v[108:111], v[140:143], v[164:167], v[108:111]
	v_mfma_f32_16x16x32_bf16 v[104:107], v[132:135], v[186:189], v[104:107]
	v_mfma_f32_16x16x32_bf16 v[100:103], v[140:143], v[186:189], v[100:103]
	v_mfma_f32_16x16x32_bf16 v[68:71], v[136:139], v[152:155], v[68:71]
	v_mfma_f32_16x16x32_bf16 v[72:75], v[144:147], v[152:155], v[72:75]
	v_mfma_f32_16x16x32_bf16 v[120:123], v[136:139], v[160:163], v[120:123]
	v_mfma_f32_16x16x32_bf16 v[116:119], v[144:147], v[160:163], v[116:119]
	v_mfma_f32_16x16x32_bf16 v[112:115], v[136:139], v[168:171], v[112:115]
	v_mfma_f32_16x16x32_bf16 v[108:111], v[144:147], v[168:171], v[108:111]
	v_mfma_f32_16x16x32_bf16 v[104:107], v[136:139], v[190:193], v[104:107]
	v_mfma_f32_16x16x32_bf16 v[100:103], v[144:147], v[190:193], v[100:103]
	v_mfma_f32_16x16x32_bf16 v[76:79], v[194:197], v[148:151], v[76:79]
	v_mfma_f32_16x16x32_bf16 v[80:83], v[202:205], v[148:151], v[80:83]
	v_mfma_f32_16x16x32_bf16 v[96:99], v[194:197], v[156:159], v[96:99]
	v_mfma_f32_16x16x32_bf16 v[92:95], v[202:205], v[156:159], v[92:95]
	v_mfma_f32_16x16x32_bf16 v[88:91], v[194:197], v[164:167], v[88:91]
	v_mfma_f32_16x16x32_bf16 v[84:87], v[202:205], v[164:167], v[84:87]
	v_mfma_f32_16x16x32_bf16 v[128:131], v[194:197], v[186:189], v[128:131]
	v_mfma_f32_16x16x32_bf16 v[124:127], v[202:205], v[186:189], v[124:127]
	v_mfma_f32_16x16x32_bf16 v[76:79], v[198:201], v[152:155], v[76:79]
	v_mfma_f32_16x16x32_bf16 v[80:83], v[208:211], v[152:155], v[80:83]
	v_mfma_f32_16x16x32_bf16 v[96:99], v[198:201], v[160:163], v[96:99]
	v_mfma_f32_16x16x32_bf16 v[92:95], v[208:211], v[160:163], v[92:95]
	v_mfma_f32_16x16x32_bf16 v[88:91], v[198:201], v[168:171], v[88:91]
	v_mfma_f32_16x16x32_bf16 v[84:87], v[208:211], v[168:171], v[84:87]
	v_mfma_f32_16x16x32_bf16 v[128:131], v[198:201], v[190:193], v[128:131]
	v_mfma_f32_16x16x32_bf16 v[124:127], v[208:211], v[190:193], v[124:127]
	s_setprio 0
	s_barrier
	ds_read_b128 v[148:151], v207 offset:16384
	ds_read_b128 v[152:155], v207 offset:17408
	ds_read_b128 v[156:159], v207 offset:18432
	ds_read_b128 v[160:163], v207 offset:19456
	ds_read_b128 v[164:167], v207 offset:20480
	ds_read_b128 v[168:171], v207 offset:21504
	ds_read_b128 v[186:189], v207 offset:22528
	ds_read_b128 v[190:193], v207 offset:23552
	s_add_i32 s72, s72, s19
	v_lshl_add_u64 v[172:173], s[6:7], 0, v[178:179]
	s_mov_b32 m0, s72
	s_nop 0
	global_load_lds_dwordx4 v[172:173], off
	v_lshl_add_u64 v[212:213], s[6:7], 0, v[174:175]
	s_add_i32 m0, s72, 0x2000
	s_nop 0
	global_load_lds_dwordx4 v[212:213], off
	s_mov_b32 m0, s20
	v_lshl_add_u64 v[216:217], s[14:15], 0, v[180:181]
	global_load_lds_dwordx4 v[216:217], off
	v_lshl_add_u64 v[218:219], s[14:15], 0, v[176:177]
	s_mov_b32 m0, s21
	s_nop 0
	global_load_lds_dwordx4 v[218:219], off
	s_add_u32 s72, s6, 0x80000
	s_addc_u32 s73, s7, 0
	s_add_i32 s74, s74, s19
	s_mov_b32 m0, s74
	s_nop 0
	global_load_lds_dwordx4 v178, s[72:73]
	s_add_i32 m0, s74, 0x2000
	s_nop 0
	global_load_lds_dwordx4 v174, s[72:73]
	s_waitcnt lgkmcnt(0)
	s_waitcnt vmcnt(6)
	s_barrier
; #define PG8_STAGE(bufoff, gbase, voff) do { _Pragma("unroll") for (int _i = 0; _i < 2; ++_i) \
;         __builtin_amdgcn_global_load_lds((const unsigned*)((const char*)(gbase) + (voff)[_i]), (LAS unsigned*)(lds + (bufoff) + ldsw + _i * 8192), 16, 0, 0); } while (0)
; #define PG8_LDA(dst, b, h) do { _Pragma("unroll") for (int m = 0; m < 4; ++m) _Pragma("unroll") for (int k = 0; k < 2; ++k) dst[m][k] = *(const LAS bf16x8*)(lds + PG8_SA(b, h) + aoff + m * 2048 + k * 1024); } while (0)
; #define PG8_LDB(dst, b, h) do { _Pragma("unroll") for (int n = 0; n < 2; ++n) _Pragma("unroll") for (int k = 0; k < 2; ++k) dst[n][k] = *(const LAS bf16x8*)(lds + PG8_SB(b, h) + boff + n * 2048 + k * 1024); } while (0)
; #define PG8_MMA(ai, bj, At, Bt) do { __builtin_amdgcn_s_setprio(1); _Pragma("unroll") for (int m = 0; m < 4; ++m) _Pragma("unroll") for (int n = 0; n < 2; ++n) _Pragma("unroll") for (int k = 0; k < 2; ++k) \
;         acc[ai][bj][m][n] = __builtin_amdgcn_mfma_f32_16x16x32_bf16(Bt[n][k], At[m][k], acc[ai][bj][m][n], 0, 0, 0); __builtin_amdgcn_s_setprio(0); } while (0)
; #define PG8_WAIT_V(n) asm volatile("s_waitcnt vmcnt(" #n ")" ::: "memory")
; #define PG8_WAIT_L(n) asm volatile("s_waitcnt lgkmcnt(" #n ")" ::: "memory")
; #define PG8_BAR __builtin_amdgcn_s_barrier()
; #define PG8_SCHED __builtin_amdgcn_sched_barrier(0)
; template <class Epi, class Sched>
; __device__ __forceinline__ void gemm_phase(LAS unsigned char* lds, const Gemm g, const Sched& S, const Epi& E) {
;     ...
;             PG8_WAIT_V(6); PG8_BAR; PG8_MMA(1, 1, At, B1); PG8_BAR;
;             PG8_LDB(B0, 1, 0); PG8_SCHED; PG8_LDA(At, 1, 0); PG8_STAGE(PG8_SA(0, 1), a2 + hstepA, voffA);
;             PG8_WAIT_L(8); PG8_BAR; PG8_WAIT_L(0); PG8_MMA(0, 0, At, B0); PG8_BAR; PG8_SCHED;
;             PG8_LDB(B1, 1, 1); PG8_STAGE(PG8_SB(1, 0), b3, voffB);
;             PG8_BAR; PG8_WAIT_L(0); PG8_MMA(0, 1, At, B1); PG8_BAR;
;             PG8_LDA(At, 1, 1); PG8_STAGE(PG8_SA(1, 0), a3, voffA);
;             PG8_BAR; PG8_WAIT_L(0); PG8_MMA(1, 0, At, B0); PG8_BAR; PG8_SCHED;
	s_setprio 1
	v_mfma_f32_16x16x32_bf16 v[56:59], v[132:135], v[148:151], v[56:59]
	v_mfma_f32_16x16x32_bf16 v[52:55], v[140:143], v[148:151], v[52:55]
	v_mfma_f32_16x16x32_bf16 v[48:51], v[132:135], v[156:159], v[48:51]
	v_mfma_f32_16x16x32_bf16 v[44:47], v[140:143], v[156:159], v[44:47]
	v_mfma_f32_16x16x32_bf16 v[40:43], v[132:135], v[164:167], v[40:43]
	v_mfma_f32_16x16x32_bf16 v[36:39], v[140:143], v[164:167], v[36:39]
	v_mfma_f32_16x16x32_bf16 v[32:35], v[132:135], v[186:189], v[32:35]
	v_mfma_f32_16x16x32_bf16 v[28:31], v[140:143], v[186:189], v[28:31]
	v_mfma_f32_16x16x32_bf16 v[56:59], v[136:139], v[152:155], v[56:59]
	v_mfma_f32_16x16x32_bf16 v[52:55], v[144:147], v[152:155], v[52:55]
	v_mfma_f32_16x16x32_bf16 v[48:51], v[136:139], v[160:163], v[48:51]
	v_mfma_f32_16x16x32_bf16 v[44:47], v[144:147], v[160:163], v[44:47]
	v_mfma_f32_16x16x32_bf16 v[40:43], v[136:139], v[168:171], v[40:43]
	v_mfma_f32_16x16x32_bf16 v[36:39], v[144:147], v[168:171], v[36:39]
	v_mfma_f32_16x16x32_bf16 v[32:35], v[136:139], v[190:193], v[32:35]
	v_mfma_f32_16x16x32_bf16 v[28:31], v[144:147], v[190:193], v[28:31]
	v_mfma_f32_16x16x32_bf16 v[24:27], v[194:197], v[148:151], v[24:27]
	v_mfma_f32_16x16x32_bf16 v[20:23], v[202:205], v[148:151], v[20:23]
	v_mfma_f32_16x16x32_bf16 v[16:19], v[194:197], v[156:159], v[16:19]
	v_mfma_f32_16x16x32_bf16 v[12:15], v[202:205], v[156:159], v[12:15]
	v_mfma_f32_16x16x32_bf16 v[8:11], v[194:197], v[164:167], v[8:11]
	v_mfma_f32_16x16x32_bf16 v[4:7], v[202:205], v[164:167], v[4:7]
	v_mfma_f32_16x16x32_bf16 v[60:63], v[194:197], v[186:189], v[60:63]
	v_mfma_f32_16x16x32_bf16 v[64:67], v[202:205], v[186:189], v[64:67]
	v_mfma_f32_16x16x32_bf16 v[24:27], v[198:201], v[152:155], v[24:27]
	v_mfma_f32_16x16x32_bf16 v[20:23], v[208:211], v[152:155], v[20:23]
	v_mfma_f32_16x16x32_bf16 v[16:19], v[198:201], v[160:163], v[16:19]
	v_mfma_f32_16x16x32_bf16 v[12:15], v[208:211], v[160:163], v[12:15]
	v_mfma_f32_16x16x32_bf16 v[8:11], v[198:201], v[168:171], v[8:11]
	v_mfma_f32_16x16x32_bf16 v[4:7], v[208:211], v[168:171], v[4:7]
	v_mfma_f32_16x16x32_bf16 v[60:63], v[198:201], v[190:193], v[60:63]
	v_mfma_f32_16x16x32_bf16 v[64:67], v[208:211], v[190:193], v[64:67]
	s_setprio 0
	s_add_i32 s72, 0, 0x18000
	v_add_u32_e32 v2, s72, v1
	s_barrier
	ds_read_b128 v[132:135], v2
	ds_read_b128 v[136:139], v2 offset:1024
	ds_read_b128 v[140:143], v2 offset:2048
	ds_read_b128 v[144:147], v2 offset:3072
	s_add_u32 s14, s14, 0x80000
	s_addc_u32 s15, s15, 0
	ds_read_b128 v[148:151], v207 offset:32768
	ds_read_b128 v[152:155], v207 offset:33792
	ds_read_b128 v[156:159], v207 offset:34816
	ds_read_b128 v[160:163], v207 offset:35840
	ds_read_b128 v[164:167], v207 offset:36864
	ds_read_b128 v[168:171], v207 offset:37888
	ds_read_b128 v[186:189], v207 offset:38912
	ds_read_b128 v[190:193], v207 offset:39936
	s_mov_b32 m0, s24
	s_nop 0
	global_load_lds_dwordx4 v180, s[14:15]
	s_mov_b32 m0, s25
	s_nop 0
	global_load_lds_dwordx4 v176, s[14:15]
	s_add_i32 s14, 0, 0x1c000
	v_add_u32_e32 v2, s14, v1
	ds_read_b128 v[194:197], v2
	ds_read_b128 v[198:201], v2 offset:1024
	ds_read_b128 v[202:205], v2 offset:2048
	ds_read_b128 v[208:211], v2 offset:3072
	s_waitcnt lgkmcnt(0)
	s_barrier
	s_setprio 1
	v_mfma_f32_16x16x32_bf16 v[68:71], v[132:135], v[148:151], v[68:71]
	v_mfma_f32_16x16x32_bf16 v[72:75], v[140:143], v[148:151], v[72:75]
	v_mfma_f32_16x16x32_bf16 v[120:123], v[132:135], v[156:159], v[120:123]
	v_mfma_f32_16x16x32_bf16 v[116:119], v[140:143], v[156:159], v[116:119]
	v_mfma_f32_16x16x32_bf16 v[112:115], v[132:135], v[164:167], v[112:115]
	v_mfma_f32_16x16x32_bf16 v[108:111], v[140:143], v[164:167], v[108:111]
	v_mfma_f32_16x16x32_bf16 v[104:107], v[132:135], v[186:189], v[104:107]
	v_mfma_f32_16x16x32_bf16 v[100:103], v[140:143], v[186:189], v[100:103]
	v_mfma_f32_16x16x32_bf16 v[68:71], v[136:139], v[152:155], v[68:71]
	v_mfma_f32_16x16x32_bf16 v[72:75], v[144:147], v[152:155], v[72:75]
	v_mfma_f32_16x16x32_bf16 v[120:123], v[136:139], v[160:163], v[120:123]
	v_mfma_f32_16x16x32_bf16 v[116:119], v[144:147], v[160:163], v[116:119]
	v_mfma_f32_16x16x32_bf16 v[112:115], v[136:139], v[168:171], v[112:115]
	v_mfma_f32_16x16x32_bf16 v[108:111], v[144:147], v[168:171], v[108:111]
	v_mfma_f32_16x16x32_bf16 v[104:107], v[136:139], v[190:193], v[104:107]
	v_mfma_f32_16x16x32_bf16 v[100:103], v[144:147], v[190:193], v[100:103]
	v_mfma_f32_16x16x32_bf16 v[76:79], v[194:197], v[148:151], v[76:79]
	v_mfma_f32_16x16x32_bf16 v[80:83], v[202:205], v[148:151], v[80:83]
	v_mfma_f32_16x16x32_bf16 v[96:99], v[194:197], v[156:159], v[96:99]
	v_mfma_f32_16x16x32_bf16 v[92:95], v[202:205], v[156:159], v[92:95]
	v_mfma_f32_16x16x32_bf16 v[88:91], v[194:197], v[164:167], v[88:91]
	v_mfma_f32_16x16x32_bf16 v[84:87], v[202:205], v[164:167], v[84:87]
	v_mfma_f32_16x16x32_bf16 v[128:131], v[194:197], v[186:189], v[128:131]
	v_mfma_f32_16x16x32_bf16 v[124:127], v[202:205], v[186:189], v[124:127]
	v_mfma_f32_16x16x32_bf16 v[76:79], v[198:201], v[152:155], v[76:79]
	v_mfma_f32_16x16x32_bf16 v[80:83], v[208:211], v[152:155], v[80:83]
	v_mfma_f32_16x16x32_bf16 v[96:99], v[198:201], v[160:163], v[96:99]
	v_mfma_f32_16x16x32_bf16 v[92:95], v[208:211], v[160:163], v[92:95]
	v_mfma_f32_16x16x32_bf16 v[88:91], v[198:201], v[168:171], v[88:91]
	v_mfma_f32_16x16x32_bf16 v[84:87], v[208:211], v[168:171], v[84:87]
	v_mfma_f32_16x16x32_bf16 v[128:131], v[198:201], v[190:193], v[128:131]
	v_mfma_f32_16x16x32_bf16 v[124:127], v[208:211], v[190:193], v[124:127]
	s_setprio 0
	s_barrier
; #define LAS __attribute__((address_space(3)))
; __device__ __forceinline__ int opaque_tid() { int t = threadIdx.x; asm volatile("" : "+v"(t)); return t; }
; #define PG8_STAGE(bufoff, gbase, voff) do { _Pragma("unroll") for (int _i = 0; _i < 2; ++_i) \
;         __builtin_amdgcn_global_load_lds((const unsigned*)((const char*)(gbase) + (voff)[_i]), (LAS unsigned*)(lds + (bufoff) + ldsw + _i * 8192), 16, 0, 0); } while (0)
; #define PG8_LDA(dst, b, h) do { _Pragma("unroll") for (int m = 0; m < 4; ++m) _Pragma("unroll") for (int k = 0; k < 2; ++k) dst[m][k] = *(const LAS bf16x8*)(lds + PG8_SA(b, h) + aoff + m * 2048 + k * 1024); } while (0)
; #define PG8_WAIT_V(n) asm volatile("s_waitcnt vmcnt(" #n ")" ::: "memory")
; #define PG8_WAIT_L(n) asm volatile("s_waitcnt lgkmcnt(" #n ")" ::: "memory")
; #define PG8_BAR __builtin_amdgcn_s_barrier()
; #define PG8_SCHED __builtin_amdgcn_sched_barrier(0)
;     __device__ __forceinline__ void operator()(f32x4 (&acc)[2][2][4][2], const Unit& u, int wr, int wc, int ui, int) const {
;         const int ol_ = opaque_tid() & 63, fr = ol_ & 15, fq = ol_ >> 4;
;         { float r_[2][4];
;           rs_read(r_, ui, wr, fr);
; #pragma unroll
;           for (int ai = 0; ai < 2; ++ai)
; #pragma unroll
;               for (int bj = 0; bj < 2; ++bj)
; #pragma unroll
;                   for (int m = 0; m < 4; ++m) { acc[ai][bj][m][0] *= r_[ai][m]; acc[ai][bj][m][1] *= r_[ai][m]; } }
;         const int col = u.pn * 128 + wc * 32 + 8 * fq;
;         if (fr >= 14) {
; #pragma unroll
;             for (int ai = 0; ai < 2; ++ai) { LAS f32x4* s = (LAS f32x4*)(hl + ((((ai * 2 + wr) * 4 + wc) * 8 + fq * 2 + (fr - 14)) * 32));
;                 s[0] = acc[ai][1][3][0]; s[1] = acc[ai][1][3][1]; }
;         }
; template <class Epi, class Sched>
; __device__ __forceinline__ void gemm_phase(LAS unsigned char* lds, const Gemm g, const Sched& S, const Epi& E) {
;     ...
;             PG8_LDA(At, 1, 1); PG8_STAGE(PG8_SA(1, 0), a3, voffA);
;             PG8_BAR; PG8_WAIT_L(0); PG8_MMA(1, 0, At, B0); PG8_BAR; PG8_SCHED;
;             PG8_STAGE(PG8_SB(1, 1), b3 + hstepB, voffB);
;             PG8_WAIT_V(6); PG8_BAR; PG8_MMA(1, 1, At, B1); PG8_BAR;
;         }
;         E(acc, cur, wr, wc, ui, fq);
;         S.done(cur);
;         if (!has_next) break;
	ds_read_b128 v[148:151], v207 offset:49152
	ds_read_b128 v[152:155], v207 offset:50176
	ds_read_b128 v[156:159], v207 offset:51200
	ds_read_b128 v[160:163], v207 offset:52224
	ds_read_b128 v[164:167], v207 offset:53248
	ds_read_b128 v[168:171], v207 offset:54272
	ds_read_b128 v[186:189], v207 offset:55296
	ds_read_b128 v[190:193], v207 offset:56320
	s_add_i32 s15, s72, s19
	v_lshl_add_u64 v[172:173], v[172:173], 0, s[8:9]
	s_mov_b32 m0, s15
	s_nop 0
	global_load_lds_dwordx4 v[172:173], off
	v_lshl_add_u64 v[172:173], v[212:213], 0, s[8:9]
	s_add_i32 m0, s15, 0x2000
	s_nop 0
	global_load_lds_dwordx4 v[172:173], off
	s_mov_b32 m0, s30
	v_lshl_add_u64 v[172:173], v[216:217], 0, s[8:9]
	global_load_lds_dwordx4 v[172:173], off
	v_lshl_add_u64 v[172:173], v[218:219], 0, s[8:9]
	s_mov_b32 m0, s31
	s_nop 0
	global_load_lds_dwordx4 v[172:173], off
	s_add_u32 s6, s6, 0x80080
	s_addc_u32 s7, s7, 0
	s_add_i32 s14, s14, s19
	s_mov_b32 m0, s14
	s_nop 0
	global_load_lds_dwordx4 v178, s[6:7]
	s_add_i32 m0, s14, 0x2000
	s_nop 0
	global_load_lds_dwordx4 v174, s[6:7]
	s_waitcnt lgkmcnt(0)
	s_waitcnt vmcnt(6)
	s_barrier
	s_setprio 1
	v_mfma_f32_16x16x32_bf16 v[56:59], v[132:135], v[148:151], v[56:59]
	v_mfma_f32_16x16x32_bf16 v[52:55], v[140:143], v[148:151], v[52:55]
	v_mfma_f32_16x16x32_bf16 v[48:51], v[132:135], v[156:159], v[48:51]
	v_mfma_f32_16x16x32_bf16 v[44:47], v[140:143], v[156:159], v[44:47]
	v_mfma_f32_16x16x32_bf16 v[40:43], v[132:135], v[164:167], v[40:43]
	v_mfma_f32_16x16x32_bf16 v[36:39], v[140:143], v[164:167], v[36:39]
	v_mfma_f32_16x16x32_bf16 v[32:35], v[132:135], v[186:189], v[32:35]
	v_mfma_f32_16x16x32_bf16 v[28:31], v[140:143], v[186:189], v[28:31]
	v_mfma_f32_16x16x32_bf16 v[56:59], v[136:139], v[152:155], v[56:59]
	v_mfma_f32_16x16x32_bf16 v[52:55], v[144:147], v[152:155], v[52:55]
	v_mfma_f32_16x16x32_bf16 v[48:51], v[136:139], v[160:163], v[48:51]
	v_mfma_f32_16x16x32_bf16 v[44:47], v[144:147], v[160:163], v[44:47]
	v_mfma_f32_16x16x32_bf16 v[40:43], v[136:139], v[168:171], v[40:43]
	v_mfma_f32_16x16x32_bf16 v[36:39], v[144:147], v[168:171], v[36:39]
	v_mfma_f32_16x16x32_bf16 v[32:35], v[136:139], v[190:193], v[32:35]
	v_mfma_f32_16x16x32_bf16 v[28:31], v[144:147], v[190:193], v[28:31]
	v_mfma_f32_16x16x32_bf16 v[24:27], v[194:197], v[148:151], v[24:27]
	v_mfma_f32_16x16x32_bf16 v[20:23], v[202:205], v[148:151], v[20:23]
	v_mfma_f32_16x16x32_bf16 v[16:19], v[194:197], v[156:159], v[16:19]
	v_mfma_f32_16x16x32_bf16 v[12:15], v[202:205], v[156:159], v[12:15]
	v_mfma_f32_16x16x32_bf16 v[8:11], v[194:197], v[164:167], v[8:11]
	v_mfma_f32_16x16x32_bf16 v[4:7], v[202:205], v[164:167], v[4:7]
	v_mfma_f32_16x16x32_bf16 v[60:63], v[194:197], v[186:189], v[60:63]
	v_mfma_f32_16x16x32_bf16 v[64:67], v[202:205], v[186:189], v[64:67]
	v_mfma_f32_16x16x32_bf16 v[24:27], v[198:201], v[152:155], v[24:27]
	v_mfma_f32_16x16x32_bf16 v[20:23], v[208:211], v[152:155], v[20:23]
	v_mfma_f32_16x16x32_bf16 v[16:19], v[198:201], v[160:163], v[16:19]
	v_mfma_f32_16x16x32_bf16 v[12:15], v[208:211], v[160:163], v[12:15]
	v_mfma_f32_16x16x32_bf16 v[8:11], v[198:201], v[168:171], v[8:11]
	v_mfma_f32_16x16x32_bf16 v[4:7], v[208:211], v[168:171], v[4:7]
	v_mfma_f32_16x16x32_bf16 v[60:63], v[198:201], v[190:193], v[60:63]
	v_mfma_f32_16x16x32_bf16 v[64:67], v[208:211], v[190:193], v[64:67]
	s_setprio 0
	s_add_i32 s71, s71, 2
	s_add_u32 s4, s4, 0x100
	s_addc_u32 s5, s5, 0
	s_add_u32 s69, s69, 0x100
	s_addc_u32 s70, s70, 0
	s_cmp_gt_u32 s71, 29
	s_barrier
	s_cbranch_scc0 .LBB0_1526
	s_lshl_b32 s4, s66, 10
	v_mov_b32_e32 v134, v0
	s_and_b32 s4, s4, 0x400
	s_add_i32 s4, s35, s4
	v_and_b32_e32 v210, 15, v134
	v_lshl_add_u32 v2, v210, 2, s4
	ds_read2_b32 v[204:205], v2 offset1:16
	ds_read2_b32 v[202:203], v2 offset0:32 offset1:48
	ds_read2_b32 v[198:199], v2 offset0:128 offset1:144
	ds_read2_b32 v[196:197], v2 offset0:160 offset1:176
	v_cmp_lt_u32_e32 vcc, 13, v210
	s_waitcnt lgkmcnt(0)
	v_mov_b32_e32 v206, v205
	v_mov_b32_e32 v208, v203
	v_mov_b32_e32 v2, v199
	v_mov_b32_e32 v200, v197
	v_pk_mul_f32 v[132:133], v[130:131], v[208:209] op_sel_hi:[1,0]
	v_pk_mul_f32 v[130:131], v[128:129], v[208:209] op_sel_hi:[1,0]
	v_pk_mul_f32 v[128:129], v[126:127], v[208:209] op_sel_hi:[1,0]
	v_pk_mul_f32 v[126:127], v[124:125], v[208:209] op_sel_hi:[1,0]
	v_pk_mul_f32 v[62:63], v[62:63], v[200:201] op_sel_hi:[1,0]
	v_pk_mul_f32 v[60:61], v[60:61], v[200:201] op_sel_hi:[1,0]
	v_pk_mul_f32 v[66:67], v[66:67], v[200:201] op_sel_hi:[1,0]
	v_pk_mul_f32 v[64:65], v[64:65], v[200:201] op_sel_hi:[1,0]
	v_bfe_u32 v125, v134, 4, 2
	s_and_saveexec_b64 s[4:5], vcc
	s_cbranch_execz .LBB0_1529
	v_lshlrev_b32_e32 v124, 1, v125
	v_add3_u32 v124, v210, v124, -14
	v_add_u32_e32 v134, s39, v124
	v_add_u32_e32 v124, s38, v124
	v_lshl_add_u32 v124, v124, 5, s62
	v_lshl_add_u32 v134, v134, 5, s62
	ds_write_b128 v124, v[130:133]
	ds_write_b128 v124, v[126:129] offset:16
	ds_write_b128 v134, v[60:63]
	ds_write_b128 v134, v[64:67] offset:16

; #define PG8_STAGE(bufoff, gbase, voff) do { _Pragma("unroll") for (int _i = 0; _i < 2; ++_i) \
;         __builtin_amdgcn_global_load_lds((const unsigned*)((const char*)(gbase) + (voff)[_i]), (LAS unsigned*)(lds + (bufoff) + ldsw + _i * 8192), 16, 0, 0); } while (0)
; #define PG8_WAIT_V(n) asm volatile("s_waitcnt vmcnt(" #n ")" ::: "memory")
; #define PG8_BAR __builtin_amdgcn_s_barrier()
; template <class Epi, class Sched>
; __device__ __forceinline__ void gemm_phase(LAS unsigned char* lds, const Gemm g, const Sched& S, const Epi& E) {
;     ...
;     for (int i = 0; i < 2; ++i) { int R, C; stage_rc(tid * 16 + i * 8192, R, C); const int Rb = Epi::PERM ? ((R & ~31) + perm32(R & 31)) : R;
;         voffA[i] = (unsigned)(R * lda + C) * 2u; voffB[i] = (unsigned)(Rb * K + C) * 2u; }
;     ...
;     PG8_STAGE(PG8_SB(0, 0), cB, voffB); PG8_STAGE(PG8_SA(0, 0), cA, voffA); PG8_STAGE(PG8_SB(0, 1), cB + hstepB, voffB); PG8_STAGE(PG8_SA(0, 1), cA + hstepA, voffA);
;     if (wr == 1) PG8_BAR;
;     PG8_WAIT_V(4); PG8_BAR;
;     PG8_STAGE(PG8_SB(1, 0), cB + kstep, voffB); PG8_STAGE(PG8_SA(1, 0), cA + kstep, voffA); PG8_STAGE(PG8_SB(1, 1), cB + hstepB + kstep, voffB);
;     PG8_WAIT_V(6); PG8_BAR;
.LBB0_1654:
	v_lshl_add_u64 v[12:13], s[14:15], 0, v[2:3]
	v_mov_b32_e32 v193, v3
	v_readlane_b32 s6, v254, 29
	s_lshl_b32 s0, s0, 5
	v_lshl_add_u64 v[14:15], s[14:15], 0, v[192:193]
	v_mov_b32_e32 v197, v3
	v_readlane_b32 s7, v254, 30
	s_and_b32 s37, s0, 0x60
	s_add_i32 m0, s29, 0x18000
	v_lshl_add_u64 v[12:13], v[12:13], 0, s[8:9]
	v_lshl_add_u64 v[16:17], s[6:7], 0, v[196:197]
	v_mov_b32_e32 v195, v3
	s_lshl_b32 s36, s1, 6
	s_lshl_b32 s4, s1, 13
	s_lshl_b32 s5, s37, 7
	s_waitcnt vmcnt(2)
	s_barrier
	global_load_lds_dwordx4 v[12:13], off
	v_lshl_add_u64 v[12:13], v[14:15], 0, s[8:9]
	s_add_i32 m0, s29, 0x1a000
	s_add_i32 s38, s29, 0x8000
	s_add_i32 s39, s29, 0xa000
	v_lshl_add_u64 v[18:19], s[6:7], 0, v[194:195]
	global_load_lds_dwordx4 v[12:13], off
	v_lshl_add_u64 v[12:13], v[16:17], 0, s[8:9]
	s_mov_b32 m0, s38
	s_add_u32 s0, s14, 0x160080
	global_load_lds_dwordx4 v[12:13], off
	v_lshl_add_u64 v[12:13], v[18:19], 0, s[8:9]
	s_mov_b32 m0, s39
	s_addc_u32 s1, s15, 0
	global_load_lds_dwordx4 v[12:13], off
	s_add_i32 m0, s29, 0x1c000
	v_lshl_add_u64 v[12:13], s[0:1], 0, v[2:3]
	global_load_lds_dwordx4 v[12:13], off
	v_lshl_add_u64 v[12:13], s[0:1], 0, v[192:193]
	s_add_i32 m0, s29, 0x1e000
	s_movk_i32 s0, 0x3c0
	global_load_lds_dwordx4 v[12:13], off
	v_and_b32_e32 v12, 48, v1
	v_lshlrev_b32_e32 v13, 6, v1
	v_lshlrev_b32_e32 v1, 2, v1
	v_and_or_b32 v12, v13, s0, v12
	v_and_b32_e32 v1, 32, v1
	v_bitop3_b32 v13, v12, s4, v1 bitop3:0xde
	s_movk_i32 s4, 0x1600
	v_bitop3_b32 v1, s5, v12, v1 bitop3:0xf6
	v_lshrrev_b32_e32 v9, 1, v9
	v_mul_lo_u32 v8, v8, s4
	s_mov_b32 s5, 0x16000
	v_mad_u64_u32 v[8:9], s[0:1], v9, s5, v[8:9]
	v_or_b32_e32 v8, v8, v10
	v_add_lshl_u32 v8, v8, v11, 1
	v_mov_b32_e32 v9, v3
	s_mov_b64 s[18:19], 0x160080
	v_lshl_add_u64 v[198:199], v[8:9], 0, s[18:19]
	v_lshrrev_b32_e32 v8, 1, v4
	v_mul_lo_u32 v4, v5, s4
	v_mad_u64_u32 v[4:5], s[0:1], v8, s5, v[4:5]
	s_waitcnt vmcnt(6)
	v_or_b32_e32 v4, v4, v6
	v_add_lshl_u32 v4, v4, v7, 1
	v_mov_b32_e32 v5, v3
	v_readlane_b32 s0, v254, 27
	v_lshl_add_u64 v[200:201], v[4:5], 0, s[18:19]
	s_mov_b32 s46, 0
	v_add_u32_e32 v224, 0, v13
	v_readlane_b32 s49, v254, 1
	s_mov_b32 s50, s0
	s_barrier
	v_readlane_b32 s1, v254, 28

; #define PG8_STAGE(bufoff, gbase, voff) do { _Pragma("unroll") for (int _i = 0; _i < 2; ++_i) \
;         __builtin_amdgcn_global_load_lds((const unsigned*)((const char*)(gbase) + (voff)[_i]), (LAS unsigned*)(lds + (bufoff) + ldsw + _i * 8192), 16, 0, 0); } while (0)
; #define PG8_LDA(dst, b, h) do { _Pragma("unroll") for (int m = 0; m < 4; ++m) _Pragma("unroll") for (int k = 0; k < 2; ++k) dst[m][k] = *(const LAS bf16x8*)(lds + PG8_SA(b, h) + aoff + m * 2048 + k * 1024); } while (0)
; #define PG8_LDB(dst, b, h) do { _Pragma("unroll") for (int n = 0; n < 2; ++n) _Pragma("unroll") for (int k = 0; k < 2; ++k) dst[n][k] = *(const LAS bf16x8*)(lds + PG8_SB(b, h) + boff + n * 2048 + k * 1024); } while (0)
; #define PG8_MMA(ai, bj, At, Bt) do { __builtin_amdgcn_s_setprio(1); _Pragma("unroll") for (int m = 0; m < 4; ++m) _Pragma("unroll") for (int n = 0; n < 2; ++n) _Pragma("unroll") for (int k = 0; k < 2; ++k) \
;         acc[ai][bj][m][n] = __builtin_amdgcn_mfma_f32_16x16x32_bf16(Bt[n][k], At[m][k], acc[ai][bj][m][n], 0, 0, 0); __builtin_amdgcn_s_setprio(0); } while (0)
; #define PG8_WAIT_V(n) asm volatile("s_waitcnt vmcnt(" #n ")" ::: "memory")
; #define PG8_WAIT_L(n) asm volatile("s_waitcnt lgkmcnt(" #n ")" ::: "memory")
; #define PG8_BAR __builtin_amdgcn_s_barrier()
; #define PG8_SCHED __builtin_amdgcn_sched_barrier(0)
; template <class Epi, class Sched>
; __device__ __forceinline__ void gemm_phase(LAS unsigned char* lds, const Gemm g, const Sched& S, const Epi& E) {
;     ...
;             PG8_LDB(B0, 0, 0); PG8_SCHED; PG8_LDA(At, 0, 0); PG8_STAGE(PG8_SA(1, 1), a1 + hstepA, voffA);
;             PG8_WAIT_L(8); PG8_BAR; PG8_WAIT_L(0); PG8_MMA(0, 0, At, B0); PG8_BAR; PG8_SCHED;
;             PG8_LDB(B1, 0, 1); PG8_STAGE(PG8_SB(0, 0), b2, voffB);
;             PG8_BAR; PG8_WAIT_L(0); PG8_MMA(0, 1, At, B1); PG8_BAR;
;             PG8_LDA(At, 0, 1); PG8_STAGE(PG8_SA(0, 0), a2, voffA);
;             PG8_BAR; PG8_WAIT_L(0); PG8_MMA(1, 0, At, B0); PG8_BAR; PG8_SCHED;
;             PG8_STAGE(PG8_SB(0, 1), b2 + hstepB, voffB);
;             PG8_WAIT_V(6); PG8_BAR; PG8_MMA(1, 1, At, B1); PG8_BAR;
.LBB0_1666:
	s_add_u32 s14, s6, 0x100
	s_addc_u32 s15, s7, 0
	s_add_i32 s45, 0, 0x10000
	v_add_u32_e32 v144, s45, v1
	ds_read_b128 v[132:135], v144
	ds_read_b128 v[136:139], v144 offset:1024
	ds_read_b128 v[140:143], v144 offset:2048
	ds_read_b128 v[144:147], v144 offset:3072
	s_cmpk_eq_i32 s44, 0x54
	s_cselect_b32 s21, s1, s15
	s_cselect_b32 s20, s0, s14
	s_cselect_b32 s19, s5, s43
	s_cselect_b32 s18, s4, s42
	ds_read_b128 v[148:151], v224
	ds_read_b128 v[152:155], v224 offset:1024
	ds_read_b128 v[156:159], v224 offset:2048
	ds_read_b128 v[160:163], v224 offset:3072
	ds_read_b128 v[164:167], v224 offset:4096
	ds_read_b128 v[168:171], v224 offset:5120
	ds_read_b128 v[172:175], v224 offset:6144
	ds_read_b128 v[176:179], v224 offset:7168
	s_add_i32 s51, 0, 0x14000
	v_add_u32_e32 v202, s51, v1
	ds_read_b128 v[180:183], v202
	ds_read_b128 v[184:187], v202 offset:1024
	ds_read_b128 v[188:191], v202 offset:2048
	ds_read_b128 v[202:205], v202 offset:3072
	s_add_i32 m0, s29, 0xc000
	s_nop 0
	global_load_lds_dwordx4 v198, s[6:7]
	s_add_i32 m0, s29, 0xe000
	s_nop 0
	global_load_lds_dwordx4 v200, s[6:7]
	s_waitcnt lgkmcnt(0)
	s_barrier
	s_setprio 1
	v_mfma_f32_16x16x32_bf16 v[128:131], v[132:135], v[148:151], v[128:131]
	v_mfma_f32_16x16x32_bf16 v[124:127], v[140:143], v[148:151], v[124:127]
	v_mfma_f32_16x16x32_bf16 v[112:115], v[132:135], v[156:159], v[112:115]
	v_mfma_f32_16x16x32_bf16 v[108:111], v[140:143], v[156:159], v[108:111]
	v_mfma_f32_16x16x32_bf16 v[100:103], v[132:135], v[164:167], v[100:103]
	v_mfma_f32_16x16x32_bf16 v[92:95], v[140:143], v[164:167], v[92:95]
	v_mfma_f32_16x16x32_bf16 v[84:87], v[132:135], v[172:175], v[84:87]
	v_mfma_f32_16x16x32_bf16 v[76:79], v[140:143], v[172:175], v[76:79]
	v_mfma_f32_16x16x32_bf16 v[128:131], v[136:139], v[152:155], v[128:131]
	v_mfma_f32_16x16x32_bf16 v[124:127], v[144:147], v[152:155], v[124:127]
	v_mfma_f32_16x16x32_bf16 v[112:115], v[136:139], v[160:163], v[112:115]
	v_mfma_f32_16x16x32_bf16 v[108:111], v[144:147], v[160:163], v[108:111]
	v_mfma_f32_16x16x32_bf16 v[100:103], v[136:139], v[168:171], v[100:103]
	v_mfma_f32_16x16x32_bf16 v[92:95], v[144:147], v[168:171], v[92:95]
	v_mfma_f32_16x16x32_bf16 v[84:87], v[136:139], v[176:179], v[84:87]
	v_mfma_f32_16x16x32_bf16 v[76:79], v[144:147], v[176:179], v[76:79]
	v_mfma_f32_16x16x32_bf16 v[120:123], v[180:183], v[148:151], v[120:123]
	v_mfma_f32_16x16x32_bf16 v[116:119], v[188:191], v[148:151], v[116:119]
	v_mfma_f32_16x16x32_bf16 v[104:107], v[180:183], v[156:159], v[104:107]
	v_mfma_f32_16x16x32_bf16 v[96:99], v[188:191], v[156:159], v[96:99]
	v_mfma_f32_16x16x32_bf16 v[88:91], v[180:183], v[164:167], v[88:91]
	v_mfma_f32_16x16x32_bf16 v[80:83], v[188:191], v[164:167], v[80:83]
	v_mfma_f32_16x16x32_bf16 v[72:75], v[180:183], v[172:175], v[72:75]
	v_mfma_f32_16x16x32_bf16 v[68:71], v[188:191], v[172:175], v[68:71]
	v_mfma_f32_16x16x32_bf16 v[120:123], v[184:187], v[152:155], v[120:123]
	v_mfma_f32_16x16x32_bf16 v[116:119], v[202:205], v[152:155], v[116:119]
	v_mfma_f32_16x16x32_bf16 v[104:107], v[184:187], v[160:163], v[104:107]
	v_mfma_f32_16x16x32_bf16 v[96:99], v[202:205], v[160:163], v[96:99]
	v_mfma_f32_16x16x32_bf16 v[88:91], v[184:187], v[168:171], v[88:91]
	v_mfma_f32_16x16x32_bf16 v[80:83], v[202:205], v[168:171], v[80:83]
	v_mfma_f32_16x16x32_bf16 v[72:75], v[184:187], v[176:179], v[72:75]
	v_mfma_f32_16x16x32_bf16 v[68:71], v[202:205], v[176:179], v[68:71]
	s_setprio 0
	s_barrier
	ds_read_b128 v[148:151], v224 offset:16384
	ds_read_b128 v[152:155], v224 offset:17408
	ds_read_b128 v[156:159], v224 offset:18432
	ds_read_b128 v[160:163], v224 offset:19456
	ds_read_b128 v[164:167], v224 offset:20480
	ds_read_b128 v[168:171], v224 offset:21504
	ds_read_b128 v[172:175], v224 offset:22528
	ds_read_b128 v[176:179], v224 offset:23552
	s_add_i32 s6, s45, s28
	v_lshl_add_u64 v[206:207], s[18:19], 0, v[2:3]
	s_mov_b32 m0, s6
	s_nop 0
	global_load_lds_dwordx4 v[206:207], off
	v_lshl_add_u64 v[208:209], s[18:19], 0, v[192:193]
	s_add_i32 m0, s6, 0x2000
	s_nop 0
	global_load_lds_dwordx4 v[208:209], off
	s_mov_b32 m0, s29
	v_lshl_add_u64 v[210:211], s[20:21], 0, v[196:197]
	global_load_lds_dwordx4 v[210:211], off
	v_lshl_add_u64 v[212:213], s[20:21], 0, v[194:195]
	s_mov_b32 m0, s30
	s_nop 0
	global_load_lds_dwordx4 v[212:213], off
	s_add_u32 s6, s18, 0x160000
	s_addc_u32 s7, s19, 0
	s_add_i32 s45, s51, s28
	s_mov_b32 m0, s45
	s_nop 0
	global_load_lds_dwordx4 v2, s[6:7]
	s_add_i32 m0, s45, 0x2000
	s_nop 0
	global_load_lds_dwordx4 v192, s[6:7]
	s_waitcnt lgkmcnt(0)
	s_waitcnt vmcnt(6)
	s_barrier
; #define PG8_STAGE(bufoff, gbase, voff) do { _Pragma("unroll") for (int _i = 0; _i < 2; ++_i) \
;         __builtin_amdgcn_global_load_lds((const unsigned*)((const char*)(gbase) + (voff)[_i]), (LAS unsigned*)(lds + (bufoff) + ldsw + _i * 8192), 16, 0, 0); } while (0)
; #define PG8_LDA(dst, b, h) do { _Pragma("unroll") for (int m = 0; m < 4; ++m) _Pragma("unroll") for (int k = 0; k < 2; ++k) dst[m][k] = *(const LAS bf16x8*)(lds + PG8_SA(b, h) + aoff + m * 2048 + k * 1024); } while (0)
; #define PG8_LDB(dst, b, h) do { _Pragma("unroll") for (int n = 0; n < 2; ++n) _Pragma("unroll") for (int k = 0; k < 2; ++k) dst[n][k] = *(const LAS bf16x8*)(lds + PG8_SB(b, h) + boff + n * 2048 + k * 1024); } while (0)
; #define PG8_MMA(ai, bj, At, Bt) do { __builtin_amdgcn_s_setprio(1); _Pragma("unroll") for (int m = 0; m < 4; ++m) _Pragma("unroll") for (int n = 0; n < 2; ++n) _Pragma("unroll") for (int k = 0; k < 2; ++k) \
;         acc[ai][bj][m][n] = __builtin_amdgcn_mfma_f32_16x16x32_bf16(Bt[n][k], At[m][k], acc[ai][bj][m][n], 0, 0, 0); __builtin_amdgcn_s_setprio(0); } while (0)
; #define PG8_WAIT_V(n) asm volatile("s_waitcnt vmcnt(" #n ")" ::: "memory")
; #define PG8_WAIT_L(n) asm volatile("s_waitcnt lgkmcnt(" #n ")" ::: "memory")
; #define PG8_BAR __builtin_amdgcn_s_barrier()
; #define PG8_SCHED __builtin_amdgcn_sched_barrier(0)
; template <class Epi, class Sched>
; __device__ __forceinline__ void gemm_phase(LAS unsigned char* lds, const Gemm g, const Sched& S, const Epi& E) {
;     ...
;             PG8_WAIT_V(6); PG8_BAR; PG8_MMA(1, 1, At, B1); PG8_BAR;
;             PG8_LDB(B0, 1, 0); PG8_SCHED; PG8_LDA(At, 1, 0); PG8_STAGE(PG8_SA(0, 1), a2 + hstepA, voffA);
;             PG8_WAIT_L(8); PG8_BAR; PG8_WAIT_L(0); PG8_MMA(0, 0, At, B0); PG8_BAR; PG8_SCHED;
;             PG8_LDB(B1, 1, 1); PG8_STAGE(PG8_SB(1, 0), b3, voffB);
;             PG8_BAR; PG8_WAIT_L(0); PG8_MMA(0, 1, At, B1); PG8_BAR;
;             PG8_LDA(At, 1, 1); PG8_STAGE(PG8_SA(1, 0), a3, voffA);
;             PG8_BAR; PG8_WAIT_L(0); PG8_MMA(1, 0, At, B0); PG8_BAR; PG8_SCHED;
	s_setprio 1
	v_mfma_f32_16x16x32_bf16 v[64:67], v[132:135], v[148:151], v[64:67]
	v_mfma_f32_16x16x32_bf16 v[60:63], v[140:143], v[148:151], v[60:63]
	v_mfma_f32_16x16x32_bf16 v[52:55], v[132:135], v[156:159], v[52:55]
	v_mfma_f32_16x16x32_bf16 v[44:47], v[140:143], v[156:159], v[44:47]
	v_mfma_f32_16x16x32_bf16 v[36:39], v[132:135], v[164:167], v[36:39]
	v_mfma_f32_16x16x32_bf16 v[28:31], v[140:143], v[164:167], v[28:31]
	v_mfma_f32_16x16x32_bf16 v[20:23], v[132:135], v[172:175], v[20:23]
	v_mfma_f32_16x16x32_bf16 v[12:15], v[140:143], v[172:175], v[12:15]
	v_mfma_f32_16x16x32_bf16 v[64:67], v[136:139], v[152:155], v[64:67]
	v_mfma_f32_16x16x32_bf16 v[60:63], v[144:147], v[152:155], v[60:63]
	v_mfma_f32_16x16x32_bf16 v[52:55], v[136:139], v[160:163], v[52:55]
	v_mfma_f32_16x16x32_bf16 v[44:47], v[144:147], v[160:163], v[44:47]
	v_mfma_f32_16x16x32_bf16 v[36:39], v[136:139], v[168:171], v[36:39]
	v_mfma_f32_16x16x32_bf16 v[28:31], v[144:147], v[168:171], v[28:31]
	v_mfma_f32_16x16x32_bf16 v[20:23], v[136:139], v[176:179], v[20:23]
	v_mfma_f32_16x16x32_bf16 v[12:15], v[144:147], v[176:179], v[12:15]
	v_mfma_f32_16x16x32_bf16 v[56:59], v[180:183], v[148:151], v[56:59]
	v_mfma_f32_16x16x32_bf16 v[48:51], v[188:191], v[148:151], v[48:51]
	v_mfma_f32_16x16x32_bf16 v[40:43], v[180:183], v[156:159], v[40:43]
	v_mfma_f32_16x16x32_bf16 v[32:35], v[188:191], v[156:159], v[32:35]
	v_mfma_f32_16x16x32_bf16 v[24:27], v[180:183], v[164:167], v[24:27]
	v_mfma_f32_16x16x32_bf16 v[16:19], v[188:191], v[164:167], v[16:19]
	v_mfma_f32_16x16x32_bf16 v[8:11], v[180:183], v[172:175], v[8:11]
	v_mfma_f32_16x16x32_bf16 v[4:7], v[188:191], v[172:175], v[4:7]
	v_mfma_f32_16x16x32_bf16 v[56:59], v[184:187], v[152:155], v[56:59]
	v_mfma_f32_16x16x32_bf16 v[48:51], v[202:205], v[152:155], v[48:51]
	v_mfma_f32_16x16x32_bf16 v[40:43], v[184:187], v[160:163], v[40:43]
	v_mfma_f32_16x16x32_bf16 v[32:35], v[202:205], v[160:163], v[32:35]
	v_mfma_f32_16x16x32_bf16 v[24:27], v[184:187], v[168:171], v[24:27]
	v_mfma_f32_16x16x32_bf16 v[16:19], v[202:205], v[168:171], v[16:19]
	v_mfma_f32_16x16x32_bf16 v[8:11], v[184:187], v[176:179], v[8:11]
	v_mfma_f32_16x16x32_bf16 v[4:7], v[202:205], v[176:179], v[4:7]
	s_setprio 0
	s_add_i32 s45, 0, 0x18000
	v_add_u32_e32 v144, s45, v1
	s_barrier
	ds_read_b128 v[132:135], v144
	ds_read_b128 v[136:139], v144 offset:1024
	ds_read_b128 v[140:143], v144 offset:2048
	ds_read_b128 v[144:147], v144 offset:3072
	s_add_u32 s6, s20, 0x160000
	s_addc_u32 s7, s21, 0
	ds_read_b128 v[148:151], v224 offset:32768
	ds_read_b128 v[152:155], v224 offset:33792
	ds_read_b128 v[156:159], v224 offset:34816
	ds_read_b128 v[160:163], v224 offset:35840
	ds_read_b128 v[164:167], v224 offset:36864
	ds_read_b128 v[168:171], v224 offset:37888
	ds_read_b128 v[172:175], v224 offset:38912
	ds_read_b128 v[176:179], v224 offset:39936
	s_mov_b32 m0, s31
	s_nop 0
	global_load_lds_dwordx4 v196, s[6:7]
	s_mov_b32 m0, s35
	s_nop 0
	global_load_lds_dwordx4 v194, s[6:7]
	s_add_i32 s20, 0, 0x1c000
	v_add_u32_e32 v202, s20, v1
	ds_read_b128 v[180:183], v202
	ds_read_b128 v[184:187], v202 offset:1024
	ds_read_b128 v[188:191], v202 offset:2048
	ds_read_b128 v[202:205], v202 offset:3072
	s_waitcnt lgkmcnt(0)
	s_barrier
	s_setprio 1
	v_mfma_f32_16x16x32_bf16 v[128:131], v[132:135], v[148:151], v[128:131]
	v_mfma_f32_16x16x32_bf16 v[124:127], v[140:143], v[148:151], v[124:127]
	v_mfma_f32_16x16x32_bf16 v[112:115], v[132:135], v[156:159], v[112:115]
	v_mfma_f32_16x16x32_bf16 v[108:111], v[140:143], v[156:159], v[108:111]
	v_mfma_f32_16x16x32_bf16 v[100:103], v[132:135], v[164:167], v[100:103]
	v_mfma_f32_16x16x32_bf16 v[92:95], v[140:143], v[164:167], v[92:95]
	v_mfma_f32_16x16x32_bf16 v[84:87], v[132:135], v[172:175], v[84:87]
	v_mfma_f32_16x16x32_bf16 v[76:79], v[140:143], v[172:175], v[76:79]
	v_mfma_f32_16x16x32_bf16 v[128:131], v[136:139], v[152:155], v[128:131]
	v_mfma_f32_16x16x32_bf16 v[124:127], v[144:147], v[152:155], v[124:127]
	v_mfma_f32_16x16x32_bf16 v[112:115], v[136:139], v[160:163], v[112:115]
	v_mfma_f32_16x16x32_bf16 v[108:111], v[144:147], v[160:163], v[108:111]
	v_mfma_f32_16x16x32_bf16 v[100:103], v[136:139], v[168:171], v[100:103]
	v_mfma_f32_16x16x32_bf16 v[92:95], v[144:147], v[168:171], v[92:95]
	v_mfma_f32_16x16x32_bf16 v[84:87], v[136:139], v[176:179], v[84:87]
	v_mfma_f32_16x16x32_bf16 v[76:79], v[144:147], v[176:179], v[76:79]
	v_mfma_f32_16x16x32_bf16 v[120:123], v[180:183], v[148:151], v[120:123]
	v_mfma_f32_16x16x32_bf16 v[116:119], v[188:191], v[148:151], v[116:119]
	v_mfma_f32_16x16x32_bf16 v[104:107], v[180:183], v[156:159], v[104:107]
	v_mfma_f32_16x16x32_bf16 v[96:99], v[188:191], v[156:159], v[96:99]
	v_mfma_f32_16x16x32_bf16 v[88:91], v[180:183], v[164:167], v[88:91]
	v_mfma_f32_16x16x32_bf16 v[80:83], v[188:191], v[164:167], v[80:83]
	v_mfma_f32_16x16x32_bf16 v[72:75], v[180:183], v[172:175], v[72:75]
	v_mfma_f32_16x16x32_bf16 v[68:71], v[188:191], v[172:175], v[68:71]
	v_mfma_f32_16x16x32_bf16 v[120:123], v[184:187], v[152:155], v[120:123]
	v_mfma_f32_16x16x32_bf16 v[116:119], v[202:205], v[152:155], v[116:119]
	v_mfma_f32_16x16x32_bf16 v[104:107], v[184:187], v[160:163], v[104:107]
	v_mfma_f32_16x16x32_bf16 v[96:99], v[202:205], v[160:163], v[96:99]
	v_mfma_f32_16x16x32_bf16 v[88:91], v[184:187], v[168:171], v[88:91]
	v_mfma_f32_16x16x32_bf16 v[80:83], v[202:205], v[168:171], v[80:83]
	v_mfma_f32_16x16x32_bf16 v[72:75], v[184:187], v[176:179], v[72:75]
	v_mfma_f32_16x16x32_bf16 v[68:71], v[202:205], v[176:179], v[68:71]
	s_setprio 0
	s_barrier
; __device__ __forceinline__ int opaque_tid() { int t = threadIdx.x; asm volatile("" : "+v"(t)); return t; }
; #define PG8_STAGE(bufoff, gbase, voff) do { _Pragma("unroll") for (int _i = 0; _i < 2; ++_i) \
;         __builtin_amdgcn_global_load_lds((const unsigned*)((const char*)(gbase) + (voff)[_i]), (LAS unsigned*)(lds + (bufoff) + ldsw + _i * 8192), 16, 0, 0); } while (0)
; #define PG8_LDA(dst, b, h) do { _Pragma("unroll") for (int m = 0; m < 4; ++m) _Pragma("unroll") for (int k = 0; k < 2; ++k) dst[m][k] = *(const LAS bf16x8*)(lds + PG8_SA(b, h) + aoff + m * 2048 + k * 1024); } while (0)
; #define PG8_LDB(dst, b, h) do { _Pragma("unroll") for (int n = 0; n < 2; ++n) _Pragma("unroll") for (int k = 0; k < 2; ++k) dst[n][k] = *(const LAS bf16x8*)(lds + PG8_SB(b, h) + boff + n * 2048 + k * 1024); } while (0)
; #define PG8_MMA(ai, bj, At, Bt) do { __builtin_amdgcn_s_setprio(1); _Pragma("unroll") for (int m = 0; m < 4; ++m) _Pragma("unroll") for (int n = 0; n < 2; ++n) _Pragma("unroll") for (int k = 0; k < 2; ++k) \
;         acc[ai][bj][m][n] = __builtin_amdgcn_mfma_f32_16x16x32_bf16(Bt[n][k], At[m][k], acc[ai][bj][m][n], 0, 0, 0); __builtin_amdgcn_s_setprio(0); } while (0)
;     __device__ __forceinline__ void operator()(const f32x4 (&acc)[2][2][4][2], const Unit& u, int wr, int wc, int, int) const {
;         const int ol_ = opaque_tid() & 63, fr = ol_ & 15, fq = ol_ >> 4;
;         const int row0 = u.pm * BM + wr * 64 + fr, col0 = u.pn * BM + wc * 32 + 8 * fq;
;         u32x4 cin[2][4][2];
; #pragma unroll
;         for (int ai = 0; ai < 2; ++ai)
; #pragma unroll
;             for (int m = 0; m < 4; ++m)
; #pragma unroll
;                 for (int bj = 0; bj < 2; ++bj) cin[ai][m][bj] = *(const u32x4*)(C + (size_t)(row0 + ai * HALF + m * 16) * ldc + col0 + bj * HALF);
; template <class Epi, class Sched>
; __device__ __forceinline__ void gemm_phase(LAS unsigned char* lds, const Gemm g, const Sched& S, const Epi& E) {
;     ...
;             PG8_LDB(B1, 1, 1); PG8_STAGE(PG8_SB(1, 0), b3, voffB);
;             PG8_BAR; PG8_WAIT_L(0); PG8_MMA(0, 1, At, B1); PG8_BAR;
;             PG8_LDA(At, 1, 1); PG8_STAGE(PG8_SA(1, 0), a3, voffA);
;             PG8_BAR; PG8_WAIT_L(0); PG8_MMA(1, 0, At, B0); PG8_BAR; PG8_SCHED;
;             PG8_STAGE(PG8_SB(1, 1), b3 + hstepB, voffB);
;             PG8_WAIT_V(6); PG8_BAR; PG8_MMA(1, 1, At, B1); PG8_BAR;
	ds_read_b128 v[148:151], v224 offset:49152
	ds_read_b128 v[152:155], v224 offset:50176
	ds_read_b128 v[156:159], v224 offset:51200
	ds_read_b128 v[160:163], v224 offset:52224
	ds_read_b128 v[164:167], v224 offset:53248
	ds_read_b128 v[168:171], v224 offset:54272
	ds_read_b128 v[172:175], v224 offset:55296
	ds_read_b128 v[176:179], v224 offset:56320
	s_add_i32 s6, s45, s28
	v_lshl_add_u64 v[206:207], v[206:207], 0, s[8:9]
	s_mov_b32 m0, s6
	s_nop 0
	global_load_lds_dwordx4 v[206:207], off
	v_lshl_add_u64 v[206:207], v[208:209], 0, s[8:9]
	s_add_i32 m0, s6, 0x2000
	s_nop 0
	global_load_lds_dwordx4 v[206:207], off
	s_mov_b32 m0, s38
	v_lshl_add_u64 v[206:207], v[210:211], 0, s[8:9]
	global_load_lds_dwordx4 v[206:207], off
	v_lshl_add_u64 v[206:207], v[212:213], 0, s[8:9]
	s_mov_b32 m0, s39
	s_nop 0
	global_load_lds_dwordx4 v[206:207], off
	s_add_u32 s6, s18, 0x160080
	s_addc_u32 s7, s19, 0
	s_add_i32 s18, s20, s28
	s_mov_b32 m0, s18
	s_nop 0
	global_load_lds_dwordx4 v2, s[6:7]
	s_add_i32 m0, s18, 0x2000
	s_nop 0
	global_load_lds_dwordx4 v192, s[6:7]
	s_waitcnt lgkmcnt(0)
	s_waitcnt vmcnt(6)
	s_barrier
	s_setprio 1
	v_mfma_f32_16x16x32_bf16 v[64:67], v[132:135], v[148:151], v[64:67]
	v_mfma_f32_16x16x32_bf16 v[60:63], v[140:143], v[148:151], v[60:63]
	v_mfma_f32_16x16x32_bf16 v[52:55], v[132:135], v[156:159], v[52:55]
	v_mfma_f32_16x16x32_bf16 v[44:47], v[140:143], v[156:159], v[44:47]
	v_mfma_f32_16x16x32_bf16 v[36:39], v[132:135], v[164:167], v[36:39]
	v_mfma_f32_16x16x32_bf16 v[28:31], v[140:143], v[164:167], v[28:31]
	v_mfma_f32_16x16x32_bf16 v[20:23], v[132:135], v[172:175], v[20:23]
	v_mfma_f32_16x16x32_bf16 v[12:15], v[140:143], v[172:175], v[12:15]
	v_mfma_f32_16x16x32_bf16 v[64:67], v[136:139], v[152:155], v[64:67]
	v_mfma_f32_16x16x32_bf16 v[60:63], v[144:147], v[152:155], v[60:63]
	v_mfma_f32_16x16x32_bf16 v[52:55], v[136:139], v[160:163], v[52:55]
	v_mfma_f32_16x16x32_bf16 v[44:47], v[144:147], v[160:163], v[44:47]
	v_mfma_f32_16x16x32_bf16 v[36:39], v[136:139], v[168:171], v[36:39]
	v_mfma_f32_16x16x32_bf16 v[28:31], v[144:147], v[168:171], v[28:31]
	v_mfma_f32_16x16x32_bf16 v[20:23], v[136:139], v[176:179], v[20:23]
	v_mfma_f32_16x16x32_bf16 v[12:15], v[144:147], v[176:179], v[12:15]
	v_mfma_f32_16x16x32_bf16 v[56:59], v[180:183], v[148:151], v[56:59]
	v_mfma_f32_16x16x32_bf16 v[48:51], v[188:191], v[148:151], v[48:51]
	v_mfma_f32_16x16x32_bf16 v[40:43], v[180:183], v[156:159], v[40:43]
	v_mfma_f32_16x16x32_bf16 v[32:35], v[188:191], v[156:159], v[32:35]
	v_mfma_f32_16x16x32_bf16 v[24:27], v[180:183], v[164:167], v[24:27]
	v_mfma_f32_16x16x32_bf16 v[16:19], v[188:191], v[164:167], v[16:19]
	v_mfma_f32_16x16x32_bf16 v[8:11], v[180:183], v[172:175], v[8:11]
	v_mfma_f32_16x16x32_bf16 v[4:7], v[188:191], v[172:175], v[4:7]
	v_mfma_f32_16x16x32_bf16 v[56:59], v[184:187], v[152:155], v[56:59]
	v_mfma_f32_16x16x32_bf16 v[48:51], v[202:205], v[152:155], v[48:51]
	v_mfma_f32_16x16x32_bf16 v[40:43], v[184:187], v[160:163], v[40:43]
	v_mfma_f32_16x16x32_bf16 v[32:35], v[202:205], v[160:163], v[32:35]
	v_mfma_f32_16x16x32_bf16 v[24:27], v[184:187], v[168:171], v[24:27]
	v_mfma_f32_16x16x32_bf16 v[16:19], v[202:205], v[168:171], v[16:19]
	v_mfma_f32_16x16x32_bf16 v[8:11], v[184:187], v[176:179], v[8:11]
	v_mfma_f32_16x16x32_bf16 v[4:7], v[202:205], v[176:179], v[4:7]
	s_setprio 0
	s_add_i32 s44, s44, 2
	s_add_u32 s42, s42, 0x100
	s_addc_u32 s43, s43, 0
	s_cmpk_gt_u32 s44, 0x55
	s_mov_b64 s[6:7], s[14:15]
	s_barrier
	s_cbranch_scc0 .LBB0_1666
	v_mov_b32_e32 v133, v0
	s_lshl_b32 s6, s50, 8
	s_add_i32 s6, s6, s36
	v_and_or_b32 v132, v133, 15, s6
	s_lshl_b32 s6, s49, 8
	v_lshrrev_b32_e32 v133, 1, v133
	v_and_or_b32 v133, v133, 24, s6
	v_or_b32_e32 v134, s37, v133
	v_ashrrev_i32_e32 v135, 31, v134
	v_lshlrev_b64 v[202:203], 1, v[134:135]
	v_ashrrev_i32_e32 v133, 31, v132
	v_lshl_add_u64 v[134:135], s[88:89], 0, v[202:203]
	v_lshlrev_b64 v[226:227], 12, v[132:133]
	v_lshl_add_u64 v[136:137], v[134:135], 0, v[226:227]
	global_load_dwordx4 v[216:219], v[136:137], off
	global_load_dwordx4 v[188:191], v[136:137], off offset:256
	v_or_b32_e32 v136, 16, v132
	v_ashrrev_i32_e32 v137, 31, v136
	v_lshlrev_b64 v[222:223], 12, v[136:137]
	v_lshl_add_u64 v[136:137], v[134:135], 0, v[222:223]
	global_load_dwordx4 v[184:187], v[136:137], off
	global_load_dwordx4 v[180:183], v[136:137], off offset:256
	v_or_b32_e32 v136, 32, v132
	v_ashrrev_i32_e32 v137, 31, v136
	v_lshlrev_b64 v[220:221], 12, v[136:137]
	v_lshl_add_u64 v[136:137], v[134:135], 0, v[220:221]
	global_load_dwordx4 v[176:179], v[136:137], off
	global_load_dwordx4 v[168:171], v[136:137], off offset:256
	v_or_b32_e32 v132, 48, v132
	v_ashrrev_i32_e32 v133, 31, v132
	v_lshlrev_b64 v[212:213], 12, v[132:133]
	v_lshl_add_u64 v[132:133], v[134:135], 0, v[212:213]
	global_load_dwordx4 v[172:175], v[132:133], off
	global_load_dwordx4 v[164:167], v[132:133], off offset:256
	s_mov_b64 s[6:7], 0x80000
	v_lshl_add_u64 v[210:211], v[226:227], 0, s[6:7]
	v_lshl_add_u64 v[132:133], v[134:135], 0, v[210:211]
	global_load_dwordx4 v[160:163], v[132:133], off
	global_load_dwordx4 v[156:159], v[132:133], off offset:256
	s_mov_b64 s[6:7], 0x90000
	v_lshl_add_u64 v[208:209], v[226:227], 0, s[6:7]
	v_lshl_add_u64 v[132:133], v[134:135], 0, v[208:209]
	global_load_dwordx4 v[152:155], v[132:133], off
	global_load_dwordx4 v[148:151], v[132:133], off offset:256
	s_mov_b64 s[6:7], 0xa0000
	v_lshl_add_u64 v[206:207], v[226:227], 0, s[6:7]
	v_lshl_add_u64 v[132:133], v[134:135], 0, v[206:207]
	global_load_dwordx4 v[144:147], v[132:133], off
	global_load_dwordx4 v[140:143], v[132:133], off offset:256
	s_mov_b64 s[6:7], 0xb0000
	v_lshl_add_u64 v[204:205], v[226:227], 0, s[6:7]
	v_lshl_add_u64 v[132:133], v[134:135], 0, v[204:205]
	global_load_dwordx4 v[136:139], v[132:133], off
	s_nop 0
	global_load_dwordx4 v[132:135], v[132:133], off offset:256
	s_and_b64 vcc, exec, s[40:41]
	s_mov_b32 s49, s47
	s_mov_b32 s50, s48
	s_mov_b64 s[14:15], s[4:5]
	s_mov_b64 s[6:7], s[0:1]
	s_waitcnt vmcnt(0)
; __device__ __forceinline__ unsigned cvt_pk_bf16(float lo, float hi) { const f32x2 v = {lo, hi}; const bf16v2_ r = __builtin_convertvector(v, bf16v2_); return __builtin_bit_cast(unsigned, r); }
; __device__ __forceinline__ float bflo(unsigned w) { return __uint_as_float(w << 16); }
; __device__ __forceinline__ float bfhi(unsigned w) { return __uint_as_float(w & 0xffff0000u); }
;     __device__ __forceinline__ void operator()(const f32x4 (&acc)[2][2][4][2], const Unit& u, int wr, int wc, int, int) const {
;     ...
; #pragma unroll
;         for (int ai = 0; ai < 2; ++ai)
; #pragma unroll
;             for (int m = 0; m < 4; ++m)
; #pragma unroll
;                 for (int bj = 0; bj < 2; ++bj) { const u32x4 c = cin[ai][m][bj]; const f32x4 v0 = acc[ai][bj][m][0], v1 = acc[ai][bj][m][1];
;                     u32x4 w; w.x = cvt_pk_bf16(bflo(c.x) + v0[0], bfhi(c.x) + v0[1]); w.y = cvt_pk_bf16(bflo(c.y) + v0[2], bfhi(c.y) + v0[3]);
;                     w.z = cvt_pk_bf16(bflo(c.z) + v1[0], bfhi(c.z) + v1[1]); w.w = cvt_pk_bf16(bflo(c.w) + v1[2], bfhi(c.w) + v1[3]);
;                     *(u32x4*)(C + (size_t)(row0 + ai * HALF + m * 16) * ldc + col0 + bj * HALF) = w; }
	v_lshlrev_b32_e32 v228, 16, v216
	v_and_b32_e32 v229, 0xffff0000, v216
	v_lshlrev_b32_e32 v216, 16, v217
	v_and_b32_e32 v217, 0xffff0000, v217
	v_pk_add_f32 v[128:129], v[128:129], v[228:229]
	v_pk_add_f32 v[130:131], v[130:131], v[216:217]
	v_cvt_pk_bf16_f32 v128, v128, v129
	v_cvt_pk_bf16_f32 v129, v130, v131
	v_lshlrev_b32_e32 v130, 16, v218
	v_and_b32_e32 v131, 0xffff0000, v218
	v_pk_add_f32 v[124:125], v[124:125], v[130:131]
	s_nop 0
	v_cvt_pk_bf16_f32 v130, v124, v125
	v_lshlrev_b32_e32 v124, 16, v219
	v_and_b32_e32 v125, 0xffff0000, v219
	v_pk_add_f32 v[124:125], v[126:127], v[124:125]
	v_lshlrev_b32_e32 v126, 16, v188
	v_and_b32_e32 v127, 0xffff0000, v188
	v_pk_add_f32 v[120:121], v[120:121], v[126:127]
	v_lshlrev_b32_e32 v126, 16, v189
	v_and_b32_e32 v127, 0xffff0000, v189
	v_pk_add_f32 v[122:123], v[122:123], v[126:127]
	v_cvt_pk_bf16_f32 v120, v120, v121
	v_cvt_pk_bf16_f32 v121, v122, v123
	v_lshlrev_b32_e32 v122, 16, v190
	v_and_b32_e32 v123, 0xffff0000, v190
	v_pk_add_f32 v[116:117], v[116:117], v[122:123]
	v_cvt_pk_bf16_f32 v131, v124, v125
	v_cvt_pk_bf16_f32 v122, v116, v117
	v_lshlrev_b32_e32 v116, 16, v191
	v_and_b32_e32 v117, 0xffff0000, v191
	v_pk_add_f32 v[116:117], v[118:119], v[116:117]
	v_lshl_add_u64 v[124:125], s[88:89], 0, v[226:227]
	v_cvt_pk_bf16_f32 v123, v116, v117
	v_lshlrev_b32_e32 v116, 16, v184
	v_and_b32_e32 v117, 0xffff0000, v184
	v_pk_add_f32 v[112:113], v[112:113], v[116:117]
	v_lshlrev_b32_e32 v116, 16, v185
	v_and_b32_e32 v117, 0xffff0000, v185
	v_pk_add_f32 v[114:115], v[114:115], v[116:117]
	v_cvt_pk_bf16_f32 v112, v112, v113
	v_cvt_pk_bf16_f32 v113, v114, v115
	v_lshlrev_b32_e32 v114, 16, v186
	v_and_b32_e32 v115, 0xffff0000, v186
	v_pk_add_f32 v[108:109], v[108:109], v[114:115]
	v_lshl_add_u64 v[124:125], v[124:125], 0, v[202:203]
	v_cvt_pk_bf16_f32 v114, v108, v109
	v_lshlrev_b32_e32 v108, 16, v187
	v_and_b32_e32 v109, 0xffff0000, v187
	v_pk_add_f32 v[108:109], v[110:111], v[108:109]
	v_lshlrev_b32_e32 v110, 16, v180
	v_and_b32_e32 v111, 0xffff0000, v180
	v_pk_add_f32 v[104:105], v[104:105], v[110:111]
	v_lshlrev_b32_e32 v110, 16, v181
	v_and_b32_e32 v111, 0xffff0000, v181
	v_pk_add_f32 v[106:107], v[106:107], v[110:111]
	v_cvt_pk_bf16_f32 v104, v104, v105
	v_cvt_pk_bf16_f32 v105, v106, v107
	v_lshlrev_b32_e32 v106, 16, v182
	v_and_b32_e32 v107, 0xffff0000, v182
	v_pk_add_f32 v[96:97], v[96:97], v[106:107]
	v_cvt_pk_bf16_f32 v115, v108, v109
	v_cvt_pk_bf16_f32 v106, v96, v97
	v_lshlrev_b32_e32 v96, 16, v183
	v_and_b32_e32 v97, 0xffff0000, v183
	v_pk_add_f32 v[96:97], v[98:99], v[96:97]
	v_lshlrev_b32_e32 v98, 16, v177
	v_cvt_pk_bf16_f32 v107, v96, v97
	v_lshlrev_b32_e32 v96, 16, v176
	v_and_b32_e32 v97, 0xffff0000, v176
	v_and_b32_e32 v99, 0xffff0000, v177
	v_pk_add_f32 v[96:97], v[100:101], v[96:97]
	v_pk_add_f32 v[98:99], v[102:103], v[98:99]
	v_cvt_pk_bf16_f32 v96, v96, v97
	v_cvt_pk_bf16_f32 v97, v98, v99
	v_lshlrev_b32_e32 v98, 16, v178
	v_and_b32_e32 v99, 0xffff0000, v178
	v_pk_add_f32 v[92:93], v[92:93], v[98:99]
	v_lshl_add_u64 v[108:109], s[88:89], 0, v[222:223]
	v_cvt_pk_bf16_f32 v98, v92, v93
	v_lshlrev_b32_e32 v92, 16, v179
	v_and_b32_e32 v93, 0xffff0000, v179
	v_pk_add_f32 v[92:93], v[94:95], v[92:93]
	v_lshlrev_b32_e32 v94, 16, v168
	v_and_b32_e32 v95, 0xffff0000, v168
	v_pk_add_f32 v[88:89], v[88:89], v[94:95]
	v_lshlrev_b32_e32 v94, 16, v169
	v_and_b32_e32 v95, 0xffff0000, v169
	v_pk_add_f32 v[90:91], v[90:91], v[94:95]
	v_cvt_pk_bf16_f32 v88, v88, v89
	v_cvt_pk_bf16_f32 v89, v90, v91
	v_lshlrev_b32_e32 v90, 16, v170
	v_and_b32_e32 v91, 0xffff0000, v170
	v_pk_add_f32 v[80:81], v[80:81], v[90:91]
	v_cvt_pk_bf16_f32 v99, v92, v93
	v_cvt_pk_bf16_f32 v90, v80, v81
	v_lshlrev_b32_e32 v80, 16, v171
	v_and_b32_e32 v81, 0xffff0000, v171
	v_pk_add_f32 v[80:81], v[82:83], v[80:81]
	v_lshlrev_b32_e32 v82, 16, v173
	v_cvt_pk_bf16_f32 v91, v80, v81
	v_lshlrev_b32_e32 v80, 16, v172
	v_and_b32_e32 v81, 0xffff0000, v172
	v_and_b32_e32 v83, 0xffff0000, v173
	v_pk_add_f32 v[80:81], v[84:85], v[80:81]
	v_pk_add_f32 v[82:83], v[86:87], v[82:83]
	v_cvt_pk_bf16_f32 v80, v80, v81
	v_cvt_pk_bf16_f32 v81, v82, v83
	v_lshlrev_b32_e32 v82, 16, v174
	v_and_b32_e32 v83, 0xffff0000, v174
	v_pk_add_f32 v[76:77], v[76:77], v[82:83]
	v_lshl_add_u64 v[92:93], s[88:89], 0, v[220:221]
	v_cvt_pk_bf16_f32 v82, v76, v77
	v_lshlrev_b32_e32 v76, 16, v175
	v_and_b32_e32 v77, 0xffff0000, v175
	v_pk_add_f32 v[76:77], v[78:79], v[76:77]
	v_lshlrev_b32_e32 v78, 16, v164
	v_and_b32_e32 v79, 0xffff0000, v164
	v_pk_add_f32 v[72:73], v[72:73], v[78:79]
	v_lshlrev_b32_e32 v78, 16, v165
	v_and_b32_e32 v79, 0xffff0000, v165
	v_pk_add_f32 v[74:75], v[74:75], v[78:79]
	v_cvt_pk_bf16_f32 v72, v72, v73
	v_cvt_pk_bf16_f32 v73, v74, v75
	v_lshlrev_b32_e32 v74, 16, v166
	v_and_b32_e32 v75, 0xffff0000, v166
	v_pk_add_f32 v[68:69], v[68:69], v[74:75]
	v_cvt_pk_bf16_f32 v83, v76, v77
	v_cvt_pk_bf16_f32 v74, v68, v69
	v_lshlrev_b32_e32 v68, 16, v167
	v_and_b32_e32 v69, 0xffff0000, v167
	v_pk_add_f32 v[68:69], v[70:71], v[68:69]
	v_lshl_add_u64 v[76:77], s[88:89], 0, v[212:213]
	v_cvt_pk_bf16_f32 v75, v68, v69
	v_lshlrev_b32_e32 v68, 16, v160
	v_and_b32_e32 v69, 0xffff0000, v160
	v_pk_add_f32 v[64:65], v[64:65], v[68:69]
	v_lshlrev_b32_e32 v68, 16, v161
	v_and_b32_e32 v69, 0xffff0000, v161
	v_pk_add_f32 v[66:67], v[66:67], v[68:69]
	v_cvt_pk_bf16_f32 v64, v64, v65
	v_cvt_pk_bf16_f32 v65, v66, v67
	v_lshlrev_b32_e32 v66, 16, v162
	v_and_b32_e32 v67, 0xffff0000, v162
	v_pk_add_f32 v[60:61], v[60:61], v[66:67]
	v_lshl_add_u64 v[108:109], v[108:109], 0, v[202:203]
	v_cvt_pk_bf16_f32 v66, v60, v61
	v_lshlrev_b32_e32 v60, 16, v163
; __device__ __forceinline__ unsigned cvt_pk_bf16(float lo, float hi) { const f32x2 v = {lo, hi}; const bf16v2_ r = __builtin_convertvector(v, bf16v2_); return __builtin_bit_cast(unsigned, r); }
; __device__ __forceinline__ float bflo(unsigned w) { return __uint_as_float(w << 16); }
; __device__ __forceinline__ float bfhi(unsigned w) { return __uint_as_float(w & 0xffff0000u); }
;     __device__ __forceinline__ void operator()(const f32x4 (&acc)[2][2][4][2], const Unit& u, int wr, int wc, int, int) const {
;     ...
; #pragma unroll
;         for (int ai = 0; ai < 2; ++ai)
; #pragma unroll
;             for (int m = 0; m < 4; ++m)
; #pragma unroll
;                 for (int bj = 0; bj < 2; ++bj) { const u32x4 c = cin[ai][m][bj]; const f32x4 v0 = acc[ai][bj][m][0], v1 = acc[ai][bj][m][1];
;                     u32x4 w; w.x = cvt_pk_bf16(bflo(c.x) + v0[0], bfhi(c.x) + v0[1]); w.y = cvt_pk_bf16(bflo(c.y) + v0[2], bfhi(c.y) + v0[3]);
;                     w.z = cvt_pk_bf16(bflo(c.z) + v1[0], bfhi(c.z) + v1[1]); w.w = cvt_pk_bf16(bflo(c.w) + v1[2], bfhi(c.w) + v1[3]);
;                     *(u32x4*)(C + (size_t)(row0 + ai * HALF + m * 16) * ldc + col0 + bj * HALF) = w; }
	v_and_b32_e32 v61, 0xffff0000, v163
	v_pk_add_f32 v[60:61], v[62:63], v[60:61]
	v_lshlrev_b32_e32 v62, 16, v156
	v_and_b32_e32 v63, 0xffff0000, v156
	v_pk_add_f32 v[56:57], v[56:57], v[62:63]
	v_lshlrev_b32_e32 v62, 16, v157
	v_and_b32_e32 v63, 0xffff0000, v157
	v_pk_add_f32 v[58:59], v[58:59], v[62:63]
	v_cvt_pk_bf16_f32 v56, v56, v57
	v_cvt_pk_bf16_f32 v57, v58, v59
	v_lshlrev_b32_e32 v58, 16, v158
	v_and_b32_e32 v59, 0xffff0000, v158
	v_pk_add_f32 v[48:49], v[48:49], v[58:59]
	v_cvt_pk_bf16_f32 v67, v60, v61
	v_cvt_pk_bf16_f32 v58, v48, v49
	v_lshlrev_b32_e32 v48, 16, v159
	v_and_b32_e32 v49, 0xffff0000, v159
	v_pk_add_f32 v[48:49], v[50:51], v[48:49]
	v_lshlrev_b32_e32 v50, 16, v153
	v_cvt_pk_bf16_f32 v59, v48, v49
	v_lshlrev_b32_e32 v48, 16, v152
	v_and_b32_e32 v49, 0xffff0000, v152
	v_and_b32_e32 v51, 0xffff0000, v153
	v_pk_add_f32 v[48:49], v[52:53], v[48:49]
	v_pk_add_f32 v[50:51], v[54:55], v[50:51]
	v_cvt_pk_bf16_f32 v48, v48, v49
	v_cvt_pk_bf16_f32 v49, v50, v51
	v_lshlrev_b32_e32 v50, 16, v154
	v_and_b32_e32 v51, 0xffff0000, v154
	v_pk_add_f32 v[44:45], v[44:45], v[50:51]
	v_lshl_add_u64 v[60:61], s[88:89], 0, v[210:211]
	v_cvt_pk_bf16_f32 v50, v44, v45
	v_lshlrev_b32_e32 v44, 16, v155
	v_and_b32_e32 v45, 0xffff0000, v155
	v_pk_add_f32 v[44:45], v[46:47], v[44:45]
	v_lshlrev_b32_e32 v46, 16, v148
	v_and_b32_e32 v47, 0xffff0000, v148
	v_pk_add_f32 v[40:41], v[40:41], v[46:47]
	v_lshlrev_b32_e32 v46, 16, v149
	v_and_b32_e32 v47, 0xffff0000, v149
	v_pk_add_f32 v[42:43], v[42:43], v[46:47]
	v_cvt_pk_bf16_f32 v40, v40, v41
	v_cvt_pk_bf16_f32 v41, v42, v43
	v_lshlrev_b32_e32 v42, 16, v150
	v_and_b32_e32 v43, 0xffff0000, v150
	v_pk_add_f32 v[32:33], v[32:33], v[42:43]
	v_cvt_pk_bf16_f32 v51, v44, v45
	v_cvt_pk_bf16_f32 v42, v32, v33
	v_lshlrev_b32_e32 v32, 16, v151
	v_and_b32_e32 v33, 0xffff0000, v151
	v_pk_add_f32 v[32:33], v[34:35], v[32:33]
	v_lshlrev_b32_e32 v34, 16, v145
	v_cvt_pk_bf16_f32 v43, v32, v33
	v_lshlrev_b32_e32 v32, 16, v144
	v_and_b32_e32 v33, 0xffff0000, v144
	v_and_b32_e32 v35, 0xffff0000, v145
	v_pk_add_f32 v[32:33], v[36:37], v[32:33]
	v_pk_add_f32 v[34:35], v[38:39], v[34:35]
	v_cvt_pk_bf16_f32 v32, v32, v33
	v_cvt_pk_bf16_f32 v33, v34, v35
	v_lshlrev_b32_e32 v34, 16, v146
	v_and_b32_e32 v35, 0xffff0000, v146
	v_pk_add_f32 v[28:29], v[28:29], v[34:35]
	v_lshl_add_u64 v[44:45], s[88:89], 0, v[208:209]
	v_cvt_pk_bf16_f32 v34, v28, v29
	v_lshlrev_b32_e32 v28, 16, v147
	v_and_b32_e32 v29, 0xffff0000, v147
	v_pk_add_f32 v[28:29], v[30:31], v[28:29]
	v_lshlrev_b32_e32 v30, 16, v140
	v_and_b32_e32 v31, 0xffff0000, v140
	v_pk_add_f32 v[24:25], v[24:25], v[30:31]
	v_lshlrev_b32_e32 v30, 16, v141
	v_and_b32_e32 v31, 0xffff0000, v141
	v_pk_add_f32 v[26:27], v[26:27], v[30:31]
	v_cvt_pk_bf16_f32 v24, v24, v25
	v_cvt_pk_bf16_f32 v25, v26, v27
	v_lshlrev_b32_e32 v26, 16, v142
	v_and_b32_e32 v27, 0xffff0000, v142
	v_pk_add_f32 v[16:17], v[16:17], v[26:27]
	v_cvt_pk_bf16_f32 v35, v28, v29
	v_cvt_pk_bf16_f32 v26, v16, v17
	v_lshlrev_b32_e32 v16, 16, v143
	v_and_b32_e32 v17, 0xffff0000, v143
	v_pk_add_f32 v[16:17], v[18:19], v[16:17]
	v_lshlrev_b32_e32 v18, 16, v137
	v_cvt_pk_bf16_f32 v27, v16, v17
	v_lshlrev_b32_e32 v16, 16, v136
	v_and_b32_e32 v17, 0xffff0000, v136
	v_and_b32_e32 v19, 0xffff0000, v137
	v_pk_add_f32 v[16:17], v[20:21], v[16:17]
	v_pk_add_f32 v[18:19], v[22:23], v[18:19]
	v_cvt_pk_bf16_f32 v16, v16, v17
	v_cvt_pk_bf16_f32 v17, v18, v19
	v_lshlrev_b32_e32 v18, 16, v138
	v_and_b32_e32 v19, 0xffff0000, v138
	v_pk_add_f32 v[12:13], v[12:13], v[18:19]
	v_lshl_add_u64 v[28:29], s[88:89], 0, v[206:207]
	v_cvt_pk_bf16_f32 v18, v12, v13
	v_lshlrev_b32_e32 v12, 16, v139
	v_and_b32_e32 v13, 0xffff0000, v139
	v_pk_add_f32 v[12:13], v[14:15], v[12:13]
	v_lshlrev_b32_e32 v14, 16, v132
	v_and_b32_e32 v15, 0xffff0000, v132
	v_pk_add_f32 v[8:9], v[8:9], v[14:15]
	v_lshlrev_b32_e32 v14, 16, v133
	v_and_b32_e32 v15, 0xffff0000, v133
	v_pk_add_f32 v[10:11], v[10:11], v[14:15]
	v_cvt_pk_bf16_f32 v8, v8, v9
	v_cvt_pk_bf16_f32 v9, v10, v11
	v_lshlrev_b32_e32 v10, 16, v134
	v_and_b32_e32 v11, 0xffff0000, v134
	v_pk_add_f32 v[4:5], v[4:5], v[10:11]
	v_cvt_pk_bf16_f32 v19, v12, v13
	v_cvt_pk_bf16_f32 v10, v4, v5
	v_lshlrev_b32_e32 v4, 16, v135
	v_and_b32_e32 v5, 0xffff0000, v135
	v_lshl_add_u64 v[12:13], s[88:89], 0, v[204:205]
	v_pk_add_f32 v[4:5], v[6:7], v[4:5]
	v_lshl_add_u64 v[92:93], v[92:93], 0, v[202:203]
	v_lshl_add_u64 v[76:77], v[76:77], 0, v[202:203]
	v_lshl_add_u64 v[60:61], v[60:61], 0, v[202:203]
	v_lshl_add_u64 v[44:45], v[44:45], 0, v[202:203]
	v_lshl_add_u64 v[28:29], v[28:29], 0, v[202:203]
	v_lshl_add_u64 v[12:13], v[12:13], 0, v[202:203]
	v_cvt_pk_bf16_f32 v11, v4, v5
	global_store_dwordx4 v[124:125], v[128:131], off
	global_store_dwordx4 v[124:125], v[120:123], off offset:256
	global_store_dwordx4 v[108:109], v[112:115], off
	global_store_dwordx4 v[108:109], v[104:107], off offset:256
	global_store_dwordx4 v[92:93], v[96:99], off
	global_store_dwordx4 v[92:93], v[88:91], off offset:256
	global_store_dwordx4 v[76:77], v[80:83], off
	global_store_dwordx4 v[76:77], v[72:75], off offset:256
	global_store_dwordx4 v[60:61], v[64:67], off
	global_store_dwordx4 v[60:61], v[56:59], off offset:256
	global_store_dwordx4 v[44:45], v[48:51], off
	global_store_dwordx4 v[44:45], v[40:43], off offset:256
	global_store_dwordx4 v[28:29], v[32:35], off
	global_store_dwordx4 v[28:29], v[24:27], off offset:256
	global_store_dwordx4 v[12:13], v[16:19], off
	global_store_dwordx4 v[12:13], v[8:11], off offset:256
	s_cbranch_vccz .LBB0_1655
	s_waitcnt vmcnt(0)
	s_cmpk_gt_u32 s2, 0xff
	s_cbranch_scc1 .LBB0_1670
	s_barrier
